# hand-written RWKV loader with two-chunk-deep prefetch; FFN2 weight conversion split between the out-projection GEMM idle workgroups and the scan-phase tail
# speedup vs baseline: 1.0290x; 1.0006x over previous
; __device__ __forceinline__ int fresh_tid(int wv) { int l; asm volatile("v_mbcnt_lo_u32_b32 %0, -1, 0\n\tv_mbcnt_hi_u32_b32 %0, -1, %0" : "=v"(l)); return wv * 64 + l; }
; #define LAS __attribute__((address_space(3)))
; __device__ __forceinline__ TDesc tconv_desc(const float* wg, const float* wu, const float* wd, const float* win, const float* wout, unsigned char* ws, int i) {
;     TDesc d; int mode = 0, tile = i;
;     if (i < 704) { d.W = wg; d.Bt = (bf16_t*)(ws + WS_WGU); d.K = 1024; d.N = DFF; mode = 1; }
;     else if (i < 1408) { d.W = wu; d.Bt = (bf16_t*)(ws + WS_WGU); d.K = 1024; d.N = DFF; mode = 2; tile = i - 704; }
;     else if (i < 2112) { d.W = wd; d.Bt = (bf16_t*)(ws + WS_WD); d.K = DFF; d.N = 1024; tile = i - 1408; }
;     else if (i < 3072) { d.W = win; d.Bt = (bf16_t*)(ws + WS_WIN); d.K = 1024; d.N = NCOLS; tile = i - 2112; }
;     else { d.W = wout; d.Bt = (bf16_t*)(ws + WS_WOUT); d.K = 1024; d.N = 1024; tile = i - 3072; }
;     const int nkt = d.K / 64; const int kt = tile % nkt, nt = tile / nkt; d.k0 = kt * 64; d.n0 = nt * 64;
;     d.brow0 = mode == 0 ? d.n0 : ((d.n0 >> 7) * 256 + (d.n0 & 127) + (mode == 2 ? 128 : 0));
;     return d;
; }
; __device__ __forceinline__ void tconv_list(const float* wg, const float* wu, const float* wd, const float* win, const float* wout, unsigned char* ws, const int ntiles, LAS float* t, const int wv) {
;     const int tid = fresh_tid(wv); const int G = gridDim.x;
;     float cur[8], nxt[8];
;     int i = blockIdx.x;
;     if (i < ntiles) { const TDesc d = tconv_desc(wg, wu, wd, win, wout, ws, i);
; #pragma unroll
;         for (int e = 0; e < 8; ++e) { const int idx = e * 512 + tid, r = idx >> 6, c = idx & 63; cur[e] = __builtin_nontemporal_load(d.W + (size_t)(d.k0 + r) * d.N + d.n0 + c); } }
;     for (; i < ntiles; i += G) {
;         const TDesc d = tconv_desc(wg, wu, wd, win, wout, ws, i);
;         { const TDesc dn = tconv_desc(wg, wu, wd, win, wout, ws, i + G < ntiles ? i + G : i);
; #pragma unroll
;             for (int e = 0; e < 8; ++e) { const int idx = e * 512 + tid, r = idx >> 6, c = idx & 63; nxt[e] = __builtin_nontemporal_load(dn.W + (size_t)(dn.k0 + r) * dn.N + dn.n0 + c); } }
.LBB0_689:
	s_cmp_lt_u32 s2, 128
	s_cbranch_scc1 .Ltc2_skip
	v_writelane_b32 v40, s4, 4
	v_writelane_b32 v40, s5, 5
	v_writelane_b32 v40, s6, 6
	v_writelane_b32 v40, s7, 7
	v_writelane_b32 v40, s8, 8
	v_writelane_b32 v40, s9, 9
	v_writelane_b32 v40, s10, 10
	v_writelane_b32 v40, s11, 11
	v_writelane_b32 v40, s12, 12
	v_writelane_b32 v40, s13, 13
	v_writelane_b32 v40, s14, 14
	v_writelane_b32 v40, s15, 15
	v_writelane_b32 v40, s16, 16
	v_writelane_b32 v40, s17, 17
	v_writelane_b32 v40, s18, 18
	v_writelane_b32 v40, s19, 19
	v_writelane_b32 v40, s20, 20
	v_writelane_b32 v40, s21, 21
	v_writelane_b32 v40, s22, 22
	v_writelane_b32 v40, s23, 23
	v_writelane_b32 v40, s24, 24
	v_writelane_b32 v40, s25, 25
	v_writelane_b32 v40, s26, 26
	v_writelane_b32 v40, s27, 27
	v_writelane_b32 v40, s28, 28
	v_writelane_b32 v40, s29, 29
	v_writelane_b32 v40, s30, 30
	v_writelane_b32 v40, s31, 31
	s_load_dwordx2 s[24:25], s[38:39], 0xd8
	s_load_dwordx2 s[26:27], s[38:39], 0xd0
	s_load_dwordx2 s[18:19], s[38:39], 0xb8
	s_load_dwordx2 s[20:21], s[38:39], 0xc0
	s_load_dwordx2 s[22:23], s[38:39], 0xc8
	v_mbcnt_lo_u32_b32 v0, -1, 0
	v_mbcnt_hi_u32_b32 v0, -1, v0
	s_lshr_b32 s28, s33, 6
	v_lshlrev_b32_e32 v1, 2, v0
	v_lshrrev_b32_e32 v2, 5, v0
	v_and_b32_e32 v3, 31, v0
	s_mul_i32 s7, s28, 260
	v_add_u32_e32 v5, s7, v1
	v_mul_u32_u24_e32 v6, 0x208, v3
	s_lshl_b32 s7, s28, 3
	v_lshl_add_u32 v6, v2, 2, v6
	v_add_u32_e32 v6, s7, v6
	v_lshlrev_b32_e32 v3, 2, v3
	s_sub_u32 s4, s2, 128
	s_add_u32 s4, s4, 808
	s_waitcnt lgkmcnt(0)
	s_cmp_lt_u32 s4, 704
	s_cbranch_scc0 .Ltc2_seg1_0
	s_mov_b32 s7, s4
	s_and_b32 s8, s7, 15
	s_lshr_b32 s9, s7, 4
	s_mul_i32 s7, s8, 720896
	s_lshl_b32 s29, s9, 8
	s_add_u32 s7, s7, s29
	s_mul_i32 s29, s28, 11264
	s_add_u32 s7, s7, s29
	s_add_u32 s10, s18, s7
	s_addc_u32 s11, s19, 0
	s_lshr_b32 s7, s9, 1
	s_lshl_b32 s7, s7, 8
	s_and_b32 s29, s9, 1
	s_lshl_b32 s29, s29, 6
	s_add_u32 s7, s7, s29
	s_mul_i32 s7, s7, 2048
	s_lshl_b32 s29, s8, 7
	s_add_u32 s7, s7, s29
	s_mul_i32 s29, s28, 4096
	s_add_u32 s7, s7, s29
	s_add_u32 s12, s26, 0x2100000
	s_addc_u32 s13, s27, 0
	s_add_u32 s12, s12, s7
	s_addc_u32 s13, s13, 0
	s_mov_b32 s14, 90112
	s_mov_b32 s15, 32768
	s_movk_i32 s16, 2048
	s_branch .Ltc2_segend_0

; __device__ __forceinline__ int fresh_tid(int wv) { int l; asm volatile("v_mbcnt_lo_u32_b32 %0, -1, 0\n\tv_mbcnt_hi_u32_b32 %0, -1, %0" : "=v"(l)); return wv * 64 + l; }
; #define LAS __attribute__((address_space(3)))
; template <bool SAMPLE>
; __device__ __forceinline__ void rwkv_unit(PR P, LAS float* lds, const int b, const int h, const int half, const int wv) {
;     constexpr int T = SAMPLE ? 4 : 2048, TC = SAMPLE ? 4 : 32, NCH = T / TC;
;     const int tid = fresh_tid(wv), lane = tid & 63, wid = tid >> 6;
;     const bf16_t* PS = (const bf16_t*)(P.ws + WS_BIG); const bf16_t* OMD = (const bf16_t*)(P.ws + WS_OMD); const bf16_t* ASIG = (const bf16_t*)(P.ws + WS_ASIG);
;     bf16_t* YS = (bf16_t*)(P.ws + WS_YS);
;     const int row_base = SAMPLE ? MP + b * 4 : b * 2048;
;     const int ltok = (tid - 256) >> 4, lcg = tid & 15; const bool lwave = tid >= 256; const int hch = h * 64 + lcg * 4;
;     const float4 mur = *(const float4*)(P.mu + hch), muk = *(const float4*)(P.mu + 512 + hch), muv = *(const float4*)(P.mu + 1024 + hch);
;     const float4 kk4 = *(const float4*)(P.k_k + hch), ka4 = *(const float4*)(P.k_a + hch);
;     typedef float f32x2 __attribute__((ext_vector_type(2)));
;     const int row0 = half * 32 + (wid & 3) * 8 + (lane >> 4) * 2, cgl = lane & 15, j0 = cgl * 4;
;     f32x2 S[4];
; #pragma unroll
;     for (int c = 0; c < 4; ++c) S[c] = (f32x2){0.f, 0.f};
;     float* sout = P.out + (SAMPLE ? O_WKS : O_WKP) + ((size_t)(b * 8 + h) * 64 + row0) * 64 + j0;
;     if (SAMPLE && wid < 4) { const float* sp = P.state_wkv + ((size_t)(b * 8 + h) * 64 + row0) * 64 + j0; const float4 s0 = *(const float4*)sp, s1 = *(const float4*)(sp + 64);
;         S[0] = (f32x2){s0.x, s1.x}; S[1] = (f32x2){s0.y, s1.y}; S[2] = (f32x2){s0.z, s1.z}; S[3] = (f32x2){s0.w, s1.w}; }
;     LAS float* buf0 = lds; LAS float* buf1 = lds + TC * 384;
;     u32x2 cr[2], ck[2], cv[2], pr[2], pk[2], pv[2], co[2], ca[2];
.LBB0_702:
	s_or_b64 exec, exec, s[8:9]
	v_ashrrev_i32_e32 v57, 6, v56
	s_lshl_b32 s8, s2, 5
	v_lshlrev_b32_e32 v21, 3, v57
	v_lshrrev_b32_e32 v56, 3, v54
	s_and_b32 s8, s8, 32
	v_and_b32_e32 v21, 24, v21
	v_and_b32_e32 v56, 6, v56
	v_and_b32_e32 v66, 15, v54
	v_or3_b32 v54, v56, s8, v21
	v_mov_b32_e32 v56, 0
	v_mov_b32_e32 v21, v56
	v_lshl_add_u64 v[58:59], s[12:13], 0, v[20:21]
	v_lshl_add_u64 v[60:61], s[10:11], 0, v[20:21]
	v_lshl_add_u64 v[62:63], s[14:15], 0, v[20:21]
	v_lshlrev_b32_e32 v20, 1, v54
	s_mov_b32 s71, 0
	v_lshl_add_u64 v[20:21], s[46:47], 0, v[20:21]
	s_lshl_b32 s70, s20, 1
	v_lshl_add_u64 v[20:21], v[20:21], 0, s[70:71]
	s_mov_b64 s[12:13], 0xbae4800
	v_lshlrev_b32_e32 v76, 2, v66
	v_cmp_gt_i32_e64 s[8:9], 4, v57
	v_or_b32_e32 v77, s6, v66
	v_lshl_add_u64 v[64:65], v[20:21], 0, s[12:13]
	v_and_b32_e32 v72, 3, v66
	v_cmp_eq_u32_e64 s[12:13], 0, v72
	v_cmp_eq_u32_e64 s[14:15], 1, v72
	v_cmp_eq_u32_e64 s[16:17], 2, v72
	s_movk_i32 s49, 0x1e00
	s_add_i32 s55, 0, 0xc000
	v_mov_b32_e32 v66, 0
	v_mov_b32_e32 v67, v56
	v_mov_b32_e32 v20, v56
	v_mov_b32_e32 v21, v56
	v_mov_b32_e32 v68, v56
	v_mov_b32_e32 v69, v56
	v_mov_b32_e32 v70, v56
	v_mov_b32_e32 v71, v56
	s_add_u32 s18, s46, 0x3d44800
	s_addc_u32 s19, s47, 0
	s_sub_u32 s20, s18, 0x1e00
	s_subb_u32 s21, s19, 0
	s_add_u32 s22, s46, 0xda04800
	s_addc_u32 s23, s47, 0
	s_add_u32 s24, s46, 0xea84800
	s_addc_u32 s25, s47, 0
	s_bfe_u32 s26, s2, 0x30001
	s_lshl_b32 s26, s26, 7
	v_lshrrev_b32_e32 v123, 1, v75
	v_add_u32_e32 v123, s26, v123
	v_mul_u32_u24_e32 v121, 0x1e00, v55
	v_add_u32_e32 v121, v121, v123
	v_lshl_add_u32 v122, v55, 10, v123
	v_add_u32_e32 v123, v74, v75
	s_cmp_lt_u32 s33, 0x100
	s_cbranch_scc1 .Lld_noprefetch
	s_mov_b32 s29, 1
	s_lshl_b32 s26, s29, 5
	s_add_i32 s26, s26, s6
	s_mul_i32 s27, s26, 0x1e00
	s_lshl_b32 s28, s26, 10
	v_add_u32_e32 v78, s27, v121
	v_add_u32_e32 v79, s28, v122
	global_load_dwordx2 v[124:125], v78, s[18:19]
	global_load_dwordx2 v[126:127], v78, s[18:19] offset:1024
	global_load_dwordx2 v[128:129], v78, s[18:19] offset:2048
	global_load_dwordx2 v[130:131], v78, s[20:21]
	global_load_dwordx2 v[132:133], v78, s[20:21] offset:1024
	global_load_dwordx2 v[134:135], v78, s[20:21] offset:2048
	global_load_dwordx2 v[136:137], v79, s[22:23]
	global_load_dwordx2 v[138:139], v79, s[24:25]
	s_add_u32 s27, s27, 0x1e000
	s_add_u32 s28, s28, 0x4000
	v_add_u32_e32 v80, s27, v121
	v_add_u32_e32 v81, s28, v122
	global_load_dwordx2 v[140:141], v80, s[18:19]
	global_load_dwordx2 v[142:143], v80, s[18:19] offset:1024
	global_load_dwordx2 v[144:145], v80, s[18:19] offset:2048
	global_load_dwordx2 v[146:147], v80, s[20:21]
	global_load_dwordx2 v[148:149], v80, s[20:21] offset:1024
	global_load_dwordx2 v[150:151], v80, s[20:21] offset:2048
	global_load_dwordx2 v[152:153], v81, s[22:23]
	global_load_dwordx2 v[154:155], v81, s[24:25]
.Lld_noprefetch:
	s_waitcnt lgkmcnt(0)
	s_barrier
	s_branch .LBB0_705

; #define LAS __attribute__((address_space(3)))
; #define RW_LOAD(c) do { RW_LOAD1(c, 0); RW_LOAD1(c, 1); } while (0)
; template <bool SAMPLE>
; __device__ __forceinline__ void rwkv_unit(PR P, LAS float* lds, const int b, const int h, const int half, const int wv) {
;     ...
;     for (int c = 0; c < NCH; ++c) {
;         LAS float* cur = (c & 1) ? buf1 : buf0; LAS float* nxt = (c & 1) ? buf0 : buf1;
;         if (c + 1 < NCH) RW_LOAD(c + 1);
.LBB0_705:
	s_cmp_lt_u32 s33, 0x100
	s_cbranch_scc1 .Lrw_scan_chunk
	s_add_i32 s56, s71, 1
	s_cmp_eq_u32 s71, 63
	s_cbranch_scc1 .LBB0_704
	s_add_i32 s29, s56, 1
	s_bitcmp1_b32 s71, 0
	s_cbranch_scc1 .Lld_odd
	s_cmp_lt_u32 s29, 64
	s_cbranch_scc0 .Lld_last_even
	s_lshl_b32 s26, s29, 5
	s_add_i32 s26, s26, s6
	s_mul_i32 s27, s26, 0x1e00
	s_lshl_b32 s28, s26, 10
	v_add_u32_e32 v78, s27, v121
	v_add_u32_e32 v79, s28, v122
	global_load_dwordx2 v[22:23], v78, s[18:19]
	global_load_dwordx2 v[24:25], v78, s[18:19] offset:1024
	global_load_dwordx2 v[26:27], v78, s[18:19] offset:2048
	global_load_dwordx2 v[28:29], v78, s[20:21]
	global_load_dwordx2 v[30:31], v78, s[20:21] offset:1024
	global_load_dwordx2 v[32:33], v78, s[20:21] offset:2048
	global_load_dwordx2 v[34:35], v79, s[22:23]
	global_load_dwordx2 v[36:37], v79, s[24:25]
	s_add_u32 s27, s27, 0x1e000
	s_add_u32 s28, s28, 0x4000
	v_add_u32_e32 v80, s27, v121
	v_add_u32_e32 v81, s28, v122
	global_load_dwordx2 v[38:39], v80, s[18:19]
	global_load_dwordx2 v[40:41], v80, s[18:19] offset:1024
	global_load_dwordx2 v[42:43], v80, s[18:19] offset:2048
	global_load_dwordx2 v[44:45], v80, s[20:21]
	global_load_dwordx2 v[46:47], v80, s[20:21] offset:1024
	global_load_dwordx2 v[48:49], v80, s[20:21] offset:2048
	global_load_dwordx2 v[50:51], v81, s[22:23]
	global_load_dwordx2 v[52:53], v81, s[24:25]
	s_waitcnt vmcnt(16)
	s_branch .Lld_go_even

.Lld_go_even:
	s_bitcmp0_b32 s71, 0
	s_cselect_b32 s26, 0xc000, 0
	v_add_u32_e32 v80, s26, v123
	v_lshlrev_b32_e32 v104, 16, v124
	v_and_b32_e32 v105, 0xffff0000, v124
	v_lshlrev_b32_e32 v106, 16, v125
	v_and_b32_e32 v107, 0xffff0000, v125
	v_lshlrev_b32_e32 v108, 16, v130
	v_and_b32_e32 v109, 0xffff0000, v130
	v_lshlrev_b32_e32 v110, 16, v131
	v_and_b32_e32 v111, 0xffff0000, v131
	v_pk_add_f32 v[108:109], v[108:109], v[104:105] neg_lo:[0,1] neg_hi:[0,1]
	v_pk_add_f32 v[110:111], v[110:111], v[106:107] neg_lo:[0,1] neg_hi:[0,1]
	v_pk_fma_f32 v[84:85], v[0:1], v[108:109], v[104:105]
	v_pk_fma_f32 v[86:87], v[2:3], v[110:111], v[106:107]
	v_lshlrev_b32_e32 v104, 16, v126
	v_and_b32_e32 v105, 0xffff0000, v126
	v_lshlrev_b32_e32 v106, 16, v127
	v_and_b32_e32 v107, 0xffff0000, v127
	v_lshlrev_b32_e32 v108, 16, v132
	v_and_b32_e32 v109, 0xffff0000, v132
	v_lshlrev_b32_e32 v110, 16, v133
	v_and_b32_e32 v111, 0xffff0000, v133
	v_pk_add_f32 v[108:109], v[108:109], v[104:105] neg_lo:[0,1] neg_hi:[0,1]
	v_pk_add_f32 v[110:111], v[110:111], v[106:107] neg_lo:[0,1] neg_hi:[0,1]
	v_pk_fma_f32 v[88:89], v[12:13], v[108:109], v[104:105]
	v_pk_fma_f32 v[90:91], v[14:15], v[110:111], v[106:107]
	v_lshlrev_b32_e32 v104, 16, v128
	v_and_b32_e32 v105, 0xffff0000, v128
	v_lshlrev_b32_e32 v106, 16, v129
	v_and_b32_e32 v107, 0xffff0000, v129
	v_lshlrev_b32_e32 v108, 16, v134
	v_and_b32_e32 v109, 0xffff0000, v134
	v_lshlrev_b32_e32 v110, 16, v135
	v_and_b32_e32 v111, 0xffff0000, v135
	v_pk_add_f32 v[108:109], v[108:109], v[104:105] neg_lo:[0,1] neg_hi:[0,1]
	v_pk_add_f32 v[110:111], v[110:111], v[106:107] neg_lo:[0,1] neg_hi:[0,1]
	v_pk_fma_f32 v[92:93], v[4:5], v[108:109], v[104:105]
	v_pk_fma_f32 v[94:95], v[6:7], v[110:111], v[106:107]
	v_lshlrev_b32_e32 v96, 16, v136
	v_and_b32_e32 v97, 0xffff0000, v136
	v_lshlrev_b32_e32 v98, 16, v137
	v_and_b32_e32 v99, 0xffff0000, v137
	v_lshlrev_b32_e32 v100, 16, v138
	v_and_b32_e32 v101, 0xffff0000, v138
	v_lshlrev_b32_e32 v102, 16, v139
	v_and_b32_e32 v103, 0xffff0000, v139
	v_pk_mul_f32 v[112:113], v[8:9], v[88:89]
	v_pk_mul_f32 v[114:115], v[10:11], v[90:91]
	v_pk_mul_f32 v[104:105], v[112:113], v[112:113]
	v_pk_fma_f32 v[104:105], v[114:115], v[114:115], v[104:105]
	v_add_f32_e32 v104, v104, v105
	v_pk_add_f32 v[116:117], v[100:101], -1.0 op_sel_hi:[1,0]
	v_pk_add_f32 v[118:119], v[102:103], -1.0 op_sel_hi:[1,0]
	v_add_f32_dpp v104, v104, v104 quad_perm:[1,0,3,2] row_mask:0xf bank_mask:0xf bound_ctrl:1
	v_pk_fma_f32 v[116:117], v[16:17], v[116:117], 1.0 op_sel_hi:[1,1,0]
	v_pk_fma_f32 v[118:119], v[18:19], v[118:119], 1.0 op_sel_hi:[1,1,0]
	v_add_f32_dpp v104, v104, v104 quad_perm:[2,3,0,1] row_mask:0xf bank_mask:0xf bound_ctrl:1
	v_pk_mul_f32 v[116:117], v[116:117], v[88:89]
	v_pk_mul_f32 v[118:119], v[118:119], v[90:91]
	v_add_f32_dpp v104, v104, v104 row_half_mirror row_mask:0xf bank_mask:0xf bound_ctrl:1
	ds_write_b128 v80, v[84:87] offset:0
	ds_write_b128 v80, v[96:99] offset:256
	v_add_f32_dpp v104, v104, v104 row_mirror row_mask:0xf bank_mask:0xf bound_ctrl:1
	v_rsq_f32_e32 v104, v104
	ds_write_b128 v80, v[116:119] offset:512
	v_min_f32_e32 v104, 0x5368d4a5, v104
	v_pk_mul_f32 v[112:113], v[112:113], v[104:105] op_sel_hi:[1,0] neg_lo:[0,1] neg_hi:[0,1]
	v_pk_mul_f32 v[114:115], v[114:115], v[104:105] op_sel_hi:[1,0] neg_lo:[0,1] neg_hi:[0,1]
	ds_write_b128 v80, v[112:115] offset:768
	v_pk_mul_f32 v[108:109], v[112:113], v[100:101] neg_lo:[1,0] neg_hi:[1,0]
	v_pk_mul_f32 v[110:111], v[114:115], v[102:103] neg_lo:[1,0] neg_hi:[1,0]
	ds_write_b128 v80, v[108:111] offset:1024
	ds_write_b128 v80, v[92:95] offset:1280
	v_lshlrev_b32_e32 v104, 16, v140
	v_and_b32_e32 v105, 0xffff0000, v140
	v_lshlrev_b32_e32 v106, 16, v141
	v_and_b32_e32 v107, 0xffff0000, v141
	v_lshlrev_b32_e32 v108, 16, v146
	v_and_b32_e32 v109, 0xffff0000, v146
	v_lshlrev_b32_e32 v110, 16, v147
	v_and_b32_e32 v111, 0xffff0000, v147
	v_pk_add_f32 v[108:109], v[108:109], v[104:105] neg_lo:[0,1] neg_hi:[0,1]
	v_pk_add_f32 v[110:111], v[110:111], v[106:107] neg_lo:[0,1] neg_hi:[0,1]
	v_pk_fma_f32 v[84:85], v[0:1], v[108:109], v[104:105]
	v_pk_fma_f32 v[86:87], v[2:3], v[110:111], v[106:107]
	v_lshlrev_b32_e32 v104, 16, v142
	v_and_b32_e32 v105, 0xffff0000, v142
	v_lshlrev_b32_e32 v106, 16, v143
	v_and_b32_e32 v107, 0xffff0000, v143
	v_lshlrev_b32_e32 v108, 16, v148
	v_and_b32_e32 v109, 0xffff0000, v148
	v_lshlrev_b32_e32 v110, 16, v149
	v_and_b32_e32 v111, 0xffff0000, v149
	v_pk_add_f32 v[108:109], v[108:109], v[104:105] neg_lo:[0,1] neg_hi:[0,1]
	v_pk_add_f32 v[110:111], v[110:111], v[106:107] neg_lo:[0,1] neg_hi:[0,1]
	v_pk_fma_f32 v[88:89], v[12:13], v[108:109], v[104:105]
	v_pk_fma_f32 v[90:91], v[14:15], v[110:111], v[106:107]
	v_lshlrev_b32_e32 v104, 16, v144
	v_and_b32_e32 v105, 0xffff0000, v144
	v_lshlrev_b32_e32 v106, 16, v145
	v_and_b32_e32 v107, 0xffff0000, v145
	v_lshlrev_b32_e32 v108, 16, v150
	v_and_b32_e32 v109, 0xffff0000, v150
	v_lshlrev_b32_e32 v110, 16, v151
	v_and_b32_e32 v111, 0xffff0000, v151
	v_pk_add_f32 v[108:109], v[108:109], v[104:105] neg_lo:[0,1] neg_hi:[0,1]
	v_pk_add_f32 v[110:111], v[110:111], v[106:107] neg_lo:[0,1] neg_hi:[0,1]
	v_pk_fma_f32 v[92:93], v[4:5], v[108:109], v[104:105]
	v_pk_fma_f32 v[94:95], v[6:7], v[110:111], v[106:107]
	v_lshlrev_b32_e32 v96, 16, v152
	v_and_b32_e32 v97, 0xffff0000, v152
	v_lshlrev_b32_e32 v98, 16, v153
	v_and_b32_e32 v99, 0xffff0000, v153
	v_lshlrev_b32_e32 v100, 16, v154
	v_and_b32_e32 v101, 0xffff0000, v154
	v_lshlrev_b32_e32 v102, 16, v155
	v_and_b32_e32 v103, 0xffff0000, v155
	v_pk_mul_f32 v[112:113], v[8:9], v[88:89]
	v_pk_mul_f32 v[114:115], v[10:11], v[90:91]
	v_pk_mul_f32 v[104:105], v[112:113], v[112:113]
	v_pk_fma_f32 v[104:105], v[114:115], v[114:115], v[104:105]
	v_add_f32_e32 v104, v104, v105
	v_pk_add_f32 v[116:117], v[100:101], -1.0 op_sel_hi:[1,0]
	v_pk_add_f32 v[118:119], v[102:103], -1.0 op_sel_hi:[1,0]
	v_add_f32_dpp v104, v104, v104 quad_perm:[1,0,3,2] row_mask:0xf bank_mask:0xf bound_ctrl:1
	v_pk_fma_f32 v[116:117], v[16:17], v[116:117], 1.0 op_sel_hi:[1,1,0]
	v_pk_fma_f32 v[118:119], v[18:19], v[118:119], 1.0 op_sel_hi:[1,1,0]
	v_add_f32_dpp v104, v104, v104 quad_perm:[2,3,0,1] row_mask:0xf bank_mask:0xf bound_ctrl:1
	v_pk_mul_f32 v[116:117], v[116:117], v[88:89]
	v_pk_mul_f32 v[118:119], v[118:119], v[90:91]
	v_add_f32_dpp v104, v104, v104 row_half_mirror row_mask:0xf bank_mask:0xf bound_ctrl:1
	ds_write_b128 v80, v[84:87] offset:24576
	ds_write_b128 v80, v[96:99] offset:24832
	v_add_f32_dpp v104, v104, v104 row_mirror row_mask:0xf bank_mask:0xf bound_ctrl:1
	v_rsq_f32_e32 v104, v104
	ds_write_b128 v80, v[116:119] offset:25088
	v_min_f32_e32 v104, 0x5368d4a5, v104
	v_pk_mul_f32 v[112:113], v[112:113], v[104:105] op_sel_hi:[1,0] neg_lo:[0,1] neg_hi:[0,1]
	v_pk_mul_f32 v[114:115], v[114:115], v[104:105] op_sel_hi:[1,0] neg_lo:[0,1] neg_hi:[0,1]
	ds_write_b128 v80, v[112:115] offset:25344
	v_pk_mul_f32 v[108:109], v[112:113], v[100:101] neg_lo:[1,0] neg_hi:[1,0]
	v_pk_mul_f32 v[110:111], v[114:115], v[102:103] neg_lo:[1,0] neg_hi:[1,0]
	ds_write_b128 v80, v[108:111] offset:25600
	ds_write_b128 v80, v[92:95] offset:25856
	s_branch .LBB0_704
.Lld_odd:
	s_cmp_lt_u32 s29, 64
	s_cbranch_scc0 .Lld_last_odd
	s_lshl_b32 s26, s29, 5
	s_add_i32 s26, s26, s6
	s_mul_i32 s27, s26, 0x1e00
	s_lshl_b32 s28, s26, 10
	v_add_u32_e32 v78, s27, v121
	v_add_u32_e32 v79, s28, v122
	global_load_dwordx2 v[124:125], v78, s[18:19]
	global_load_dwordx2 v[126:127], v78, s[18:19] offset:1024
	global_load_dwordx2 v[128:129], v78, s[18:19] offset:2048
	global_load_dwordx2 v[130:131], v78, s[20:21]
	global_load_dwordx2 v[132:133], v78, s[20:21] offset:1024
	global_load_dwordx2 v[134:135], v78, s[20:21] offset:2048
	global_load_dwordx2 v[136:137], v79, s[22:23]
	global_load_dwordx2 v[138:139], v79, s[24:25]
	s_add_u32 s27, s27, 0x1e000
	s_add_u32 s28, s28, 0x4000
	v_add_u32_e32 v80, s27, v121
	v_add_u32_e32 v81, s28, v122
	global_load_dwordx2 v[140:141], v80, s[18:19]
	global_load_dwordx2 v[142:143], v80, s[18:19] offset:1024
	global_load_dwordx2 v[144:145], v80, s[18:19] offset:2048
	global_load_dwordx2 v[146:147], v80, s[20:21]
	global_load_dwordx2 v[148:149], v80, s[20:21] offset:1024
	global_load_dwordx2 v[150:151], v80, s[20:21] offset:2048
	global_load_dwordx2 v[152:153], v81, s[22:23]
	global_load_dwordx2 v[154:155], v81, s[24:25]
	s_waitcnt vmcnt(16)
	s_branch .Lld_go_odd

.Lld_go_odd:
	s_bitcmp0_b32 s71, 0
	s_cselect_b32 s26, 0xc000, 0
	v_add_u32_e32 v80, s26, v123
	v_lshlrev_b32_e32 v104, 16, v22
	v_and_b32_e32 v105, 0xffff0000, v22
	v_lshlrev_b32_e32 v106, 16, v23
	v_and_b32_e32 v107, 0xffff0000, v23
	v_lshlrev_b32_e32 v108, 16, v28
	v_and_b32_e32 v109, 0xffff0000, v28
	v_lshlrev_b32_e32 v110, 16, v29
	v_and_b32_e32 v111, 0xffff0000, v29
	v_pk_add_f32 v[108:109], v[108:109], v[104:105] neg_lo:[0,1] neg_hi:[0,1]
	v_pk_add_f32 v[110:111], v[110:111], v[106:107] neg_lo:[0,1] neg_hi:[0,1]
	v_pk_fma_f32 v[84:85], v[0:1], v[108:109], v[104:105]
	v_pk_fma_f32 v[86:87], v[2:3], v[110:111], v[106:107]
	v_lshlrev_b32_e32 v104, 16, v24
	v_and_b32_e32 v105, 0xffff0000, v24
	v_lshlrev_b32_e32 v106, 16, v25
	v_and_b32_e32 v107, 0xffff0000, v25
	v_lshlrev_b32_e32 v108, 16, v30
	v_and_b32_e32 v109, 0xffff0000, v30
	v_lshlrev_b32_e32 v110, 16, v31
	v_and_b32_e32 v111, 0xffff0000, v31
	v_pk_add_f32 v[108:109], v[108:109], v[104:105] neg_lo:[0,1] neg_hi:[0,1]
	v_pk_add_f32 v[110:111], v[110:111], v[106:107] neg_lo:[0,1] neg_hi:[0,1]
	v_pk_fma_f32 v[88:89], v[12:13], v[108:109], v[104:105]
	v_pk_fma_f32 v[90:91], v[14:15], v[110:111], v[106:107]
	v_lshlrev_b32_e32 v104, 16, v26
	v_and_b32_e32 v105, 0xffff0000, v26
	v_lshlrev_b32_e32 v106, 16, v27
	v_and_b32_e32 v107, 0xffff0000, v27
	v_lshlrev_b32_e32 v108, 16, v32
	v_and_b32_e32 v109, 0xffff0000, v32
	v_lshlrev_b32_e32 v110, 16, v33
	v_and_b32_e32 v111, 0xffff0000, v33
	v_pk_add_f32 v[108:109], v[108:109], v[104:105] neg_lo:[0,1] neg_hi:[0,1]
	v_pk_add_f32 v[110:111], v[110:111], v[106:107] neg_lo:[0,1] neg_hi:[0,1]
	v_pk_fma_f32 v[92:93], v[4:5], v[108:109], v[104:105]
	v_pk_fma_f32 v[94:95], v[6:7], v[110:111], v[106:107]
	v_lshlrev_b32_e32 v96, 16, v34
	v_and_b32_e32 v97, 0xffff0000, v34
	v_lshlrev_b32_e32 v98, 16, v35
	v_and_b32_e32 v99, 0xffff0000, v35
	v_lshlrev_b32_e32 v100, 16, v36
	v_and_b32_e32 v101, 0xffff0000, v36
	v_lshlrev_b32_e32 v102, 16, v37
	v_and_b32_e32 v103, 0xffff0000, v37
	v_pk_mul_f32 v[112:113], v[8:9], v[88:89]
	v_pk_mul_f32 v[114:115], v[10:11], v[90:91]
	v_pk_mul_f32 v[104:105], v[112:113], v[112:113]
	v_pk_fma_f32 v[104:105], v[114:115], v[114:115], v[104:105]
	v_add_f32_e32 v104, v104, v105
	v_pk_add_f32 v[116:117], v[100:101], -1.0 op_sel_hi:[1,0]
	v_pk_add_f32 v[118:119], v[102:103], -1.0 op_sel_hi:[1,0]
	v_add_f32_dpp v104, v104, v104 quad_perm:[1,0,3,2] row_mask:0xf bank_mask:0xf bound_ctrl:1
	v_pk_fma_f32 v[116:117], v[16:17], v[116:117], 1.0 op_sel_hi:[1,1,0]
	v_pk_fma_f32 v[118:119], v[18:19], v[118:119], 1.0 op_sel_hi:[1,1,0]
	v_add_f32_dpp v104, v104, v104 quad_perm:[2,3,0,1] row_mask:0xf bank_mask:0xf bound_ctrl:1
	v_pk_mul_f32 v[116:117], v[116:117], v[88:89]
	v_pk_mul_f32 v[118:119], v[118:119], v[90:91]
	v_add_f32_dpp v104, v104, v104 row_half_mirror row_mask:0xf bank_mask:0xf bound_ctrl:1
	ds_write_b128 v80, v[84:87] offset:0
	ds_write_b128 v80, v[96:99] offset:256
	v_add_f32_dpp v104, v104, v104 row_mirror row_mask:0xf bank_mask:0xf bound_ctrl:1
	v_rsq_f32_e32 v104, v104
	ds_write_b128 v80, v[116:119] offset:512
	v_min_f32_e32 v104, 0x5368d4a5, v104
	v_pk_mul_f32 v[112:113], v[112:113], v[104:105] op_sel_hi:[1,0] neg_lo:[0,1] neg_hi:[0,1]
	v_pk_mul_f32 v[114:115], v[114:115], v[104:105] op_sel_hi:[1,0] neg_lo:[0,1] neg_hi:[0,1]
	ds_write_b128 v80, v[112:115] offset:768
	v_pk_mul_f32 v[108:109], v[112:113], v[100:101] neg_lo:[1,0] neg_hi:[1,0]
	v_pk_mul_f32 v[110:111], v[114:115], v[102:103] neg_lo:[1,0] neg_hi:[1,0]
	ds_write_b128 v80, v[108:111] offset:1024
	ds_write_b128 v80, v[92:95] offset:1280
	v_lshlrev_b32_e32 v104, 16, v38
	v_and_b32_e32 v105, 0xffff0000, v38
	v_lshlrev_b32_e32 v106, 16, v39
	v_and_b32_e32 v107, 0xffff0000, v39
	v_lshlrev_b32_e32 v108, 16, v44
	v_and_b32_e32 v109, 0xffff0000, v44
	v_lshlrev_b32_e32 v110, 16, v45
	v_and_b32_e32 v111, 0xffff0000, v45
	v_pk_add_f32 v[108:109], v[108:109], v[104:105] neg_lo:[0,1] neg_hi:[0,1]
	v_pk_add_f32 v[110:111], v[110:111], v[106:107] neg_lo:[0,1] neg_hi:[0,1]
	v_pk_fma_f32 v[84:85], v[0:1], v[108:109], v[104:105]
	v_pk_fma_f32 v[86:87], v[2:3], v[110:111], v[106:107]
	v_lshlrev_b32_e32 v104, 16, v40
	v_and_b32_e32 v105, 0xffff0000, v40
	v_lshlrev_b32_e32 v106, 16, v41
	v_and_b32_e32 v107, 0xffff0000, v41
	v_lshlrev_b32_e32 v108, 16, v46
	v_and_b32_e32 v109, 0xffff0000, v46
	v_lshlrev_b32_e32 v110, 16, v47
	v_and_b32_e32 v111, 0xffff0000, v47
	v_pk_add_f32 v[108:109], v[108:109], v[104:105] neg_lo:[0,1] neg_hi:[0,1]
	v_pk_add_f32 v[110:111], v[110:111], v[106:107] neg_lo:[0,1] neg_hi:[0,1]
	v_pk_fma_f32 v[88:89], v[12:13], v[108:109], v[104:105]
	v_pk_fma_f32 v[90:91], v[14:15], v[110:111], v[106:107]
	v_lshlrev_b32_e32 v104, 16, v42
	v_and_b32_e32 v105, 0xffff0000, v42
	v_lshlrev_b32_e32 v106, 16, v43
	v_and_b32_e32 v107, 0xffff0000, v43
	v_lshlrev_b32_e32 v108, 16, v48
	v_and_b32_e32 v109, 0xffff0000, v48
	v_lshlrev_b32_e32 v110, 16, v49
	v_and_b32_e32 v111, 0xffff0000, v49
	v_pk_add_f32 v[108:109], v[108:109], v[104:105] neg_lo:[0,1] neg_hi:[0,1]
	v_pk_add_f32 v[110:111], v[110:111], v[106:107] neg_lo:[0,1] neg_hi:[0,1]
	v_pk_fma_f32 v[92:93], v[4:5], v[108:109], v[104:105]
	v_pk_fma_f32 v[94:95], v[6:7], v[110:111], v[106:107]
	v_lshlrev_b32_e32 v96, 16, v50
	v_and_b32_e32 v97, 0xffff0000, v50
	v_lshlrev_b32_e32 v98, 16, v51
	v_and_b32_e32 v99, 0xffff0000, v51
	v_lshlrev_b32_e32 v100, 16, v52
	v_and_b32_e32 v101, 0xffff0000, v52
	v_lshlrev_b32_e32 v102, 16, v53
	v_and_b32_e32 v103, 0xffff0000, v53
	v_pk_mul_f32 v[112:113], v[8:9], v[88:89]
	v_pk_mul_f32 v[114:115], v[10:11], v[90:91]
	v_pk_mul_f32 v[104:105], v[112:113], v[112:113]
	v_pk_fma_f32 v[104:105], v[114:115], v[114:115], v[104:105]
	v_add_f32_e32 v104, v104, v105
	v_pk_add_f32 v[116:117], v[100:101], -1.0 op_sel_hi:[1,0]
	v_pk_add_f32 v[118:119], v[102:103], -1.0 op_sel_hi:[1,0]
	v_add_f32_dpp v104, v104, v104 quad_perm:[1,0,3,2] row_mask:0xf bank_mask:0xf bound_ctrl:1
	v_pk_fma_f32 v[116:117], v[16:17], v[116:117], 1.0 op_sel_hi:[1,1,0]
	v_pk_fma_f32 v[118:119], v[18:19], v[118:119], 1.0 op_sel_hi:[1,1,0]
	v_add_f32_dpp v104, v104, v104 quad_perm:[2,3,0,1] row_mask:0xf bank_mask:0xf bound_ctrl:1
	v_pk_mul_f32 v[116:117], v[116:117], v[88:89]
	v_pk_mul_f32 v[118:119], v[118:119], v[90:91]
	v_add_f32_dpp v104, v104, v104 row_half_mirror row_mask:0xf bank_mask:0xf bound_ctrl:1
	ds_write_b128 v80, v[84:87] offset:24576
	ds_write_b128 v80, v[96:99] offset:24832
	v_add_f32_dpp v104, v104, v104 row_mirror row_mask:0xf bank_mask:0xf bound_ctrl:1
	v_rsq_f32_e32 v104, v104
	ds_write_b128 v80, v[116:119] offset:25088
	v_min_f32_e32 v104, 0x5368d4a5, v104
	v_pk_mul_f32 v[112:113], v[112:113], v[104:105] op_sel_hi:[1,0] neg_lo:[0,1] neg_hi:[0,1]
	v_pk_mul_f32 v[114:115], v[114:115], v[104:105] op_sel_hi:[1,0] neg_lo:[0,1] neg_hi:[0,1]
	ds_write_b128 v80, v[112:115] offset:25344
	v_pk_mul_f32 v[108:109], v[112:113], v[100:101] neg_lo:[1,0] neg_hi:[1,0]
	v_pk_mul_f32 v[110:111], v[114:115], v[102:103] neg_lo:[1,0] neg_hi:[1,0]
	ds_write_b128 v80, v[108:111] offset:25600
	ds_write_b128 v80, v[92:95] offset:25856
	s_branch .LBB0_704

; #define LAS __attribute__((address_space(3)))
; #define ROW16_SUM4(x, y, z, w) do { DPP4(x, y, z, w, "quad_perm:[1,0,3,2]", "s_nop 1"); DPP4(x, y, z, w, "quad_perm:[2,3,0,1]", ""); DPP4(x, y, z, w, "row_half_mirror", ""); DPP4(x, y, z, w, "row_mirror", ""); } while (0)
; template <bool SAMPLE>
; __device__ __forceinline__ void rwkv_unit(PR P, LAS float* lds, const int b, const int h, const int half, const int wv) {
;     ...
;             for (int g = 0; g < TC / GS; ++g) {
;                 float yk0 = 0.f, yk1 = 0.f;
;                 const LAS float* q0 = cur + (g * GS) * 384;
;                 f32x4 r4 = *(const LAS f32x4*)(q0 + j0), o4 = *(const LAS f32x4*)(q0 + 64 + j0), k4 = *(const LAS f32x4*)(q0 + 128 + j0), a4 = *(const LAS f32x4*)(q0 + 192 + j0), b4 = *(const LAS f32x4*)(q0 + 256 + j0);
;                 f32x2 v2 = *(const LAS f32x2*)(q0 + 320 + row0);
;                 float py0 = 0.f, py1 = 0.f;
; #pragma unroll
;                 for (int tt = 0; tt < GS; ++tt) {
;                     const LAS float* qn = q0 + (tt + 1 < GS ? tt + 1 : tt) * 384;
;                     const f32x4 nr4 = *(const LAS f32x4*)(qn + j0), no4 = *(const LAS f32x4*)(qn + 64 + j0), nk4 = *(const LAS f32x4*)(qn + 128 + j0), na4 = *(const LAS f32x4*)(qn + 192 + j0), nb4 = *(const LAS f32x4*)(qn + 256 + j0);
;                     const f32x2 nv2 = *(const LAS f32x2*)(qn + 320 + row0);
;                     f32x2 sa = (S[0] * a4[0] + S[1] * a4[1]) + (S[2] * a4[2] + S[3] * a4[3]);
;                     float sx = sa.x, sy = sa.y; ROW16_SUM4(sx, sy, py0, py1); sa = (f32x2){sx, sy};
;                     if (tt > 0) { yk0 = cgl == tt - 1 ? py0 : yk0; yk1 = cgl == tt - 1 ? py1 : yk1; }
; #pragma unroll
;                     for (int c = 0; c < 4; ++c) { f32x2 t = S[c] - S[c] * o4[c]; t = t + sa * b4[c]; S[c] = t + v2 * k4[c]; }
;                     const f32x2 y = (S[0] * r4[0] + S[1] * r4[1]) + (S[2] * r4[2] + S[3] * r4[3]);
;                     py0 = y.x; py1 = y.y;
;                     r4 = nr4; o4 = no4; k4 = nk4; a4 = na4; b4 = nb4; v2 = nv2;
;                 }
.Lrw_first_chunk:
	s_waitcnt lgkmcnt(0)
	v_pk_mul_f32 v[150:151], v[66:67], v[172:173] op_sel_hi:[1,0]
	v_pk_fma_f32 v[142:143], v[66:67], v[164:165], v[66:67] op_sel_hi:[1,0,1] neg_lo:[1,0,0] neg_hi:[1,0,0]
	ds_read_b128 v[212:215], v152 offset:3840
	v_pk_fma_f32 v[150:151], v[20:21], v[172:173], v[150:151] op_sel:[0,1,0]
	v_pk_fma_f32 v[144:145], v[20:21], v[164:165], v[20:21] op_sel:[0,1,0] neg_lo:[1,0,0] neg_hi:[1,0,0]
	ds_read_b128 v[204:207], v152 offset:3328
	v_pk_fma_f32 v[150:151], v[68:69], v[174:175], v[150:151] op_sel_hi:[1,0,1]
	v_pk_fma_f32 v[146:147], v[68:69], v[166:167], v[68:69] op_sel_hi:[1,0,1] neg_lo:[1,0,0] neg_hi:[1,0,0]
	ds_read2st64_b64 v[244:247], v153 offset0:8 offset1:11
	v_pk_fma_f32 v[150:151], v[70:71], v[174:175], v[150:151] op_sel:[0,1,0]
	v_pk_fma_f32 v[148:149], v[70:71], v[166:167], v[70:71] op_sel:[0,1,0] neg_lo:[1,0,0] neg_hi:[1,0,0]
	ds_read_b128 v[208:211], v152 offset:3584
	v_pk_fma_f32 v[142:143], v[240:241], v[168:169], v[142:143] op_sel_hi:[1,0,1]
	v_pk_fma_f32 v[144:145], v[240:241], v[168:169], v[144:145] op_sel:[0,1,0]
	v_add_f32_dpp v150, v150, v150 quad_perm:[1,0,3,2] row_mask:0xf bank_mask:0xf bound_ctrl:1
	v_add_f32_dpp v151, v151, v151 quad_perm:[1,0,3,2] row_mask:0xf bank_mask:0xf bound_ctrl:1
	v_pk_fma_f32 v[146:147], v[240:241], v[170:171], v[146:147] op_sel_hi:[1,0,1]
	v_add_f32_dpp v150, v150, v150 quad_perm:[2,3,0,1] row_mask:0xf bank_mask:0xf bound_ctrl:1
	v_add_f32_dpp v151, v151, v151 quad_perm:[2,3,0,1] row_mask:0xf bank_mask:0xf bound_ctrl:1
	v_pk_fma_f32 v[148:149], v[240:241], v[170:171], v[148:149] op_sel:[0,1,0]
	v_add_f32_dpp v150, v150, v150 row_half_mirror row_mask:0xf bank_mask:0xf bound_ctrl:1
	v_add_f32_dpp v151, v151, v151 row_half_mirror row_mask:0xf bank_mask:0xf bound_ctrl:1
	ds_read_b128 v[232:235], v152 offset:5376
	v_add_f32_dpp v150, v150, v150 row_mirror row_mask:0xf bank_mask:0xf bound_ctrl:1
	v_add_f32_dpp v151, v151, v151 row_mirror row_mask:0xf bank_mask:0xf bound_ctrl:1
	ds_read_b128 v[224:227], v152 offset:4864
	ds_read_b128 v[216:219], v152 offset:4096
	ds_read_b128 v[228:231], v152 offset:5120
	ds_read_b128 v[236:239], v152 offset:5632
	ds_read_b128 v[200:203], v152 offset:3072
	ds_read_b128 v[220:223], v152 offset:4608
	v_pk_fma_f32 v[66:67], v[150:151], v[176:177], v[142:143] op_sel_hi:[1,0,1]
	v_pk_fma_f32 v[20:21], v[150:151], v[176:177], v[144:145] op_sel:[0,1,0]
	v_pk_fma_f32 v[68:69], v[150:151], v[178:179], v[146:147] op_sel_hi:[1,0,1]
	v_pk_fma_f32 v[70:71], v[150:151], v[178:179], v[148:149] op_sel:[0,1,0]
	v_pk_mul_f32 v[78:79], v[66:67], v[160:161] op_sel_hi:[1,0]
	v_pk_mul_f32 v[150:151], v[66:67], v[192:193] op_sel_hi:[1,0]
	v_pk_fma_f32 v[142:143], v[66:67], v[184:185], v[66:67] op_sel_hi:[1,0,1] neg_lo:[1,0,0] neg_hi:[1,0,0]
	v_pk_fma_f32 v[78:79], v[20:21], v[160:161], v[78:79] op_sel:[0,1,0]
	v_pk_fma_f32 v[150:151], v[20:21], v[192:193], v[150:151] op_sel:[0,1,0]
	v_pk_fma_f32 v[144:145], v[20:21], v[184:185], v[20:21] op_sel:[0,1,0] neg_lo:[1,0,0] neg_hi:[1,0,0]
	v_pk_fma_f32 v[78:79], v[68:69], v[162:163], v[78:79] op_sel_hi:[1,0,1]
	v_pk_fma_f32 v[150:151], v[68:69], v[194:195], v[150:151] op_sel_hi:[1,0,1]
	v_pk_fma_f32 v[146:147], v[68:69], v[186:187], v[68:69] op_sel_hi:[1,0,1] neg_lo:[1,0,0] neg_hi:[1,0,0]
	v_pk_fma_f32 v[78:79], v[70:71], v[162:163], v[78:79] op_sel:[0,1,0]
	v_pk_fma_f32 v[150:151], v[70:71], v[194:195], v[150:151] op_sel:[0,1,0]
	v_pk_fma_f32 v[148:149], v[70:71], v[186:187], v[70:71] op_sel:[0,1,0] neg_lo:[1,0,0] neg_hi:[1,0,0]
	v_pk_fma_f32 v[142:143], v[242:243], v[188:189], v[142:143] op_sel_hi:[1,0,1]
	v_pk_fma_f32 v[144:145], v[242:243], v[188:189], v[144:145] op_sel:[0,1,0]
	v_add_f32_dpp v150, v150, v150 quad_perm:[1,0,3,2] row_mask:0xf bank_mask:0xf bound_ctrl:1
	v_add_f32_dpp v151, v151, v151 quad_perm:[1,0,3,2] row_mask:0xf bank_mask:0xf bound_ctrl:1
	v_pk_fma_f32 v[146:147], v[242:243], v[190:191], v[146:147] op_sel_hi:[1,0,1]
	v_add_f32_dpp v150, v150, v150 quad_perm:[2,3,0,1] row_mask:0xf bank_mask:0xf bound_ctrl:1
	v_add_f32_dpp v151, v151, v151 quad_perm:[2,3,0,1] row_mask:0xf bank_mask:0xf bound_ctrl:1
	v_pk_fma_f32 v[148:149], v[242:243], v[190:191], v[148:149] op_sel:[0,1,0]
	v_add_f32_dpp v150, v150, v150 row_half_mirror row_mask:0xf bank_mask:0xf bound_ctrl:1
	v_add_f32_dpp v151, v151, v151 row_half_mirror row_mask:0xf bank_mask:0xf bound_ctrl:1
	s_nop 0
	v_add_f32_dpp v150, v150, v150 row_mirror row_mask:0xf bank_mask:0xf bound_ctrl:1
	v_add_f32_dpp v151, v151, v151 row_mirror row_mask:0xf bank_mask:0xf bound_ctrl:1
	s_waitcnt lgkmcnt(0)
; #define LAS __attribute__((address_space(3)))
; #define ROW16_SUM4(x, y, z, w) do { DPP4(x, y, z, w, "quad_perm:[1,0,3,2]", "s_nop 1"); DPP4(x, y, z, w, "quad_perm:[2,3,0,1]", ""); DPP4(x, y, z, w, "row_half_mirror", ""); DPP4(x, y, z, w, "row_mirror", ""); } while (0)
; template <bool SAMPLE>
; __device__ __forceinline__ void rwkv_unit(PR P, LAS float* lds, const int b, const int h, const int half, const int wv) {
;     ...
;             for (int g = 0; g < TC / GS; ++g) {
;                 float yk0 = 0.f, yk1 = 0.f;
;                 const LAS float* q0 = cur + (g * GS) * 384;
;                 f32x4 r4 = *(const LAS f32x4*)(q0 + j0), o4 = *(const LAS f32x4*)(q0 + 64 + j0), k4 = *(const LAS f32x4*)(q0 + 128 + j0), a4 = *(const LAS f32x4*)(q0 + 192 + j0), b4 = *(const LAS f32x4*)(q0 + 256 + j0);
;                 f32x2 v2 = *(const LAS f32x2*)(q0 + 320 + row0);
;                 float py0 = 0.f, py1 = 0.f;
; #pragma unroll
;                 for (int tt = 0; tt < GS; ++tt) {
;                     const LAS float* qn = q0 + (tt + 1 < GS ? tt + 1 : tt) * 384;
;                     const f32x4 nr4 = *(const LAS f32x4*)(qn + j0), no4 = *(const LAS f32x4*)(qn + 64 + j0), nk4 = *(const LAS f32x4*)(qn + 128 + j0), na4 = *(const LAS f32x4*)(qn + 192 + j0), nb4 = *(const LAS f32x4*)(qn + 256 + j0);
;                     const f32x2 nv2 = *(const LAS f32x2*)(qn + 320 + row0);
;                     f32x2 sa = (S[0] * a4[0] + S[1] * a4[1]) + (S[2] * a4[2] + S[3] * a4[3]);
;                     float sx = sa.x, sy = sa.y; ROW16_SUM4(sx, sy, py0, py1); sa = (f32x2){sx, sy};
;                     if (tt > 0) { yk0 = cgl == tt - 1 ? py0 : yk0; yk1 = cgl == tt - 1 ? py1 : yk1; }
; #pragma unroll
;                     for (int c = 0; c < 4; ++c) { f32x2 t = S[c] - S[c] * o4[c]; t = t + sa * b4[c]; S[c] = t + v2 * k4[c]; }
;                     const f32x2 y = (S[0] * r4[0] + S[1] * r4[1]) + (S[2] * r4[2] + S[3] * r4[3]);
;                     py0 = y.x; py1 = y.y;
;                     r4 = nr4; o4 = no4; k4 = nk4; a4 = na4; b4 = nb4; v2 = nv2;
;                 }
	v_pk_fma_f32 v[66:67], v[150:151], v[196:197], v[142:143] op_sel_hi:[1,0,1]
	v_pk_fma_f32 v[20:21], v[150:151], v[196:197], v[144:145] op_sel:[0,1,0]
	v_pk_fma_f32 v[68:69], v[150:151], v[198:199], v[146:147] op_sel_hi:[1,0,1]
	v_pk_fma_f32 v[70:71], v[150:151], v[198:199], v[148:149] op_sel:[0,1,0]
	v_pk_mul_f32 v[80:81], v[66:67], v[180:181] op_sel_hi:[1,0]
	v_pk_mul_f32 v[150:151], v[66:67], v[212:213] op_sel_hi:[1,0]
	v_pk_fma_f32 v[142:143], v[66:67], v[204:205], v[66:67] op_sel_hi:[1,0,1] neg_lo:[1,0,0] neg_hi:[1,0,0]
	ds_read_b128 v[172:175], v152 offset:6912
	v_pk_fma_f32 v[80:81], v[20:21], v[180:181], v[80:81] op_sel:[0,1,0]
	v_pk_fma_f32 v[150:151], v[20:21], v[212:213], v[150:151] op_sel:[0,1,0]
	v_pk_fma_f32 v[144:145], v[20:21], v[204:205], v[20:21] op_sel:[0,1,0] neg_lo:[1,0,0] neg_hi:[1,0,0]
	ds_read_b128 v[164:167], v152 offset:6400
	v_pk_fma_f32 v[80:81], v[68:69], v[182:183], v[80:81] op_sel_hi:[1,0,1]
	v_pk_fma_f32 v[150:151], v[68:69], v[214:215], v[150:151] op_sel_hi:[1,0,1]
	v_pk_fma_f32 v[146:147], v[68:69], v[206:207], v[68:69] op_sel_hi:[1,0,1] neg_lo:[1,0,0] neg_hi:[1,0,0]
	ds_read2st64_b64 v[248:251], v153 offset0:14 offset1:17
	v_pk_fma_f32 v[80:81], v[70:71], v[182:183], v[80:81] op_sel:[0,1,0]
	v_pk_fma_f32 v[150:151], v[70:71], v[214:215], v[150:151] op_sel:[0,1,0]
	v_pk_fma_f32 v[148:149], v[70:71], v[206:207], v[70:71] op_sel:[0,1,0] neg_lo:[1,0,0] neg_hi:[1,0,0]
	ds_read_b128 v[168:171], v152 offset:6656
	v_pk_fma_f32 v[142:143], v[244:245], v[208:209], v[142:143] op_sel_hi:[1,0,1]
	v_pk_fma_f32 v[144:145], v[244:245], v[208:209], v[144:145] op_sel:[0,1,0]
	v_add_f32_dpp v150, v150, v150 quad_perm:[1,0,3,2] row_mask:0xf bank_mask:0xf bound_ctrl:1
	v_add_f32_dpp v151, v151, v151 quad_perm:[1,0,3,2] row_mask:0xf bank_mask:0xf bound_ctrl:1
	v_pk_fma_f32 v[146:147], v[244:245], v[210:211], v[146:147] op_sel_hi:[1,0,1]
	v_add_f32_dpp v150, v150, v150 quad_perm:[2,3,0,1] row_mask:0xf bank_mask:0xf bound_ctrl:1
	v_add_f32_dpp v151, v151, v151 quad_perm:[2,3,0,1] row_mask:0xf bank_mask:0xf bound_ctrl:1
	v_pk_fma_f32 v[148:149], v[244:245], v[210:211], v[148:149] op_sel:[0,1,0]
	v_add_f32_dpp v150, v150, v150 row_half_mirror row_mask:0xf bank_mask:0xf bound_ctrl:1
	v_add_f32_dpp v151, v151, v151 row_half_mirror row_mask:0xf bank_mask:0xf bound_ctrl:1
	ds_read_b128 v[192:195], v152 offset:8448
	v_add_f32_dpp v150, v150, v150 row_mirror row_mask:0xf bank_mask:0xf bound_ctrl:1
	v_add_f32_dpp v151, v151, v151 row_mirror row_mask:0xf bank_mask:0xf bound_ctrl:1
	ds_read_b128 v[184:187], v152 offset:7936
	ds_read_b128 v[176:179], v152 offset:7168
	ds_read_b128 v[188:191], v152 offset:8192
	ds_read_b128 v[196:199], v152 offset:8704
	ds_read_b128 v[160:163], v152 offset:6144
	ds_read_b128 v[180:183], v152 offset:7680
	v_pk_fma_f32 v[66:67], v[150:151], v[216:217], v[142:143] op_sel_hi:[1,0,1]
	v_pk_fma_f32 v[20:21], v[150:151], v[216:217], v[144:145] op_sel:[0,1,0]
	v_pk_fma_f32 v[68:69], v[150:151], v[218:219], v[146:147] op_sel_hi:[1,0,1]
	v_pk_fma_f32 v[70:71], v[150:151], v[218:219], v[148:149] op_sel:[0,1,0]
	v_pk_mul_f32 v[82:83], v[66:67], v[200:201] op_sel_hi:[1,0]
	v_pk_mul_f32 v[150:151], v[66:67], v[232:233] op_sel_hi:[1,0]
	v_pk_fma_f32 v[142:143], v[66:67], v[224:225], v[66:67] op_sel_hi:[1,0,1] neg_lo:[1,0,0] neg_hi:[1,0,0]
	v_pk_fma_f32 v[82:83], v[20:21], v[200:201], v[82:83] op_sel:[0,1,0]
	v_pk_fma_f32 v[150:151], v[20:21], v[232:233], v[150:151] op_sel:[0,1,0]
	v_pk_fma_f32 v[144:145], v[20:21], v[224:225], v[20:21] op_sel:[0,1,0] neg_lo:[1,0,0] neg_hi:[1,0,0]
	v_pk_fma_f32 v[82:83], v[68:69], v[202:203], v[82:83] op_sel_hi:[1,0,1]
	v_pk_fma_f32 v[150:151], v[68:69], v[234:235], v[150:151] op_sel_hi:[1,0,1]
	v_pk_fma_f32 v[146:147], v[68:69], v[226:227], v[68:69] op_sel_hi:[1,0,1] neg_lo:[1,0,0] neg_hi:[1,0,0]
	v_pk_fma_f32 v[82:83], v[70:71], v[202:203], v[82:83] op_sel:[0,1,0]
	v_pk_fma_f32 v[150:151], v[70:71], v[234:235], v[150:151] op_sel:[0,1,0]
	v_pk_fma_f32 v[148:149], v[70:71], v[226:227], v[70:71] op_sel:[0,1,0] neg_lo:[1,0,0] neg_hi:[1,0,0]
	v_pk_fma_f32 v[142:143], v[246:247], v[228:229], v[142:143] op_sel_hi:[1,0,1]
	v_pk_fma_f32 v[144:145], v[246:247], v[228:229], v[144:145] op_sel:[0,1,0]
	v_add_f32_dpp v150, v150, v150 quad_perm:[1,0,3,2] row_mask:0xf bank_mask:0xf bound_ctrl:1
	v_add_f32_dpp v151, v151, v151 quad_perm:[1,0,3,2] row_mask:0xf bank_mask:0xf bound_ctrl:1
	v_pk_fma_f32 v[146:147], v[246:247], v[230:231], v[146:147] op_sel_hi:[1,0,1]
	v_add_f32_dpp v150, v150, v150 quad_perm:[2,3,0,1] row_mask:0xf bank_mask:0xf bound_ctrl:1
	v_add_f32_dpp v151, v151, v151 quad_perm:[2,3,0,1] row_mask:0xf bank_mask:0xf bound_ctrl:1
	v_pk_fma_f32 v[148:149], v[246:247], v[230:231], v[148:149] op_sel:[0,1,0]
	v_add_f32_dpp v150, v150, v150 row_half_mirror row_mask:0xf bank_mask:0xf bound_ctrl:1
	v_add_f32_dpp v151, v151, v151 row_half_mirror row_mask:0xf bank_mask:0xf bound_ctrl:1
	s_nop 0
	v_add_f32_dpp v150, v150, v150 row_mirror row_mask:0xf bank_mask:0xf bound_ctrl:1
	v_add_f32_dpp v151, v151, v151 row_mirror row_mask:0xf bank_mask:0xf bound_ctrl:1
	s_waitcnt lgkmcnt(0)
; #define LAS __attribute__((address_space(3)))
; #define ROW16_SUM4(x, y, z, w) do { DPP4(x, y, z, w, "quad_perm:[1,0,3,2]", "s_nop 1"); DPP4(x, y, z, w, "quad_perm:[2,3,0,1]", ""); DPP4(x, y, z, w, "row_half_mirror", ""); DPP4(x, y, z, w, "row_mirror", ""); } while (0)
; template <bool SAMPLE>
; __device__ __forceinline__ void rwkv_unit(PR P, LAS float* lds, const int b, const int h, const int half, const int wv) {
;     ...
;             for (int g = 0; g < TC / GS; ++g) {
;                 float yk0 = 0.f, yk1 = 0.f;
;                 const LAS float* q0 = cur + (g * GS) * 384;
;                 f32x4 r4 = *(const LAS f32x4*)(q0 + j0), o4 = *(const LAS f32x4*)(q0 + 64 + j0), k4 = *(const LAS f32x4*)(q0 + 128 + j0), a4 = *(const LAS f32x4*)(q0 + 192 + j0), b4 = *(const LAS f32x4*)(q0 + 256 + j0);
;                 f32x2 v2 = *(const LAS f32x2*)(q0 + 320 + row0);
;                 float py0 = 0.f, py1 = 0.f;
; #pragma unroll
;                 for (int tt = 0; tt < GS; ++tt) {
;                     const LAS float* qn = q0 + (tt + 1 < GS ? tt + 1 : tt) * 384;
;                     const f32x4 nr4 = *(const LAS f32x4*)(qn + j0), no4 = *(const LAS f32x4*)(qn + 64 + j0), nk4 = *(const LAS f32x4*)(qn + 128 + j0), na4 = *(const LAS f32x4*)(qn + 192 + j0), nb4 = *(const LAS f32x4*)(qn + 256 + j0);
;                     const f32x2 nv2 = *(const LAS f32x2*)(qn + 320 + row0);
;                     f32x2 sa = (S[0] * a4[0] + S[1] * a4[1]) + (S[2] * a4[2] + S[3] * a4[3]);
;                     float sx = sa.x, sy = sa.y; ROW16_SUM4(sx, sy, py0, py1); sa = (f32x2){sx, sy};
;                     if (tt > 0) { yk0 = cgl == tt - 1 ? py0 : yk0; yk1 = cgl == tt - 1 ? py1 : yk1; }
; #pragma unroll
;                     for (int c = 0; c < 4; ++c) { f32x2 t = S[c] - S[c] * o4[c]; t = t + sa * b4[c]; S[c] = t + v2 * k4[c]; }
;                     const f32x2 y = (S[0] * r4[0] + S[1] * r4[1]) + (S[2] * r4[2] + S[3] * r4[3]);
;                     py0 = y.x; py1 = y.y;
;                     r4 = nr4; o4 = no4; k4 = nk4; a4 = na4; b4 = nb4; v2 = nv2;
;                 }
	v_pk_fma_f32 v[66:67], v[150:151], v[236:237], v[142:143] op_sel_hi:[1,0,1]
	v_pk_fma_f32 v[20:21], v[150:151], v[236:237], v[144:145] op_sel:[0,1,0]
	v_pk_fma_f32 v[68:69], v[150:151], v[238:239], v[146:147] op_sel_hi:[1,0,1]
	v_pk_fma_f32 v[70:71], v[150:151], v[238:239], v[148:149] op_sel:[0,1,0]
	v_pk_mul_f32 v[84:85], v[66:67], v[220:221] op_sel_hi:[1,0]
	v_pk_mul_f32 v[150:151], v[66:67], v[172:173] op_sel_hi:[1,0]
	v_pk_fma_f32 v[142:143], v[66:67], v[164:165], v[66:67] op_sel_hi:[1,0,1] neg_lo:[1,0,0] neg_hi:[1,0,0]
	ds_read_b128 v[212:215], v152 offset:9984
	v_pk_fma_f32 v[84:85], v[20:21], v[220:221], v[84:85] op_sel:[0,1,0]
	v_pk_fma_f32 v[150:151], v[20:21], v[172:173], v[150:151] op_sel:[0,1,0]
	v_pk_fma_f32 v[144:145], v[20:21], v[164:165], v[20:21] op_sel:[0,1,0] neg_lo:[1,0,0] neg_hi:[1,0,0]
	ds_read_b128 v[204:207], v152 offset:9472
	v_pk_fma_f32 v[84:85], v[68:69], v[222:223], v[84:85] op_sel_hi:[1,0,1]
	v_pk_fma_f32 v[150:151], v[68:69], v[174:175], v[150:151] op_sel_hi:[1,0,1]
	v_pk_fma_f32 v[146:147], v[68:69], v[166:167], v[68:69] op_sel_hi:[1,0,1] neg_lo:[1,0,0] neg_hi:[1,0,0]
	ds_read2st64_b64 v[240:243], v153 offset0:20 offset1:23
	v_pk_fma_f32 v[84:85], v[70:71], v[222:223], v[84:85] op_sel:[0,1,0]
	v_pk_fma_f32 v[150:151], v[70:71], v[174:175], v[150:151] op_sel:[0,1,0]
	v_pk_fma_f32 v[148:149], v[70:71], v[166:167], v[70:71] op_sel:[0,1,0] neg_lo:[1,0,0] neg_hi:[1,0,0]
	ds_read_b128 v[208:211], v152 offset:9728
	v_pk_fma_f32 v[142:143], v[248:249], v[168:169], v[142:143] op_sel_hi:[1,0,1]
	v_pk_fma_f32 v[144:145], v[248:249], v[168:169], v[144:145] op_sel:[0,1,0]
	v_add_f32_dpp v150, v150, v150 quad_perm:[1,0,3,2] row_mask:0xf bank_mask:0xf bound_ctrl:1
	v_add_f32_dpp v151, v151, v151 quad_perm:[1,0,3,2] row_mask:0xf bank_mask:0xf bound_ctrl:1
	v_pk_fma_f32 v[146:147], v[248:249], v[170:171], v[146:147] op_sel_hi:[1,0,1]
	v_add_f32_dpp v150, v150, v150 quad_perm:[2,3,0,1] row_mask:0xf bank_mask:0xf bound_ctrl:1
	v_add_f32_dpp v151, v151, v151 quad_perm:[2,3,0,1] row_mask:0xf bank_mask:0xf bound_ctrl:1
	v_pk_fma_f32 v[148:149], v[248:249], v[170:171], v[148:149] op_sel:[0,1,0]
	v_add_f32_dpp v150, v150, v150 row_half_mirror row_mask:0xf bank_mask:0xf bound_ctrl:1
	v_add_f32_dpp v151, v151, v151 row_half_mirror row_mask:0xf bank_mask:0xf bound_ctrl:1
	ds_read_b128 v[232:235], v152 offset:11520
	v_add_f32_dpp v150, v150, v150 row_mirror row_mask:0xf bank_mask:0xf bound_ctrl:1
	v_add_f32_dpp v151, v151, v151 row_mirror row_mask:0xf bank_mask:0xf bound_ctrl:1
	ds_read_b128 v[224:227], v152 offset:11008
	ds_read_b128 v[216:219], v152 offset:10240
	ds_read_b128 v[228:231], v152 offset:11264
	ds_read_b128 v[236:239], v152 offset:11776
	ds_read_b128 v[200:203], v152 offset:9216
	ds_read_b128 v[220:223], v152 offset:10752
	v_pk_fma_f32 v[66:67], v[150:151], v[176:177], v[142:143] op_sel_hi:[1,0,1]
	v_pk_fma_f32 v[20:21], v[150:151], v[176:177], v[144:145] op_sel:[0,1,0]
	v_pk_fma_f32 v[68:69], v[150:151], v[178:179], v[146:147] op_sel_hi:[1,0,1]
	v_pk_fma_f32 v[70:71], v[150:151], v[178:179], v[148:149] op_sel:[0,1,0]
	v_pk_mul_f32 v[86:87], v[66:67], v[160:161] op_sel_hi:[1,0]
	v_pk_mul_f32 v[150:151], v[66:67], v[192:193] op_sel_hi:[1,0]
	v_pk_fma_f32 v[142:143], v[66:67], v[184:185], v[66:67] op_sel_hi:[1,0,1] neg_lo:[1,0,0] neg_hi:[1,0,0]
	v_pk_fma_f32 v[86:87], v[20:21], v[160:161], v[86:87] op_sel:[0,1,0]
	v_pk_fma_f32 v[150:151], v[20:21], v[192:193], v[150:151] op_sel:[0,1,0]
	v_pk_fma_f32 v[144:145], v[20:21], v[184:185], v[20:21] op_sel:[0,1,0] neg_lo:[1,0,0] neg_hi:[1,0,0]
	v_pk_fma_f32 v[86:87], v[68:69], v[162:163], v[86:87] op_sel_hi:[1,0,1]
	v_pk_fma_f32 v[150:151], v[68:69], v[194:195], v[150:151] op_sel_hi:[1,0,1]
	v_pk_fma_f32 v[146:147], v[68:69], v[186:187], v[68:69] op_sel_hi:[1,0,1] neg_lo:[1,0,0] neg_hi:[1,0,0]
	v_pk_fma_f32 v[86:87], v[70:71], v[162:163], v[86:87] op_sel:[0,1,0]
	v_pk_fma_f32 v[150:151], v[70:71], v[194:195], v[150:151] op_sel:[0,1,0]
	v_pk_fma_f32 v[148:149], v[70:71], v[186:187], v[70:71] op_sel:[0,1,0] neg_lo:[1,0,0] neg_hi:[1,0,0]
	v_pk_fma_f32 v[142:143], v[250:251], v[188:189], v[142:143] op_sel_hi:[1,0,1]
	v_pk_fma_f32 v[144:145], v[250:251], v[188:189], v[144:145] op_sel:[0,1,0]
	v_add_f32_dpp v150, v150, v150 quad_perm:[1,0,3,2] row_mask:0xf bank_mask:0xf bound_ctrl:1
	v_add_f32_dpp v151, v151, v151 quad_perm:[1,0,3,2] row_mask:0xf bank_mask:0xf bound_ctrl:1
	v_pk_fma_f32 v[146:147], v[250:251], v[190:191], v[146:147] op_sel_hi:[1,0,1]
	v_add_f32_dpp v150, v150, v150 quad_perm:[2,3,0,1] row_mask:0xf bank_mask:0xf bound_ctrl:1
	v_add_f32_dpp v151, v151, v151 quad_perm:[2,3,0,1] row_mask:0xf bank_mask:0xf bound_ctrl:1
	v_pk_fma_f32 v[148:149], v[250:251], v[190:191], v[148:149] op_sel:[0,1,0]
	v_add_f32_dpp v150, v150, v150 row_half_mirror row_mask:0xf bank_mask:0xf bound_ctrl:1
	v_add_f32_dpp v151, v151, v151 row_half_mirror row_mask:0xf bank_mask:0xf bound_ctrl:1
	s_nop 0
	v_add_f32_dpp v150, v150, v150 row_mirror row_mask:0xf bank_mask:0xf bound_ctrl:1
	v_add_f32_dpp v151, v151, v151 row_mirror row_mask:0xf bank_mask:0xf bound_ctrl:1
	s_waitcnt lgkmcnt(0)
; #define LAS __attribute__((address_space(3)))
; #define ROW16_SUM4(x, y, z, w) do { DPP4(x, y, z, w, "quad_perm:[1,0,3,2]", "s_nop 1"); DPP4(x, y, z, w, "quad_perm:[2,3,0,1]", ""); DPP4(x, y, z, w, "row_half_mirror", ""); DPP4(x, y, z, w, "row_mirror", ""); } while (0)
; template <bool SAMPLE>
; __device__ __forceinline__ void rwkv_unit(PR P, LAS float* lds, const int b, const int h, const int half, const int wv) {
;     ...
;             for (int g = 0; g < TC / GS; ++g) {
;                 float yk0 = 0.f, yk1 = 0.f;
;                 const LAS float* q0 = cur + (g * GS) * 384;
;                 f32x4 r4 = *(const LAS f32x4*)(q0 + j0), o4 = *(const LAS f32x4*)(q0 + 64 + j0), k4 = *(const LAS f32x4*)(q0 + 128 + j0), a4 = *(const LAS f32x4*)(q0 + 192 + j0), b4 = *(const LAS f32x4*)(q0 + 256 + j0);
;                 f32x2 v2 = *(const LAS f32x2*)(q0 + 320 + row0);
;                 float py0 = 0.f, py1 = 0.f;
; #pragma unroll
;                 for (int tt = 0; tt < GS; ++tt) {
;                     const LAS float* qn = q0 + (tt + 1 < GS ? tt + 1 : tt) * 384;
;                     const f32x4 nr4 = *(const LAS f32x4*)(qn + j0), no4 = *(const LAS f32x4*)(qn + 64 + j0), nk4 = *(const LAS f32x4*)(qn + 128 + j0), na4 = *(const LAS f32x4*)(qn + 192 + j0), nb4 = *(const LAS f32x4*)(qn + 256 + j0);
;                     const f32x2 nv2 = *(const LAS f32x2*)(qn + 320 + row0);
;                     f32x2 sa = (S[0] * a4[0] + S[1] * a4[1]) + (S[2] * a4[2] + S[3] * a4[3]);
;                     float sx = sa.x, sy = sa.y; ROW16_SUM4(sx, sy, py0, py1); sa = (f32x2){sx, sy};
;                     if (tt > 0) { yk0 = cgl == tt - 1 ? py0 : yk0; yk1 = cgl == tt - 1 ? py1 : yk1; }
; #pragma unroll
;                     for (int c = 0; c < 4; ++c) { f32x2 t = S[c] - S[c] * o4[c]; t = t + sa * b4[c]; S[c] = t + v2 * k4[c]; }
;                     const f32x2 y = (S[0] * r4[0] + S[1] * r4[1]) + (S[2] * r4[2] + S[3] * r4[3]);
;                     py0 = y.x; py1 = y.y;
;                     r4 = nr4; o4 = no4; k4 = nk4; a4 = na4; b4 = nb4; v2 = nv2;
;                 }
	v_pk_fma_f32 v[66:67], v[150:151], v[196:197], v[142:143] op_sel_hi:[1,0,1]
	v_pk_fma_f32 v[20:21], v[150:151], v[196:197], v[144:145] op_sel:[0,1,0]
	v_pk_fma_f32 v[68:69], v[150:151], v[198:199], v[146:147] op_sel_hi:[1,0,1]
	v_pk_fma_f32 v[70:71], v[150:151], v[198:199], v[148:149] op_sel:[0,1,0]
	v_pk_mul_f32 v[88:89], v[66:67], v[180:181] op_sel_hi:[1,0]
	v_pk_mul_f32 v[150:151], v[66:67], v[212:213] op_sel_hi:[1,0]
	v_pk_fma_f32 v[142:143], v[66:67], v[204:205], v[66:67] op_sel_hi:[1,0,1] neg_lo:[1,0,0] neg_hi:[1,0,0]
	ds_read_b128 v[172:175], v152 offset:13056
	v_pk_fma_f32 v[88:89], v[20:21], v[180:181], v[88:89] op_sel:[0,1,0]
	v_pk_fma_f32 v[150:151], v[20:21], v[212:213], v[150:151] op_sel:[0,1,0]
	v_pk_fma_f32 v[144:145], v[20:21], v[204:205], v[20:21] op_sel:[0,1,0] neg_lo:[1,0,0] neg_hi:[1,0,0]
	ds_read_b128 v[164:167], v152 offset:12544
	v_pk_fma_f32 v[88:89], v[68:69], v[182:183], v[88:89] op_sel_hi:[1,0,1]
	v_pk_fma_f32 v[150:151], v[68:69], v[214:215], v[150:151] op_sel_hi:[1,0,1]
	v_pk_fma_f32 v[146:147], v[68:69], v[206:207], v[68:69] op_sel_hi:[1,0,1] neg_lo:[1,0,0] neg_hi:[1,0,0]
	ds_read2st64_b64 v[244:247], v153 offset0:26 offset1:29
	v_pk_fma_f32 v[88:89], v[70:71], v[182:183], v[88:89] op_sel:[0,1,0]
	v_pk_fma_f32 v[150:151], v[70:71], v[214:215], v[150:151] op_sel:[0,1,0]
	v_pk_fma_f32 v[148:149], v[70:71], v[206:207], v[70:71] op_sel:[0,1,0] neg_lo:[1,0,0] neg_hi:[1,0,0]
	ds_read_b128 v[168:171], v152 offset:12800
	v_pk_fma_f32 v[142:143], v[240:241], v[208:209], v[142:143] op_sel_hi:[1,0,1]
	v_pk_fma_f32 v[144:145], v[240:241], v[208:209], v[144:145] op_sel:[0,1,0]
	v_add_f32_dpp v150, v150, v150 quad_perm:[1,0,3,2] row_mask:0xf bank_mask:0xf bound_ctrl:1
	v_add_f32_dpp v151, v151, v151 quad_perm:[1,0,3,2] row_mask:0xf bank_mask:0xf bound_ctrl:1
	v_pk_fma_f32 v[146:147], v[240:241], v[210:211], v[146:147] op_sel_hi:[1,0,1]
	v_add_f32_dpp v150, v150, v150 quad_perm:[2,3,0,1] row_mask:0xf bank_mask:0xf bound_ctrl:1
	v_add_f32_dpp v151, v151, v151 quad_perm:[2,3,0,1] row_mask:0xf bank_mask:0xf bound_ctrl:1
	v_pk_fma_f32 v[148:149], v[240:241], v[210:211], v[148:149] op_sel:[0,1,0]
	v_add_f32_dpp v150, v150, v150 row_half_mirror row_mask:0xf bank_mask:0xf bound_ctrl:1
	v_add_f32_dpp v151, v151, v151 row_half_mirror row_mask:0xf bank_mask:0xf bound_ctrl:1
	ds_read_b128 v[192:195], v152 offset:14592
	v_add_f32_dpp v150, v150, v150 row_mirror row_mask:0xf bank_mask:0xf bound_ctrl:1
	v_add_f32_dpp v151, v151, v151 row_mirror row_mask:0xf bank_mask:0xf bound_ctrl:1
	ds_read_b128 v[184:187], v152 offset:14080
	ds_read_b128 v[176:179], v152 offset:13312
	ds_read_b128 v[188:191], v152 offset:14336
	ds_read_b128 v[196:199], v152 offset:14848
	ds_read_b128 v[160:163], v152 offset:12288
	ds_read_b128 v[180:183], v152 offset:13824
	v_pk_fma_f32 v[66:67], v[150:151], v[216:217], v[142:143] op_sel_hi:[1,0,1]
	v_pk_fma_f32 v[20:21], v[150:151], v[216:217], v[144:145] op_sel:[0,1,0]
	v_pk_fma_f32 v[68:69], v[150:151], v[218:219], v[146:147] op_sel_hi:[1,0,1]
	v_pk_fma_f32 v[70:71], v[150:151], v[218:219], v[148:149] op_sel:[0,1,0]
	v_pk_mul_f32 v[90:91], v[66:67], v[200:201] op_sel_hi:[1,0]
	v_pk_mul_f32 v[150:151], v[66:67], v[232:233] op_sel_hi:[1,0]
	v_pk_fma_f32 v[142:143], v[66:67], v[224:225], v[66:67] op_sel_hi:[1,0,1] neg_lo:[1,0,0] neg_hi:[1,0,0]
	v_pk_fma_f32 v[90:91], v[20:21], v[200:201], v[90:91] op_sel:[0,1,0]
	v_pk_fma_f32 v[150:151], v[20:21], v[232:233], v[150:151] op_sel:[0,1,0]
	v_pk_fma_f32 v[144:145], v[20:21], v[224:225], v[20:21] op_sel:[0,1,0] neg_lo:[1,0,0] neg_hi:[1,0,0]
	v_pk_fma_f32 v[90:91], v[68:69], v[202:203], v[90:91] op_sel_hi:[1,0,1]
	v_pk_fma_f32 v[150:151], v[68:69], v[234:235], v[150:151] op_sel_hi:[1,0,1]
	v_pk_fma_f32 v[146:147], v[68:69], v[226:227], v[68:69] op_sel_hi:[1,0,1] neg_lo:[1,0,0] neg_hi:[1,0,0]
	v_pk_fma_f32 v[90:91], v[70:71], v[202:203], v[90:91] op_sel:[0,1,0]
	v_pk_fma_f32 v[150:151], v[70:71], v[234:235], v[150:151] op_sel:[0,1,0]
	v_pk_fma_f32 v[148:149], v[70:71], v[226:227], v[70:71] op_sel:[0,1,0] neg_lo:[1,0,0] neg_hi:[1,0,0]
	v_pk_fma_f32 v[142:143], v[242:243], v[228:229], v[142:143] op_sel_hi:[1,0,1]
	v_pk_fma_f32 v[144:145], v[242:243], v[228:229], v[144:145] op_sel:[0,1,0]
	v_add_f32_dpp v150, v150, v150 quad_perm:[1,0,3,2] row_mask:0xf bank_mask:0xf bound_ctrl:1
	v_add_f32_dpp v151, v151, v151 quad_perm:[1,0,3,2] row_mask:0xf bank_mask:0xf bound_ctrl:1
	v_pk_fma_f32 v[146:147], v[242:243], v[230:231], v[146:147] op_sel_hi:[1,0,1]
	v_add_f32_dpp v150, v150, v150 quad_perm:[2,3,0,1] row_mask:0xf bank_mask:0xf bound_ctrl:1
	v_add_f32_dpp v151, v151, v151 quad_perm:[2,3,0,1] row_mask:0xf bank_mask:0xf bound_ctrl:1
	v_pk_fma_f32 v[148:149], v[242:243], v[230:231], v[148:149] op_sel:[0,1,0]
	v_add_f32_dpp v150, v150, v150 row_half_mirror row_mask:0xf bank_mask:0xf bound_ctrl:1
	v_add_f32_dpp v151, v151, v151 row_half_mirror row_mask:0xf bank_mask:0xf bound_ctrl:1
	s_nop 0
	v_add_f32_dpp v150, v150, v150 row_mirror row_mask:0xf bank_mask:0xf bound_ctrl:1
	v_add_f32_dpp v151, v151, v151 row_mirror row_mask:0xf bank_mask:0xf bound_ctrl:1
	s_waitcnt lgkmcnt(0)
; #define LAS __attribute__((address_space(3)))
; #define ROW16_SUM4(x, y, z, w) do { DPP4(x, y, z, w, "quad_perm:[1,0,3,2]", "s_nop 1"); DPP4(x, y, z, w, "quad_perm:[2,3,0,1]", ""); DPP4(x, y, z, w, "row_half_mirror", ""); DPP4(x, y, z, w, "row_mirror", ""); } while (0)
; template <bool SAMPLE>
; __device__ __forceinline__ void rwkv_unit(PR P, LAS float* lds, const int b, const int h, const int half, const int wv) {
;     ...
;             for (int g = 0; g < TC / GS; ++g) {
;                 float yk0 = 0.f, yk1 = 0.f;
;                 const LAS float* q0 = cur + (g * GS) * 384;
;                 f32x4 r4 = *(const LAS f32x4*)(q0 + j0), o4 = *(const LAS f32x4*)(q0 + 64 + j0), k4 = *(const LAS f32x4*)(q0 + 128 + j0), a4 = *(const LAS f32x4*)(q0 + 192 + j0), b4 = *(const LAS f32x4*)(q0 + 256 + j0);
;                 f32x2 v2 = *(const LAS f32x2*)(q0 + 320 + row0);
;                 float py0 = 0.f, py1 = 0.f;
; #pragma unroll
;                 for (int tt = 0; tt < GS; ++tt) {
;                     const LAS float* qn = q0 + (tt + 1 < GS ? tt + 1 : tt) * 384;
;                     const f32x4 nr4 = *(const LAS f32x4*)(qn + j0), no4 = *(const LAS f32x4*)(qn + 64 + j0), nk4 = *(const LAS f32x4*)(qn + 128 + j0), na4 = *(const LAS f32x4*)(qn + 192 + j0), nb4 = *(const LAS f32x4*)(qn + 256 + j0);
;                     const f32x2 nv2 = *(const LAS f32x2*)(qn + 320 + row0);
;                     f32x2 sa = (S[0] * a4[0] + S[1] * a4[1]) + (S[2] * a4[2] + S[3] * a4[3]);
;                     float sx = sa.x, sy = sa.y; ROW16_SUM4(sx, sy, py0, py1); sa = (f32x2){sx, sy};
;                     if (tt > 0) { yk0 = cgl == tt - 1 ? py0 : yk0; yk1 = cgl == tt - 1 ? py1 : yk1; }
; #pragma unroll
;                     for (int c = 0; c < 4; ++c) { f32x2 t = S[c] - S[c] * o4[c]; t = t + sa * b4[c]; S[c] = t + v2 * k4[c]; }
;                     const f32x2 y = (S[0] * r4[0] + S[1] * r4[1]) + (S[2] * r4[2] + S[3] * r4[3]);
;                     py0 = y.x; py1 = y.y;
;                     r4 = nr4; o4 = no4; k4 = nk4; a4 = na4; b4 = nb4; v2 = nv2;
;                 }
	v_pk_fma_f32 v[66:67], v[150:151], v[236:237], v[142:143] op_sel_hi:[1,0,1]
	v_pk_fma_f32 v[20:21], v[150:151], v[236:237], v[144:145] op_sel:[0,1,0]
	v_pk_fma_f32 v[68:69], v[150:151], v[238:239], v[146:147] op_sel_hi:[1,0,1]
	v_pk_fma_f32 v[70:71], v[150:151], v[238:239], v[148:149] op_sel:[0,1,0]
	v_pk_mul_f32 v[92:93], v[66:67], v[220:221] op_sel_hi:[1,0]
	v_pk_mul_f32 v[150:151], v[66:67], v[172:173] op_sel_hi:[1,0]
	v_pk_fma_f32 v[142:143], v[66:67], v[164:165], v[66:67] op_sel_hi:[1,0,1] neg_lo:[1,0,0] neg_hi:[1,0,0]
	ds_read_b128 v[212:215], v152 offset:16128
	v_pk_fma_f32 v[92:93], v[20:21], v[220:221], v[92:93] op_sel:[0,1,0]
	v_pk_fma_f32 v[150:151], v[20:21], v[172:173], v[150:151] op_sel:[0,1,0]
	v_pk_fma_f32 v[144:145], v[20:21], v[164:165], v[20:21] op_sel:[0,1,0] neg_lo:[1,0,0] neg_hi:[1,0,0]
	ds_read_b128 v[204:207], v152 offset:15616
	v_pk_fma_f32 v[92:93], v[68:69], v[222:223], v[92:93] op_sel_hi:[1,0,1]
	v_pk_fma_f32 v[150:151], v[68:69], v[174:175], v[150:151] op_sel_hi:[1,0,1]
	v_pk_fma_f32 v[146:147], v[68:69], v[166:167], v[68:69] op_sel_hi:[1,0,1] neg_lo:[1,0,0] neg_hi:[1,0,0]
	ds_read2st64_b64 v[248:251], v153 offset0:32 offset1:35
	v_pk_fma_f32 v[92:93], v[70:71], v[222:223], v[92:93] op_sel:[0,1,0]
	v_pk_fma_f32 v[150:151], v[70:71], v[174:175], v[150:151] op_sel:[0,1,0]
	v_pk_fma_f32 v[148:149], v[70:71], v[166:167], v[70:71] op_sel:[0,1,0] neg_lo:[1,0,0] neg_hi:[1,0,0]
	ds_read_b128 v[208:211], v152 offset:15872
	v_pk_fma_f32 v[142:143], v[244:245], v[168:169], v[142:143] op_sel_hi:[1,0,1]
	v_pk_fma_f32 v[144:145], v[244:245], v[168:169], v[144:145] op_sel:[0,1,0]
	v_add_f32_dpp v150, v150, v150 quad_perm:[1,0,3,2] row_mask:0xf bank_mask:0xf bound_ctrl:1
	v_add_f32_dpp v151, v151, v151 quad_perm:[1,0,3,2] row_mask:0xf bank_mask:0xf bound_ctrl:1
	v_pk_fma_f32 v[146:147], v[244:245], v[170:171], v[146:147] op_sel_hi:[1,0,1]
	v_add_f32_dpp v150, v150, v150 quad_perm:[2,3,0,1] row_mask:0xf bank_mask:0xf bound_ctrl:1
	v_add_f32_dpp v151, v151, v151 quad_perm:[2,3,0,1] row_mask:0xf bank_mask:0xf bound_ctrl:1
	v_pk_fma_f32 v[148:149], v[244:245], v[170:171], v[148:149] op_sel:[0,1,0]
	v_add_f32_dpp v150, v150, v150 row_half_mirror row_mask:0xf bank_mask:0xf bound_ctrl:1
	v_add_f32_dpp v151, v151, v151 row_half_mirror row_mask:0xf bank_mask:0xf bound_ctrl:1
	ds_read_b128 v[232:235], v152 offset:17664
	v_add_f32_dpp v150, v150, v150 row_mirror row_mask:0xf bank_mask:0xf bound_ctrl:1
	v_add_f32_dpp v151, v151, v151 row_mirror row_mask:0xf bank_mask:0xf bound_ctrl:1
	ds_read_b128 v[224:227], v152 offset:17152
	ds_read_b128 v[216:219], v152 offset:16384
	ds_read_b128 v[228:231], v152 offset:17408
	ds_read_b128 v[236:239], v152 offset:17920
	ds_read_b128 v[200:203], v152 offset:15360
	ds_read_b128 v[220:223], v152 offset:16896
	v_pk_fma_f32 v[66:67], v[150:151], v[176:177], v[142:143] op_sel_hi:[1,0,1]
	v_pk_fma_f32 v[20:21], v[150:151], v[176:177], v[144:145] op_sel:[0,1,0]
	v_pk_fma_f32 v[68:69], v[150:151], v[178:179], v[146:147] op_sel_hi:[1,0,1]
	v_pk_fma_f32 v[70:71], v[150:151], v[178:179], v[148:149] op_sel:[0,1,0]
	v_pk_mul_f32 v[94:95], v[66:67], v[160:161] op_sel_hi:[1,0]
	v_pk_mul_f32 v[150:151], v[66:67], v[192:193] op_sel_hi:[1,0]
	v_pk_fma_f32 v[142:143], v[66:67], v[184:185], v[66:67] op_sel_hi:[1,0,1] neg_lo:[1,0,0] neg_hi:[1,0,0]
	v_pk_fma_f32 v[94:95], v[20:21], v[160:161], v[94:95] op_sel:[0,1,0]
	v_pk_fma_f32 v[150:151], v[20:21], v[192:193], v[150:151] op_sel:[0,1,0]
	v_pk_fma_f32 v[144:145], v[20:21], v[184:185], v[20:21] op_sel:[0,1,0] neg_lo:[1,0,0] neg_hi:[1,0,0]
	v_pk_fma_f32 v[94:95], v[68:69], v[162:163], v[94:95] op_sel_hi:[1,0,1]
	v_pk_fma_f32 v[150:151], v[68:69], v[194:195], v[150:151] op_sel_hi:[1,0,1]
	v_pk_fma_f32 v[146:147], v[68:69], v[186:187], v[68:69] op_sel_hi:[1,0,1] neg_lo:[1,0,0] neg_hi:[1,0,0]
	v_pk_fma_f32 v[94:95], v[70:71], v[162:163], v[94:95] op_sel:[0,1,0]
	v_pk_fma_f32 v[150:151], v[70:71], v[194:195], v[150:151] op_sel:[0,1,0]
	v_pk_fma_f32 v[148:149], v[70:71], v[186:187], v[70:71] op_sel:[0,1,0] neg_lo:[1,0,0] neg_hi:[1,0,0]
	v_pk_fma_f32 v[142:143], v[246:247], v[188:189], v[142:143] op_sel_hi:[1,0,1]
	v_pk_fma_f32 v[144:145], v[246:247], v[188:189], v[144:145] op_sel:[0,1,0]
	v_add_f32_dpp v150, v150, v150 quad_perm:[1,0,3,2] row_mask:0xf bank_mask:0xf bound_ctrl:1
	v_add_f32_dpp v151, v151, v151 quad_perm:[1,0,3,2] row_mask:0xf bank_mask:0xf bound_ctrl:1
	v_pk_fma_f32 v[146:147], v[246:247], v[190:191], v[146:147] op_sel_hi:[1,0,1]
	v_add_f32_dpp v150, v150, v150 quad_perm:[2,3,0,1] row_mask:0xf bank_mask:0xf bound_ctrl:1
	v_add_f32_dpp v151, v151, v151 quad_perm:[2,3,0,1] row_mask:0xf bank_mask:0xf bound_ctrl:1
	v_pk_fma_f32 v[148:149], v[246:247], v[190:191], v[148:149] op_sel:[0,1,0]
	v_add_f32_dpp v150, v150, v150 row_half_mirror row_mask:0xf bank_mask:0xf bound_ctrl:1
	v_add_f32_dpp v151, v151, v151 row_half_mirror row_mask:0xf bank_mask:0xf bound_ctrl:1
	s_nop 0
	v_add_f32_dpp v150, v150, v150 row_mirror row_mask:0xf bank_mask:0xf bound_ctrl:1
	v_add_f32_dpp v151, v151, v151 row_mirror row_mask:0xf bank_mask:0xf bound_ctrl:1
	s_waitcnt lgkmcnt(0)
; #define LAS __attribute__((address_space(3)))
; #define ROW16_SUM4(x, y, z, w) do { DPP4(x, y, z, w, "quad_perm:[1,0,3,2]", "s_nop 1"); DPP4(x, y, z, w, "quad_perm:[2,3,0,1]", ""); DPP4(x, y, z, w, "row_half_mirror", ""); DPP4(x, y, z, w, "row_mirror", ""); } while (0)
; template <bool SAMPLE>
; __device__ __forceinline__ void rwkv_unit(PR P, LAS float* lds, const int b, const int h, const int half, const int wv) {
;     ...
;             for (int g = 0; g < TC / GS; ++g) {
;                 float yk0 = 0.f, yk1 = 0.f;
;                 const LAS float* q0 = cur + (g * GS) * 384;
;                 f32x4 r4 = *(const LAS f32x4*)(q0 + j0), o4 = *(const LAS f32x4*)(q0 + 64 + j0), k4 = *(const LAS f32x4*)(q0 + 128 + j0), a4 = *(const LAS f32x4*)(q0 + 192 + j0), b4 = *(const LAS f32x4*)(q0 + 256 + j0);
;                 f32x2 v2 = *(const LAS f32x2*)(q0 + 320 + row0);
;                 float py0 = 0.f, py1 = 0.f;
; #pragma unroll
;                 for (int tt = 0; tt < GS; ++tt) {
;                     const LAS float* qn = q0 + (tt + 1 < GS ? tt + 1 : tt) * 384;
;                     const f32x4 nr4 = *(const LAS f32x4*)(qn + j0), no4 = *(const LAS f32x4*)(qn + 64 + j0), nk4 = *(const LAS f32x4*)(qn + 128 + j0), na4 = *(const LAS f32x4*)(qn + 192 + j0), nb4 = *(const LAS f32x4*)(qn + 256 + j0);
;                     const f32x2 nv2 = *(const LAS f32x2*)(qn + 320 + row0);
;                     f32x2 sa = (S[0] * a4[0] + S[1] * a4[1]) + (S[2] * a4[2] + S[3] * a4[3]);
;                     float sx = sa.x, sy = sa.y; ROW16_SUM4(sx, sy, py0, py1); sa = (f32x2){sx, sy};
;                     if (tt > 0) { yk0 = cgl == tt - 1 ? py0 : yk0; yk1 = cgl == tt - 1 ? py1 : yk1; }
; #pragma unroll
;                     for (int c = 0; c < 4; ++c) { f32x2 t = S[c] - S[c] * o4[c]; t = t + sa * b4[c]; S[c] = t + v2 * k4[c]; }
;                     const f32x2 y = (S[0] * r4[0] + S[1] * r4[1]) + (S[2] * r4[2] + S[3] * r4[3]);
;                     py0 = y.x; py1 = y.y;
;                     r4 = nr4; o4 = no4; k4 = nk4; a4 = na4; b4 = nb4; v2 = nv2;
;                 }
	v_pk_fma_f32 v[66:67], v[150:151], v[196:197], v[142:143] op_sel_hi:[1,0,1]
	v_pk_fma_f32 v[20:21], v[150:151], v[196:197], v[144:145] op_sel:[0,1,0]
	v_pk_fma_f32 v[68:69], v[150:151], v[198:199], v[146:147] op_sel_hi:[1,0,1]
	v_pk_fma_f32 v[70:71], v[150:151], v[198:199], v[148:149] op_sel:[0,1,0]
	v_pk_mul_f32 v[96:97], v[66:67], v[180:181] op_sel_hi:[1,0]
	v_pk_mul_f32 v[150:151], v[66:67], v[212:213] op_sel_hi:[1,0]
	v_pk_fma_f32 v[142:143], v[66:67], v[204:205], v[66:67] op_sel_hi:[1,0,1] neg_lo:[1,0,0] neg_hi:[1,0,0]
	ds_read_b128 v[172:175], v152 offset:19200
	v_pk_fma_f32 v[96:97], v[20:21], v[180:181], v[96:97] op_sel:[0,1,0]
	v_pk_fma_f32 v[150:151], v[20:21], v[212:213], v[150:151] op_sel:[0,1,0]
	v_pk_fma_f32 v[144:145], v[20:21], v[204:205], v[20:21] op_sel:[0,1,0] neg_lo:[1,0,0] neg_hi:[1,0,0]
	ds_read_b128 v[164:167], v152 offset:18688
	v_pk_fma_f32 v[96:97], v[68:69], v[182:183], v[96:97] op_sel_hi:[1,0,1]
	v_pk_fma_f32 v[150:151], v[68:69], v[214:215], v[150:151] op_sel_hi:[1,0,1]
	v_pk_fma_f32 v[146:147], v[68:69], v[206:207], v[68:69] op_sel_hi:[1,0,1] neg_lo:[1,0,0] neg_hi:[1,0,0]
	ds_read2st64_b64 v[240:243], v153 offset0:38 offset1:41
	v_pk_fma_f32 v[96:97], v[70:71], v[182:183], v[96:97] op_sel:[0,1,0]
	v_pk_fma_f32 v[150:151], v[70:71], v[214:215], v[150:151] op_sel:[0,1,0]
	v_pk_fma_f32 v[148:149], v[70:71], v[206:207], v[70:71] op_sel:[0,1,0] neg_lo:[1,0,0] neg_hi:[1,0,0]
	ds_read_b128 v[168:171], v152 offset:18944
	v_pk_fma_f32 v[142:143], v[248:249], v[208:209], v[142:143] op_sel_hi:[1,0,1]
	v_pk_fma_f32 v[144:145], v[248:249], v[208:209], v[144:145] op_sel:[0,1,0]
	v_add_f32_dpp v150, v150, v150 quad_perm:[1,0,3,2] row_mask:0xf bank_mask:0xf bound_ctrl:1
	v_add_f32_dpp v151, v151, v151 quad_perm:[1,0,3,2] row_mask:0xf bank_mask:0xf bound_ctrl:1
	v_pk_fma_f32 v[146:147], v[248:249], v[210:211], v[146:147] op_sel_hi:[1,0,1]
	v_add_f32_dpp v150, v150, v150 quad_perm:[2,3,0,1] row_mask:0xf bank_mask:0xf bound_ctrl:1
	v_add_f32_dpp v151, v151, v151 quad_perm:[2,3,0,1] row_mask:0xf bank_mask:0xf bound_ctrl:1
	v_pk_fma_f32 v[148:149], v[248:249], v[210:211], v[148:149] op_sel:[0,1,0]
	v_add_f32_dpp v150, v150, v150 row_half_mirror row_mask:0xf bank_mask:0xf bound_ctrl:1
	v_add_f32_dpp v151, v151, v151 row_half_mirror row_mask:0xf bank_mask:0xf bound_ctrl:1
	ds_read_b128 v[192:195], v152 offset:20736
	v_add_f32_dpp v150, v150, v150 row_mirror row_mask:0xf bank_mask:0xf bound_ctrl:1
	v_add_f32_dpp v151, v151, v151 row_mirror row_mask:0xf bank_mask:0xf bound_ctrl:1
	ds_read_b128 v[184:187], v152 offset:20224
	ds_read_b128 v[176:179], v152 offset:19456
	ds_read_b128 v[188:191], v152 offset:20480
	ds_read_b128 v[196:199], v152 offset:20992
	ds_read_b128 v[160:163], v152 offset:18432
	ds_read_b128 v[180:183], v152 offset:19968
	v_pk_fma_f32 v[66:67], v[150:151], v[216:217], v[142:143] op_sel_hi:[1,0,1]
	v_pk_fma_f32 v[20:21], v[150:151], v[216:217], v[144:145] op_sel:[0,1,0]
	v_pk_fma_f32 v[68:69], v[150:151], v[218:219], v[146:147] op_sel_hi:[1,0,1]
	v_pk_fma_f32 v[70:71], v[150:151], v[218:219], v[148:149] op_sel:[0,1,0]
	v_pk_mul_f32 v[98:99], v[66:67], v[200:201] op_sel_hi:[1,0]
	v_pk_mul_f32 v[150:151], v[66:67], v[232:233] op_sel_hi:[1,0]
	v_pk_fma_f32 v[142:143], v[66:67], v[224:225], v[66:67] op_sel_hi:[1,0,1] neg_lo:[1,0,0] neg_hi:[1,0,0]
	v_pk_fma_f32 v[98:99], v[20:21], v[200:201], v[98:99] op_sel:[0,1,0]
	v_pk_fma_f32 v[150:151], v[20:21], v[232:233], v[150:151] op_sel:[0,1,0]
	v_pk_fma_f32 v[144:145], v[20:21], v[224:225], v[20:21] op_sel:[0,1,0] neg_lo:[1,0,0] neg_hi:[1,0,0]
	v_pk_fma_f32 v[98:99], v[68:69], v[202:203], v[98:99] op_sel_hi:[1,0,1]
	v_pk_fma_f32 v[150:151], v[68:69], v[234:235], v[150:151] op_sel_hi:[1,0,1]
	v_pk_fma_f32 v[146:147], v[68:69], v[226:227], v[68:69] op_sel_hi:[1,0,1] neg_lo:[1,0,0] neg_hi:[1,0,0]
	v_pk_fma_f32 v[98:99], v[70:71], v[202:203], v[98:99] op_sel:[0,1,0]
	v_pk_fma_f32 v[150:151], v[70:71], v[234:235], v[150:151] op_sel:[0,1,0]
	v_pk_fma_f32 v[148:149], v[70:71], v[226:227], v[70:71] op_sel:[0,1,0] neg_lo:[1,0,0] neg_hi:[1,0,0]
	v_pk_fma_f32 v[142:143], v[250:251], v[228:229], v[142:143] op_sel_hi:[1,0,1]
	v_pk_fma_f32 v[144:145], v[250:251], v[228:229], v[144:145] op_sel:[0,1,0]
	v_add_f32_dpp v150, v150, v150 quad_perm:[1,0,3,2] row_mask:0xf bank_mask:0xf bound_ctrl:1
	v_add_f32_dpp v151, v151, v151 quad_perm:[1,0,3,2] row_mask:0xf bank_mask:0xf bound_ctrl:1
	v_pk_fma_f32 v[146:147], v[250:251], v[230:231], v[146:147] op_sel_hi:[1,0,1]
	v_add_f32_dpp v150, v150, v150 quad_perm:[2,3,0,1] row_mask:0xf bank_mask:0xf bound_ctrl:1
	v_add_f32_dpp v151, v151, v151 quad_perm:[2,3,0,1] row_mask:0xf bank_mask:0xf bound_ctrl:1
	v_pk_fma_f32 v[148:149], v[250:251], v[230:231], v[148:149] op_sel:[0,1,0]
	v_add_f32_dpp v150, v150, v150 row_half_mirror row_mask:0xf bank_mask:0xf bound_ctrl:1
	v_add_f32_dpp v151, v151, v151 row_half_mirror row_mask:0xf bank_mask:0xf bound_ctrl:1
	s_nop 0
	v_add_f32_dpp v150, v150, v150 row_mirror row_mask:0xf bank_mask:0xf bound_ctrl:1
	v_add_f32_dpp v151, v151, v151 row_mirror row_mask:0xf bank_mask:0xf bound_ctrl:1
	s_waitcnt lgkmcnt(0)
; #define LAS __attribute__((address_space(3)))
; #define ROW16_SUM4(x, y, z, w) do { DPP4(x, y, z, w, "quad_perm:[1,0,3,2]", "s_nop 1"); DPP4(x, y, z, w, "quad_perm:[2,3,0,1]", ""); DPP4(x, y, z, w, "row_half_mirror", ""); DPP4(x, y, z, w, "row_mirror", ""); } while (0)
; template <bool SAMPLE>
; __device__ __forceinline__ void rwkv_unit(PR P, LAS float* lds, const int b, const int h, const int half, const int wv) {
;     ...
;             for (int g = 0; g < TC / GS; ++g) {
;                 float yk0 = 0.f, yk1 = 0.f;
;                 const LAS float* q0 = cur + (g * GS) * 384;
;                 f32x4 r4 = *(const LAS f32x4*)(q0 + j0), o4 = *(const LAS f32x4*)(q0 + 64 + j0), k4 = *(const LAS f32x4*)(q0 + 128 + j0), a4 = *(const LAS f32x4*)(q0 + 192 + j0), b4 = *(const LAS f32x4*)(q0 + 256 + j0);
;                 f32x2 v2 = *(const LAS f32x2*)(q0 + 320 + row0);
;                 float py0 = 0.f, py1 = 0.f;
; #pragma unroll
;                 for (int tt = 0; tt < GS; ++tt) {
;                     const LAS float* qn = q0 + (tt + 1 < GS ? tt + 1 : tt) * 384;
;                     const f32x4 nr4 = *(const LAS f32x4*)(qn + j0), no4 = *(const LAS f32x4*)(qn + 64 + j0), nk4 = *(const LAS f32x4*)(qn + 128 + j0), na4 = *(const LAS f32x4*)(qn + 192 + j0), nb4 = *(const LAS f32x4*)(qn + 256 + j0);
;                     const f32x2 nv2 = *(const LAS f32x2*)(qn + 320 + row0);
;                     f32x2 sa = (S[0] * a4[0] + S[1] * a4[1]) + (S[2] * a4[2] + S[3] * a4[3]);
;                     float sx = sa.x, sy = sa.y; ROW16_SUM4(sx, sy, py0, py1); sa = (f32x2){sx, sy};
;                     if (tt > 0) { yk0 = cgl == tt - 1 ? py0 : yk0; yk1 = cgl == tt - 1 ? py1 : yk1; }
; #pragma unroll
;                     for (int c = 0; c < 4; ++c) { f32x2 t = S[c] - S[c] * o4[c]; t = t + sa * b4[c]; S[c] = t + v2 * k4[c]; }
;                     const f32x2 y = (S[0] * r4[0] + S[1] * r4[1]) + (S[2] * r4[2] + S[3] * r4[3]);
;                     py0 = y.x; py1 = y.y;
;                     r4 = nr4; o4 = no4; k4 = nk4; a4 = na4; b4 = nb4; v2 = nv2;
;                 }
	v_pk_fma_f32 v[66:67], v[150:151], v[236:237], v[142:143] op_sel_hi:[1,0,1]
	v_pk_fma_f32 v[20:21], v[150:151], v[236:237], v[144:145] op_sel:[0,1,0]
	v_pk_fma_f32 v[68:69], v[150:151], v[238:239], v[146:147] op_sel_hi:[1,0,1]
	v_pk_fma_f32 v[70:71], v[150:151], v[238:239], v[148:149] op_sel:[0,1,0]
	v_pk_mul_f32 v[100:101], v[66:67], v[220:221] op_sel_hi:[1,0]
	v_pk_mul_f32 v[150:151], v[66:67], v[172:173] op_sel_hi:[1,0]
	v_pk_fma_f32 v[142:143], v[66:67], v[164:165], v[66:67] op_sel_hi:[1,0,1] neg_lo:[1,0,0] neg_hi:[1,0,0]
	ds_read_b128 v[212:215], v152 offset:22272
	v_pk_fma_f32 v[100:101], v[20:21], v[220:221], v[100:101] op_sel:[0,1,0]
	v_pk_fma_f32 v[150:151], v[20:21], v[172:173], v[150:151] op_sel:[0,1,0]
	v_pk_fma_f32 v[144:145], v[20:21], v[164:165], v[20:21] op_sel:[0,1,0] neg_lo:[1,0,0] neg_hi:[1,0,0]
	ds_read_b128 v[204:207], v152 offset:21760
	v_pk_fma_f32 v[100:101], v[68:69], v[222:223], v[100:101] op_sel_hi:[1,0,1]
	v_pk_fma_f32 v[150:151], v[68:69], v[174:175], v[150:151] op_sel_hi:[1,0,1]
	v_pk_fma_f32 v[146:147], v[68:69], v[166:167], v[68:69] op_sel_hi:[1,0,1] neg_lo:[1,0,0] neg_hi:[1,0,0]
	ds_read2st64_b64 v[244:247], v153 offset0:44 offset1:47
	v_pk_fma_f32 v[100:101], v[70:71], v[222:223], v[100:101] op_sel:[0,1,0]
	v_pk_fma_f32 v[150:151], v[70:71], v[174:175], v[150:151] op_sel:[0,1,0]
	v_pk_fma_f32 v[148:149], v[70:71], v[166:167], v[70:71] op_sel:[0,1,0] neg_lo:[1,0,0] neg_hi:[1,0,0]
	ds_read_b128 v[208:211], v152 offset:22016
	v_pk_fma_f32 v[142:143], v[240:241], v[168:169], v[142:143] op_sel_hi:[1,0,1]
	v_pk_fma_f32 v[144:145], v[240:241], v[168:169], v[144:145] op_sel:[0,1,0]
	v_add_f32_dpp v150, v150, v150 quad_perm:[1,0,3,2] row_mask:0xf bank_mask:0xf bound_ctrl:1
	v_add_f32_dpp v151, v151, v151 quad_perm:[1,0,3,2] row_mask:0xf bank_mask:0xf bound_ctrl:1
	v_pk_fma_f32 v[146:147], v[240:241], v[170:171], v[146:147] op_sel_hi:[1,0,1]
	v_add_f32_dpp v150, v150, v150 quad_perm:[2,3,0,1] row_mask:0xf bank_mask:0xf bound_ctrl:1
	v_add_f32_dpp v151, v151, v151 quad_perm:[2,3,0,1] row_mask:0xf bank_mask:0xf bound_ctrl:1
	v_pk_fma_f32 v[148:149], v[240:241], v[170:171], v[148:149] op_sel:[0,1,0]
	v_add_f32_dpp v150, v150, v150 row_half_mirror row_mask:0xf bank_mask:0xf bound_ctrl:1
	v_add_f32_dpp v151, v151, v151 row_half_mirror row_mask:0xf bank_mask:0xf bound_ctrl:1
	ds_read_b128 v[232:235], v152 offset:23808
	v_add_f32_dpp v150, v150, v150 row_mirror row_mask:0xf bank_mask:0xf bound_ctrl:1
	v_add_f32_dpp v151, v151, v151 row_mirror row_mask:0xf bank_mask:0xf bound_ctrl:1
	ds_read_b128 v[224:227], v152 offset:23296
	ds_read_b128 v[216:219], v152 offset:22528
	ds_read_b128 v[228:231], v152 offset:23552
	ds_read_b128 v[236:239], v152 offset:24064
	ds_read_b128 v[200:203], v152 offset:21504
	ds_read_b128 v[220:223], v152 offset:23040
	v_pk_fma_f32 v[66:67], v[150:151], v[176:177], v[142:143] op_sel_hi:[1,0,1]
	v_pk_fma_f32 v[20:21], v[150:151], v[176:177], v[144:145] op_sel:[0,1,0]
	v_pk_fma_f32 v[68:69], v[150:151], v[178:179], v[146:147] op_sel_hi:[1,0,1]
	v_pk_fma_f32 v[70:71], v[150:151], v[178:179], v[148:149] op_sel:[0,1,0]
	v_pk_mul_f32 v[102:103], v[66:67], v[160:161] op_sel_hi:[1,0]
	v_pk_mul_f32 v[150:151], v[66:67], v[192:193] op_sel_hi:[1,0]
	v_pk_fma_f32 v[142:143], v[66:67], v[184:185], v[66:67] op_sel_hi:[1,0,1] neg_lo:[1,0,0] neg_hi:[1,0,0]
	v_pk_fma_f32 v[102:103], v[20:21], v[160:161], v[102:103] op_sel:[0,1,0]
	v_pk_fma_f32 v[150:151], v[20:21], v[192:193], v[150:151] op_sel:[0,1,0]
	v_pk_fma_f32 v[144:145], v[20:21], v[184:185], v[20:21] op_sel:[0,1,0] neg_lo:[1,0,0] neg_hi:[1,0,0]
	v_pk_fma_f32 v[102:103], v[68:69], v[162:163], v[102:103] op_sel_hi:[1,0,1]
	v_pk_fma_f32 v[150:151], v[68:69], v[194:195], v[150:151] op_sel_hi:[1,0,1]
	v_pk_fma_f32 v[146:147], v[68:69], v[186:187], v[68:69] op_sel_hi:[1,0,1] neg_lo:[1,0,0] neg_hi:[1,0,0]
	v_pk_fma_f32 v[102:103], v[70:71], v[162:163], v[102:103] op_sel:[0,1,0]
	v_pk_fma_f32 v[150:151], v[70:71], v[194:195], v[150:151] op_sel:[0,1,0]
	v_pk_fma_f32 v[148:149], v[70:71], v[186:187], v[70:71] op_sel:[0,1,0] neg_lo:[1,0,0] neg_hi:[1,0,0]
	v_pk_fma_f32 v[142:143], v[242:243], v[188:189], v[142:143] op_sel_hi:[1,0,1]
	v_pk_fma_f32 v[144:145], v[242:243], v[188:189], v[144:145] op_sel:[0,1,0]
	v_add_f32_dpp v150, v150, v150 quad_perm:[1,0,3,2] row_mask:0xf bank_mask:0xf bound_ctrl:1
	v_add_f32_dpp v151, v151, v151 quad_perm:[1,0,3,2] row_mask:0xf bank_mask:0xf bound_ctrl:1
	v_pk_fma_f32 v[146:147], v[242:243], v[190:191], v[146:147] op_sel_hi:[1,0,1]
	v_add_f32_dpp v150, v150, v150 quad_perm:[2,3,0,1] row_mask:0xf bank_mask:0xf bound_ctrl:1
	v_add_f32_dpp v151, v151, v151 quad_perm:[2,3,0,1] row_mask:0xf bank_mask:0xf bound_ctrl:1
	v_pk_fma_f32 v[148:149], v[242:243], v[190:191], v[148:149] op_sel:[0,1,0]
	v_add_f32_dpp v150, v150, v150 row_half_mirror row_mask:0xf bank_mask:0xf bound_ctrl:1
	v_add_f32_dpp v151, v151, v151 row_half_mirror row_mask:0xf bank_mask:0xf bound_ctrl:1
	s_nop 0
	v_add_f32_dpp v150, v150, v150 row_mirror row_mask:0xf bank_mask:0xf bound_ctrl:1
	v_add_f32_dpp v151, v151, v151 row_mirror row_mask:0xf bank_mask:0xf bound_ctrl:1
	s_waitcnt lgkmcnt(0)
; #define LAS __attribute__((address_space(3)))
; #define ROW16_SUM4(x, y, z, w) do { DPP4(x, y, z, w, "quad_perm:[1,0,3,2]", "s_nop 1"); DPP4(x, y, z, w, "quad_perm:[2,3,0,1]", ""); DPP4(x, y, z, w, "row_half_mirror", ""); DPP4(x, y, z, w, "row_mirror", ""); } while (0)
; template <bool SAMPLE>
; __device__ __forceinline__ void rwkv_unit(PR P, LAS float* lds, const int b, const int h, const int half, const int wv) {
;     ...
;             for (int g = 0; g < TC / GS; ++g) {
;                 float yk0 = 0.f, yk1 = 0.f;
;                 const LAS float* q0 = cur + (g * GS) * 384;
;                 f32x4 r4 = *(const LAS f32x4*)(q0 + j0), o4 = *(const LAS f32x4*)(q0 + 64 + j0), k4 = *(const LAS f32x4*)(q0 + 128 + j0), a4 = *(const LAS f32x4*)(q0 + 192 + j0), b4 = *(const LAS f32x4*)(q0 + 256 + j0);
;                 f32x2 v2 = *(const LAS f32x2*)(q0 + 320 + row0);
;                 float py0 = 0.f, py1 = 0.f;
; #pragma unroll
;                 for (int tt = 0; tt < GS; ++tt) {
;                     const LAS float* qn = q0 + (tt + 1 < GS ? tt + 1 : tt) * 384;
;                     const f32x4 nr4 = *(const LAS f32x4*)(qn + j0), no4 = *(const LAS f32x4*)(qn + 64 + j0), nk4 = *(const LAS f32x4*)(qn + 128 + j0), na4 = *(const LAS f32x4*)(qn + 192 + j0), nb4 = *(const LAS f32x4*)(qn + 256 + j0);
;                     const f32x2 nv2 = *(const LAS f32x2*)(qn + 320 + row0);
;                     f32x2 sa = (S[0] * a4[0] + S[1] * a4[1]) + (S[2] * a4[2] + S[3] * a4[3]);
;                     float sx = sa.x, sy = sa.y; ROW16_SUM4(sx, sy, py0, py1); sa = (f32x2){sx, sy};
;                     if (tt > 0) { yk0 = cgl == tt - 1 ? py0 : yk0; yk1 = cgl == tt - 1 ? py1 : yk1; }
; #pragma unroll
;                     for (int c = 0; c < 4; ++c) { f32x2 t = S[c] - S[c] * o4[c]; t = t + sa * b4[c]; S[c] = t + v2 * k4[c]; }
;                     const f32x2 y = (S[0] * r4[0] + S[1] * r4[1]) + (S[2] * r4[2] + S[3] * r4[3]);
;                     py0 = y.x; py1 = y.y;
;                     r4 = nr4; o4 = no4; k4 = nk4; a4 = na4; b4 = nb4; v2 = nv2;
;                 }
	v_pk_fma_f32 v[66:67], v[150:151], v[196:197], v[142:143] op_sel_hi:[1,0,1]
	v_pk_fma_f32 v[20:21], v[150:151], v[196:197], v[144:145] op_sel:[0,1,0]
	v_pk_fma_f32 v[68:69], v[150:151], v[198:199], v[146:147] op_sel_hi:[1,0,1]
	v_pk_fma_f32 v[70:71], v[150:151], v[198:199], v[148:149] op_sel:[0,1,0]
	v_pk_mul_f32 v[104:105], v[66:67], v[180:181] op_sel_hi:[1,0]
	v_pk_mul_f32 v[150:151], v[66:67], v[212:213] op_sel_hi:[1,0]
	v_pk_fma_f32 v[142:143], v[66:67], v[204:205], v[66:67] op_sel_hi:[1,0,1] neg_lo:[1,0,0] neg_hi:[1,0,0]
	ds_read_b128 v[172:175], v152 offset:25344
	v_pk_fma_f32 v[104:105], v[20:21], v[180:181], v[104:105] op_sel:[0,1,0]
	v_pk_fma_f32 v[150:151], v[20:21], v[212:213], v[150:151] op_sel:[0,1,0]
	v_pk_fma_f32 v[144:145], v[20:21], v[204:205], v[20:21] op_sel:[0,1,0] neg_lo:[1,0,0] neg_hi:[1,0,0]
	ds_read_b128 v[164:167], v152 offset:24832
	v_pk_fma_f32 v[104:105], v[68:69], v[182:183], v[104:105] op_sel_hi:[1,0,1]
	v_pk_fma_f32 v[150:151], v[68:69], v[214:215], v[150:151] op_sel_hi:[1,0,1]
	v_pk_fma_f32 v[146:147], v[68:69], v[206:207], v[68:69] op_sel_hi:[1,0,1] neg_lo:[1,0,0] neg_hi:[1,0,0]
	ds_read2st64_b64 v[248:251], v153 offset0:50 offset1:53
	v_pk_fma_f32 v[104:105], v[70:71], v[182:183], v[104:105] op_sel:[0,1,0]
	v_pk_fma_f32 v[150:151], v[70:71], v[214:215], v[150:151] op_sel:[0,1,0]
	v_pk_fma_f32 v[148:149], v[70:71], v[206:207], v[70:71] op_sel:[0,1,0] neg_lo:[1,0,0] neg_hi:[1,0,0]
	ds_read_b128 v[168:171], v152 offset:25088
	v_pk_fma_f32 v[142:143], v[244:245], v[208:209], v[142:143] op_sel_hi:[1,0,1]
	v_pk_fma_f32 v[144:145], v[244:245], v[208:209], v[144:145] op_sel:[0,1,0]
	v_add_f32_dpp v150, v150, v150 quad_perm:[1,0,3,2] row_mask:0xf bank_mask:0xf bound_ctrl:1
	v_add_f32_dpp v151, v151, v151 quad_perm:[1,0,3,2] row_mask:0xf bank_mask:0xf bound_ctrl:1
	v_pk_fma_f32 v[146:147], v[244:245], v[210:211], v[146:147] op_sel_hi:[1,0,1]
	v_add_f32_dpp v150, v150, v150 quad_perm:[2,3,0,1] row_mask:0xf bank_mask:0xf bound_ctrl:1
	v_add_f32_dpp v151, v151, v151 quad_perm:[2,3,0,1] row_mask:0xf bank_mask:0xf bound_ctrl:1
	v_pk_fma_f32 v[148:149], v[244:245], v[210:211], v[148:149] op_sel:[0,1,0]
	v_add_f32_dpp v150, v150, v150 row_half_mirror row_mask:0xf bank_mask:0xf bound_ctrl:1
	v_add_f32_dpp v151, v151, v151 row_half_mirror row_mask:0xf bank_mask:0xf bound_ctrl:1
	ds_read_b128 v[192:195], v152 offset:26880
	v_add_f32_dpp v150, v150, v150 row_mirror row_mask:0xf bank_mask:0xf bound_ctrl:1
	v_add_f32_dpp v151, v151, v151 row_mirror row_mask:0xf bank_mask:0xf bound_ctrl:1
	ds_read_b128 v[184:187], v152 offset:26368
	ds_read_b128 v[176:179], v152 offset:25600
	ds_read_b128 v[188:191], v152 offset:26624
	ds_read_b128 v[196:199], v152 offset:27136
	ds_read_b128 v[160:163], v152 offset:24576
	ds_read_b128 v[180:183], v152 offset:26112
	v_pk_fma_f32 v[66:67], v[150:151], v[216:217], v[142:143] op_sel_hi:[1,0,1]
	v_pk_fma_f32 v[20:21], v[150:151], v[216:217], v[144:145] op_sel:[0,1,0]
	v_pk_fma_f32 v[68:69], v[150:151], v[218:219], v[146:147] op_sel_hi:[1,0,1]
	v_pk_fma_f32 v[70:71], v[150:151], v[218:219], v[148:149] op_sel:[0,1,0]
	v_pk_mul_f32 v[106:107], v[66:67], v[200:201] op_sel_hi:[1,0]
	v_pk_mul_f32 v[150:151], v[66:67], v[232:233] op_sel_hi:[1,0]
	v_pk_fma_f32 v[142:143], v[66:67], v[224:225], v[66:67] op_sel_hi:[1,0,1] neg_lo:[1,0,0] neg_hi:[1,0,0]
	v_pk_fma_f32 v[106:107], v[20:21], v[200:201], v[106:107] op_sel:[0,1,0]
	v_pk_fma_f32 v[150:151], v[20:21], v[232:233], v[150:151] op_sel:[0,1,0]
	v_pk_fma_f32 v[144:145], v[20:21], v[224:225], v[20:21] op_sel:[0,1,0] neg_lo:[1,0,0] neg_hi:[1,0,0]
	v_pk_fma_f32 v[106:107], v[68:69], v[202:203], v[106:107] op_sel_hi:[1,0,1]
	v_pk_fma_f32 v[150:151], v[68:69], v[234:235], v[150:151] op_sel_hi:[1,0,1]
	v_pk_fma_f32 v[146:147], v[68:69], v[226:227], v[68:69] op_sel_hi:[1,0,1] neg_lo:[1,0,0] neg_hi:[1,0,0]
	v_pk_fma_f32 v[106:107], v[70:71], v[202:203], v[106:107] op_sel:[0,1,0]
	v_pk_fma_f32 v[150:151], v[70:71], v[234:235], v[150:151] op_sel:[0,1,0]
	v_pk_fma_f32 v[148:149], v[70:71], v[226:227], v[70:71] op_sel:[0,1,0] neg_lo:[1,0,0] neg_hi:[1,0,0]
	v_pk_fma_f32 v[142:143], v[246:247], v[228:229], v[142:143] op_sel_hi:[1,0,1]
	v_pk_fma_f32 v[144:145], v[246:247], v[228:229], v[144:145] op_sel:[0,1,0]
	v_add_f32_dpp v150, v150, v150 quad_perm:[1,0,3,2] row_mask:0xf bank_mask:0xf bound_ctrl:1
	v_add_f32_dpp v151, v151, v151 quad_perm:[1,0,3,2] row_mask:0xf bank_mask:0xf bound_ctrl:1
	v_pk_fma_f32 v[146:147], v[246:247], v[230:231], v[146:147] op_sel_hi:[1,0,1]
	v_add_f32_dpp v150, v150, v150 quad_perm:[2,3,0,1] row_mask:0xf bank_mask:0xf bound_ctrl:1
	v_add_f32_dpp v151, v151, v151 quad_perm:[2,3,0,1] row_mask:0xf bank_mask:0xf bound_ctrl:1
	v_pk_fma_f32 v[148:149], v[246:247], v[230:231], v[148:149] op_sel:[0,1,0]
	v_add_f32_dpp v150, v150, v150 row_half_mirror row_mask:0xf bank_mask:0xf bound_ctrl:1
	v_add_f32_dpp v151, v151, v151 row_half_mirror row_mask:0xf bank_mask:0xf bound_ctrl:1
	s_nop 0
	v_add_f32_dpp v150, v150, v150 row_mirror row_mask:0xf bank_mask:0xf bound_ctrl:1
	v_add_f32_dpp v151, v151, v151 row_mirror row_mask:0xf bank_mask:0xf bound_ctrl:1
	s_waitcnt lgkmcnt(0)
; #define LAS __attribute__((address_space(3)))
; #define ROW16_SUM4(x, y, z, w) do { DPP4(x, y, z, w, "quad_perm:[1,0,3,2]", "s_nop 1"); DPP4(x, y, z, w, "quad_perm:[2,3,0,1]", ""); DPP4(x, y, z, w, "row_half_mirror", ""); DPP4(x, y, z, w, "row_mirror", ""); } while (0)
; template <bool SAMPLE>
; __device__ __forceinline__ void rwkv_unit(PR P, LAS float* lds, const int b, const int h, const int half, const int wv) {
;     ...
;             for (int g = 0; g < TC / GS; ++g) {
;                 float yk0 = 0.f, yk1 = 0.f;
;                 const LAS float* q0 = cur + (g * GS) * 384;
;                 f32x4 r4 = *(const LAS f32x4*)(q0 + j0), o4 = *(const LAS f32x4*)(q0 + 64 + j0), k4 = *(const LAS f32x4*)(q0 + 128 + j0), a4 = *(const LAS f32x4*)(q0 + 192 + j0), b4 = *(const LAS f32x4*)(q0 + 256 + j0);
;                 f32x2 v2 = *(const LAS f32x2*)(q0 + 320 + row0);
;                 float py0 = 0.f, py1 = 0.f;
; #pragma unroll
;                 for (int tt = 0; tt < GS; ++tt) {
;                     const LAS float* qn = q0 + (tt + 1 < GS ? tt + 1 : tt) * 384;
;                     const f32x4 nr4 = *(const LAS f32x4*)(qn + j0), no4 = *(const LAS f32x4*)(qn + 64 + j0), nk4 = *(const LAS f32x4*)(qn + 128 + j0), na4 = *(const LAS f32x4*)(qn + 192 + j0), nb4 = *(const LAS f32x4*)(qn + 256 + j0);
;                     const f32x2 nv2 = *(const LAS f32x2*)(qn + 320 + row0);
;                     f32x2 sa = (S[0] * a4[0] + S[1] * a4[1]) + (S[2] * a4[2] + S[3] * a4[3]);
;                     float sx = sa.x, sy = sa.y; ROW16_SUM4(sx, sy, py0, py1); sa = (f32x2){sx, sy};
;                     if (tt > 0) { yk0 = cgl == tt - 1 ? py0 : yk0; yk1 = cgl == tt - 1 ? py1 : yk1; }
; #pragma unroll
;                     for (int c = 0; c < 4; ++c) { f32x2 t = S[c] - S[c] * o4[c]; t = t + sa * b4[c]; S[c] = t + v2 * k4[c]; }
;                     const f32x2 y = (S[0] * r4[0] + S[1] * r4[1]) + (S[2] * r4[2] + S[3] * r4[3]);
;                     py0 = y.x; py1 = y.y;
;                     r4 = nr4; o4 = no4; k4 = nk4; a4 = na4; b4 = nb4; v2 = nv2;
;                 }
	v_pk_fma_f32 v[66:67], v[150:151], v[236:237], v[142:143] op_sel_hi:[1,0,1]
	v_pk_fma_f32 v[20:21], v[150:151], v[236:237], v[144:145] op_sel:[0,1,0]
	v_pk_fma_f32 v[68:69], v[150:151], v[238:239], v[146:147] op_sel_hi:[1,0,1]
	v_pk_fma_f32 v[70:71], v[150:151], v[238:239], v[148:149] op_sel:[0,1,0]
	v_pk_mul_f32 v[108:109], v[66:67], v[220:221] op_sel_hi:[1,0]
	v_pk_mul_f32 v[150:151], v[66:67], v[172:173] op_sel_hi:[1,0]
	v_pk_fma_f32 v[142:143], v[66:67], v[164:165], v[66:67] op_sel_hi:[1,0,1] neg_lo:[1,0,0] neg_hi:[1,0,0]
	ds_read_b128 v[212:215], v152 offset:28416
	v_pk_fma_f32 v[108:109], v[20:21], v[220:221], v[108:109] op_sel:[0,1,0]
	v_pk_fma_f32 v[150:151], v[20:21], v[172:173], v[150:151] op_sel:[0,1,0]
	v_pk_fma_f32 v[144:145], v[20:21], v[164:165], v[20:21] op_sel:[0,1,0] neg_lo:[1,0,0] neg_hi:[1,0,0]
	ds_read_b128 v[204:207], v152 offset:27904
	v_pk_fma_f32 v[108:109], v[68:69], v[222:223], v[108:109] op_sel_hi:[1,0,1]
	v_pk_fma_f32 v[150:151], v[68:69], v[174:175], v[150:151] op_sel_hi:[1,0,1]
	v_pk_fma_f32 v[146:147], v[68:69], v[166:167], v[68:69] op_sel_hi:[1,0,1] neg_lo:[1,0,0] neg_hi:[1,0,0]
	ds_read2st64_b64 v[240:243], v153 offset0:56 offset1:59
	v_pk_fma_f32 v[108:109], v[70:71], v[222:223], v[108:109] op_sel:[0,1,0]
	v_pk_fma_f32 v[150:151], v[70:71], v[174:175], v[150:151] op_sel:[0,1,0]
	v_pk_fma_f32 v[148:149], v[70:71], v[166:167], v[70:71] op_sel:[0,1,0] neg_lo:[1,0,0] neg_hi:[1,0,0]
	ds_read_b128 v[208:211], v152 offset:28160
	v_pk_fma_f32 v[142:143], v[248:249], v[168:169], v[142:143] op_sel_hi:[1,0,1]
	v_pk_fma_f32 v[144:145], v[248:249], v[168:169], v[144:145] op_sel:[0,1,0]
	v_add_f32_dpp v150, v150, v150 quad_perm:[1,0,3,2] row_mask:0xf bank_mask:0xf bound_ctrl:1
	v_add_f32_dpp v151, v151, v151 quad_perm:[1,0,3,2] row_mask:0xf bank_mask:0xf bound_ctrl:1
	v_pk_fma_f32 v[146:147], v[248:249], v[170:171], v[146:147] op_sel_hi:[1,0,1]
	v_add_f32_dpp v150, v150, v150 quad_perm:[2,3,0,1] row_mask:0xf bank_mask:0xf bound_ctrl:1
	v_add_f32_dpp v151, v151, v151 quad_perm:[2,3,0,1] row_mask:0xf bank_mask:0xf bound_ctrl:1
	v_pk_fma_f32 v[148:149], v[248:249], v[170:171], v[148:149] op_sel:[0,1,0]
	v_add_f32_dpp v150, v150, v150 row_half_mirror row_mask:0xf bank_mask:0xf bound_ctrl:1
	v_add_f32_dpp v151, v151, v151 row_half_mirror row_mask:0xf bank_mask:0xf bound_ctrl:1
	ds_read_b128 v[232:235], v152 offset:29952
	v_add_f32_dpp v150, v150, v150 row_mirror row_mask:0xf bank_mask:0xf bound_ctrl:1
	v_add_f32_dpp v151, v151, v151 row_mirror row_mask:0xf bank_mask:0xf bound_ctrl:1
	ds_read_b128 v[224:227], v152 offset:29440
	ds_read_b128 v[216:219], v152 offset:28672
	ds_read_b128 v[228:231], v152 offset:29696
	ds_read_b128 v[236:239], v152 offset:30208
	ds_read_b128 v[200:203], v152 offset:27648
	ds_read_b128 v[220:223], v152 offset:29184
	v_pk_fma_f32 v[66:67], v[150:151], v[176:177], v[142:143] op_sel_hi:[1,0,1]
	v_pk_fma_f32 v[20:21], v[150:151], v[176:177], v[144:145] op_sel:[0,1,0]
	v_pk_fma_f32 v[68:69], v[150:151], v[178:179], v[146:147] op_sel_hi:[1,0,1]
	v_pk_fma_f32 v[70:71], v[150:151], v[178:179], v[148:149] op_sel:[0,1,0]
	v_add_f32_dpp v78, v78, v78 row_ror:8 row_mask:0xf bank_mask:0x3 bound_ctrl:1
	v_add_f32_dpp v78, v94, v94 row_ror:8 row_mask:0xf bank_mask:0xc bound_ctrl:1
	v_add_f32_dpp v80, v80, v80 row_ror:8 row_mask:0xf bank_mask:0x3 bound_ctrl:1
	v_add_f32_dpp v80, v96, v96 row_ror:8 row_mask:0xf bank_mask:0xc bound_ctrl:1
	v_add_f32_dpp v82, v82, v82 row_ror:8 row_mask:0xf bank_mask:0x3 bound_ctrl:1
	v_add_f32_dpp v82, v98, v98 row_ror:8 row_mask:0xf bank_mask:0xc bound_ctrl:1
	v_add_f32_dpp v84, v84, v84 row_ror:8 row_mask:0xf bank_mask:0x3 bound_ctrl:1
	v_add_f32_dpp v84, v100, v100 row_ror:8 row_mask:0xf bank_mask:0xc bound_ctrl:1
	v_add_f32_dpp v86, v86, v86 row_ror:8 row_mask:0xf bank_mask:0x3 bound_ctrl:1
	v_add_f32_dpp v86, v102, v102 row_ror:8 row_mask:0xf bank_mask:0xc bound_ctrl:1
	v_add_f32_dpp v88, v88, v88 row_ror:8 row_mask:0xf bank_mask:0x3 bound_ctrl:1
	v_add_f32_dpp v88, v104, v104 row_ror:8 row_mask:0xf bank_mask:0xc bound_ctrl:1
	v_add_f32_dpp v90, v90, v90 row_ror:8 row_mask:0xf bank_mask:0x3 bound_ctrl:1
	v_add_f32_dpp v90, v106, v106 row_ror:8 row_mask:0xf bank_mask:0xc bound_ctrl:1
	v_add_f32_dpp v92, v92, v92 row_ror:8 row_mask:0xf bank_mask:0x3 bound_ctrl:1
	v_add_f32_dpp v92, v108, v108 row_ror:8 row_mask:0xf bank_mask:0xc bound_ctrl:1
	v_add_f32_dpp v79, v79, v79 row_ror:8 row_mask:0xf bank_mask:0x3 bound_ctrl:1
	v_add_f32_dpp v79, v95, v95 row_ror:8 row_mask:0xf bank_mask:0xc bound_ctrl:1
	v_add_f32_dpp v81, v81, v81 row_ror:8 row_mask:0xf bank_mask:0x3 bound_ctrl:1
	v_add_f32_dpp v81, v97, v97 row_ror:8 row_mask:0xf bank_mask:0xc bound_ctrl:1
	v_add_f32_dpp v83, v83, v83 row_ror:8 row_mask:0xf bank_mask:0x3 bound_ctrl:1
	v_add_f32_dpp v83, v99, v99 row_ror:8 row_mask:0xf bank_mask:0xc bound_ctrl:1
	v_add_f32_dpp v85, v85, v85 row_ror:8 row_mask:0xf bank_mask:0x3 bound_ctrl:1
	v_add_f32_dpp v85, v101, v101 row_ror:8 row_mask:0xf bank_mask:0xc bound_ctrl:1
	v_add_f32_dpp v87, v87, v87 row_ror:8 row_mask:0xf bank_mask:0x3 bound_ctrl:1
	v_add_f32_dpp v87, v103, v103 row_ror:8 row_mask:0xf bank_mask:0xc bound_ctrl:1
	v_add_f32_dpp v89, v89, v89 row_ror:8 row_mask:0xf bank_mask:0x3 bound_ctrl:1
	v_add_f32_dpp v89, v105, v105 row_ror:8 row_mask:0xf bank_mask:0xc bound_ctrl:1
	v_add_f32_dpp v91, v91, v91 row_ror:8 row_mask:0xf bank_mask:0x3 bound_ctrl:1
	v_add_f32_dpp v91, v107, v107 row_ror:8 row_mask:0xf bank_mask:0xc bound_ctrl:1
	v_add_f32_dpp v93, v93, v93 row_ror:8 row_mask:0xf bank_mask:0x3 bound_ctrl:1
	v_add_f32_dpp v93, v109, v109 row_ror:8 row_mask:0xf bank_mask:0xc bound_ctrl:1
; __device__ __forceinline__ unsigned cvt_pk_bf16(float lo, float hi) { const f32x2_t v = {lo, hi}; const bf16x2_t b = __builtin_convertvector(v, bf16x2_t); return __builtin_bit_cast(unsigned, b); }
; #define LAS __attribute__((address_space(3)))
; #define ROW16_SUM4(x, y, z, w) do { DPP4(x, y, z, w, "quad_perm:[1,0,3,2]", "s_nop 1"); DPP4(x, y, z, w, "quad_perm:[2,3,0,1]", ""); DPP4(x, y, z, w, "row_half_mirror", ""); DPP4(x, y, z, w, "row_mirror", ""); } while (0)
; #define ROW16_SUM2(x, y) do { DPP2(x, y, "quad_perm:[1,0,3,2]", "s_nop 1"); DPP2(x, y, "quad_perm:[2,3,0,1]", "s_nop 0"); DPP2(x, y, "row_half_mirror", "s_nop 0"); DPP2(x, y, "row_mirror", "s_nop 0"); } while (0)
; template <bool SAMPLE>
; __device__ __forceinline__ void rwkv_unit(PR P, LAS float* lds, const int b, const int h, const int half, const int wv) {
;     ...
;                 for (int tt = 0; tt < GS; ++tt) {
;                     const LAS float* qn = q0 + (tt + 1 < GS ? tt + 1 : tt) * 384;
;                     const f32x4 nr4 = *(const LAS f32x4*)(qn + j0), no4 = *(const LAS f32x4*)(qn + 64 + j0), nk4 = *(const LAS f32x4*)(qn + 128 + j0), na4 = *(const LAS f32x4*)(qn + 192 + j0), nb4 = *(const LAS f32x4*)(qn + 256 + j0);
;                     const f32x2 nv2 = *(const LAS f32x2*)(qn + 320 + row0);
;                     f32x2 sa = (S[0] * a4[0] + S[1] * a4[1]) + (S[2] * a4[2] + S[3] * a4[3]);
;                     float sx = sa.x, sy = sa.y; ROW16_SUM4(sx, sy, py0, py1); sa = (f32x2){sx, sy};
;                     if (tt > 0) { yk0 = cgl == tt - 1 ? py0 : yk0; yk1 = cgl == tt - 1 ? py1 : yk1; }
; #pragma unroll
;                     for (int c = 0; c < 4; ++c) { f32x2 t = S[c] - S[c] * o4[c]; t = t + sa * b4[c]; S[c] = t + v2 * k4[c]; }
;                     const f32x2 y = (S[0] * r4[0] + S[1] * r4[1]) + (S[2] * r4[2] + S[3] * r4[3]);
;                     py0 = y.x; py1 = y.y;
;                     r4 = nr4; o4 = no4; k4 = nk4; a4 = na4; b4 = nb4; v2 = nv2;
;                 }
;                 ROW16_SUM2(py0, py1); yk0 = cgl == GS - 1 ? py0 : yk0; yk1 = cgl == GS - 1 ? py1 : yk1;
;                 if (cgl < GS) *(unsigned*)(YS + (size_t)(row_base + c * TC + g * GS + cgl) * 512 + h * 64 + row0) = pg8::cvt_pk_bf16(yk0, yk1);
	v_add_f32_dpp v78, v78, v78 row_shl:4 row_mask:0xf bank_mask:0x5 bound_ctrl:1
	v_add_f32_dpp v78, v86, v86 row_shr:4 row_mask:0xf bank_mask:0xa bound_ctrl:1
	v_add_f32_dpp v80, v80, v80 row_shl:4 row_mask:0xf bank_mask:0x5 bound_ctrl:1
	v_add_f32_dpp v80, v88, v88 row_shr:4 row_mask:0xf bank_mask:0xa bound_ctrl:1
	v_add_f32_dpp v82, v82, v82 row_shl:4 row_mask:0xf bank_mask:0x5 bound_ctrl:1
	v_add_f32_dpp v82, v90, v90 row_shr:4 row_mask:0xf bank_mask:0xa bound_ctrl:1
	v_add_f32_dpp v84, v84, v84 row_shl:4 row_mask:0xf bank_mask:0x5 bound_ctrl:1
	v_add_f32_dpp v84, v92, v92 row_shr:4 row_mask:0xf bank_mask:0xa bound_ctrl:1
	v_add_f32_dpp v79, v79, v79 row_shl:4 row_mask:0xf bank_mask:0x5 bound_ctrl:1
	v_add_f32_dpp v79, v87, v87 row_shr:4 row_mask:0xf bank_mask:0xa bound_ctrl:1
	v_add_f32_dpp v81, v81, v81 row_shl:4 row_mask:0xf bank_mask:0x5 bound_ctrl:1
	v_add_f32_dpp v81, v89, v89 row_shr:4 row_mask:0xf bank_mask:0xa bound_ctrl:1
	v_add_f32_dpp v83, v83, v83 row_shl:4 row_mask:0xf bank_mask:0x5 bound_ctrl:1
	v_add_f32_dpp v83, v91, v91 row_shr:4 row_mask:0xf bank_mask:0xa bound_ctrl:1
	v_add_f32_dpp v85, v85, v85 row_shl:4 row_mask:0xf bank_mask:0x5 bound_ctrl:1
	v_add_f32_dpp v85, v93, v93 row_shr:4 row_mask:0xf bank_mask:0xa bound_ctrl:1
	v_add_f32_dpp v78, v78, v78 quad_perm:[1,0,3,2] row_mask:0xf bank_mask:0xf bound_ctrl:1
	v_add_f32_dpp v80, v80, v80 quad_perm:[1,0,3,2] row_mask:0xf bank_mask:0xf bound_ctrl:1
	v_add_f32_dpp v82, v82, v82 quad_perm:[1,0,3,2] row_mask:0xf bank_mask:0xf bound_ctrl:1
	v_add_f32_dpp v84, v84, v84 quad_perm:[1,0,3,2] row_mask:0xf bank_mask:0xf bound_ctrl:1
	v_add_f32_dpp v79, v79, v79 quad_perm:[1,0,3,2] row_mask:0xf bank_mask:0xf bound_ctrl:1
	v_add_f32_dpp v81, v81, v81 quad_perm:[1,0,3,2] row_mask:0xf bank_mask:0xf bound_ctrl:1
	v_add_f32_dpp v83, v83, v83 quad_perm:[1,0,3,2] row_mask:0xf bank_mask:0xf bound_ctrl:1
	v_add_f32_dpp v85, v85, v85 quad_perm:[1,0,3,2] row_mask:0xf bank_mask:0xf bound_ctrl:1
	v_add_f32_dpp v78, v78, v78 quad_perm:[2,3,0,1] row_mask:0xf bank_mask:0xf bound_ctrl:1
	v_add_f32_dpp v80, v80, v80 quad_perm:[2,3,0,1] row_mask:0xf bank_mask:0xf bound_ctrl:1
	v_add_f32_dpp v82, v82, v82 quad_perm:[2,3,0,1] row_mask:0xf bank_mask:0xf bound_ctrl:1
	v_add_f32_dpp v84, v84, v84 quad_perm:[2,3,0,1] row_mask:0xf bank_mask:0xf bound_ctrl:1
	v_add_f32_dpp v79, v79, v79 quad_perm:[2,3,0,1] row_mask:0xf bank_mask:0xf bound_ctrl:1
	v_add_f32_dpp v81, v81, v81 quad_perm:[2,3,0,1] row_mask:0xf bank_mask:0xf bound_ctrl:1
	v_add_f32_dpp v83, v83, v83 quad_perm:[2,3,0,1] row_mask:0xf bank_mask:0xf bound_ctrl:1
	v_add_f32_dpp v85, v85, v85 quad_perm:[2,3,0,1] row_mask:0xf bank_mask:0xf bound_ctrl:1
	v_add_u32_e32 v72, 0, v57
	v_ashrrev_i32_e32 v73, 31, v72
	v_lshlrev_b64 v[72:73], 10, v[72:73]
	v_lshl_add_u64 v[72:73], v[64:65], 0, v[72:73]
	v_cndmask_b32_e64 v154, v84, v82, s[16:17]
	v_cndmask_b32_e64 v155, v85, v83, s[16:17]
	v_cndmask_b32_e64 v154, v154, v80, s[14:15]
	v_cndmask_b32_e64 v155, v155, v81, s[14:15]
	v_cndmask_b32_e64 v154, v154, v78, s[12:13]
	v_cndmask_b32_e64 v155, v155, v79, s[12:13]
	v_cvt_pk_bf16_f32 v154, v154, v155
	global_store_dword v[72:73], v154, off
	v_pk_mul_f32 v[110:111], v[66:67], v[160:161] op_sel_hi:[1,0]
	v_pk_mul_f32 v[150:151], v[66:67], v[192:193] op_sel_hi:[1,0]
	v_pk_fma_f32 v[142:143], v[66:67], v[184:185], v[66:67] op_sel_hi:[1,0,1] neg_lo:[1,0,0] neg_hi:[1,0,0]
	v_pk_fma_f32 v[110:111], v[20:21], v[160:161], v[110:111] op_sel:[0,1,0]
	v_pk_fma_f32 v[150:151], v[20:21], v[192:193], v[150:151] op_sel:[0,1,0]
	v_pk_fma_f32 v[144:145], v[20:21], v[184:185], v[20:21] op_sel:[0,1,0] neg_lo:[1,0,0] neg_hi:[1,0,0]
	v_pk_fma_f32 v[110:111], v[68:69], v[162:163], v[110:111] op_sel_hi:[1,0,1]
	v_pk_fma_f32 v[150:151], v[68:69], v[194:195], v[150:151] op_sel_hi:[1,0,1]
	v_pk_fma_f32 v[146:147], v[68:69], v[186:187], v[68:69] op_sel_hi:[1,0,1] neg_lo:[1,0,0] neg_hi:[1,0,0]
	v_pk_fma_f32 v[110:111], v[70:71], v[162:163], v[110:111] op_sel:[0,1,0]
	v_pk_fma_f32 v[150:151], v[70:71], v[194:195], v[150:151] op_sel:[0,1,0]
	v_pk_fma_f32 v[148:149], v[70:71], v[186:187], v[70:71] op_sel:[0,1,0] neg_lo:[1,0,0] neg_hi:[1,0,0]
	v_pk_fma_f32 v[142:143], v[250:251], v[188:189], v[142:143] op_sel_hi:[1,0,1]
	v_pk_fma_f32 v[144:145], v[250:251], v[188:189], v[144:145] op_sel:[0,1,0]
	v_add_f32_dpp v150, v150, v150 quad_perm:[1,0,3,2] row_mask:0xf bank_mask:0xf bound_ctrl:1
	v_add_f32_dpp v151, v151, v151 quad_perm:[1,0,3,2] row_mask:0xf bank_mask:0xf bound_ctrl:1
	v_pk_fma_f32 v[146:147], v[250:251], v[190:191], v[146:147] op_sel_hi:[1,0,1]
	v_add_f32_dpp v150, v150, v150 quad_perm:[2,3,0,1] row_mask:0xf bank_mask:0xf bound_ctrl:1
	v_add_f32_dpp v151, v151, v151 quad_perm:[2,3,0,1] row_mask:0xf bank_mask:0xf bound_ctrl:1
	v_pk_fma_f32 v[148:149], v[250:251], v[190:191], v[148:149] op_sel:[0,1,0]
	v_add_f32_dpp v150, v150, v150 row_half_mirror row_mask:0xf bank_mask:0xf bound_ctrl:1
	v_add_f32_dpp v151, v151, v151 row_half_mirror row_mask:0xf bank_mask:0xf bound_ctrl:1
	s_nop 0
	v_add_f32_dpp v150, v150, v150 row_mirror row_mask:0xf bank_mask:0xf bound_ctrl:1
	v_add_f32_dpp v151, v151, v151 row_mirror row_mask:0xf bank_mask:0xf bound_ctrl:1
	s_waitcnt lgkmcnt(0)
; #define LAS __attribute__((address_space(3)))
; #define ROW16_SUM4(x, y, z, w) do { DPP4(x, y, z, w, "quad_perm:[1,0,3,2]", "s_nop 1"); DPP4(x, y, z, w, "quad_perm:[2,3,0,1]", ""); DPP4(x, y, z, w, "row_half_mirror", ""); DPP4(x, y, z, w, "row_mirror", ""); } while (0)
; template <bool SAMPLE>
; __device__ __forceinline__ void rwkv_unit(PR P, LAS float* lds, const int b, const int h, const int half, const int wv) {
;     ...
;             for (int g = 0; g < TC / GS; ++g) {
;                 float yk0 = 0.f, yk1 = 0.f;
;                 const LAS float* q0 = cur + (g * GS) * 384;
;                 f32x4 r4 = *(const LAS f32x4*)(q0 + j0), o4 = *(const LAS f32x4*)(q0 + 64 + j0), k4 = *(const LAS f32x4*)(q0 + 128 + j0), a4 = *(const LAS f32x4*)(q0 + 192 + j0), b4 = *(const LAS f32x4*)(q0 + 256 + j0);
;                 f32x2 v2 = *(const LAS f32x2*)(q0 + 320 + row0);
;                 float py0 = 0.f, py1 = 0.f;
; #pragma unroll
;                 for (int tt = 0; tt < GS; ++tt) {
;                     const LAS float* qn = q0 + (tt + 1 < GS ? tt + 1 : tt) * 384;
;                     const f32x4 nr4 = *(const LAS f32x4*)(qn + j0), no4 = *(const LAS f32x4*)(qn + 64 + j0), nk4 = *(const LAS f32x4*)(qn + 128 + j0), na4 = *(const LAS f32x4*)(qn + 192 + j0), nb4 = *(const LAS f32x4*)(qn + 256 + j0);
;                     const f32x2 nv2 = *(const LAS f32x2*)(qn + 320 + row0);
;                     f32x2 sa = (S[0] * a4[0] + S[1] * a4[1]) + (S[2] * a4[2] + S[3] * a4[3]);
;                     float sx = sa.x, sy = sa.y; ROW16_SUM4(sx, sy, py0, py1); sa = (f32x2){sx, sy};
;                     if (tt > 0) { yk0 = cgl == tt - 1 ? py0 : yk0; yk1 = cgl == tt - 1 ? py1 : yk1; }
; #pragma unroll
;                     for (int c = 0; c < 4; ++c) { f32x2 t = S[c] - S[c] * o4[c]; t = t + sa * b4[c]; S[c] = t + v2 * k4[c]; }
;                     const f32x2 y = (S[0] * r4[0] + S[1] * r4[1]) + (S[2] * r4[2] + S[3] * r4[3]);
;                     py0 = y.x; py1 = y.y;
;                     r4 = nr4; o4 = no4; k4 = nk4; a4 = na4; b4 = nb4; v2 = nv2;
;                 }
	v_pk_fma_f32 v[66:67], v[150:151], v[196:197], v[142:143] op_sel_hi:[1,0,1]
	v_pk_fma_f32 v[20:21], v[150:151], v[196:197], v[144:145] op_sel:[0,1,0]
	v_pk_fma_f32 v[68:69], v[150:151], v[198:199], v[146:147] op_sel_hi:[1,0,1]
	v_pk_fma_f32 v[70:71], v[150:151], v[198:199], v[148:149] op_sel:[0,1,0]
	v_pk_mul_f32 v[112:113], v[66:67], v[180:181] op_sel_hi:[1,0]
	v_pk_mul_f32 v[150:151], v[66:67], v[212:213] op_sel_hi:[1,0]
	v_pk_fma_f32 v[142:143], v[66:67], v[204:205], v[66:67] op_sel_hi:[1,0,1] neg_lo:[1,0,0] neg_hi:[1,0,0]
	ds_read_b128 v[172:175], v152 offset:31488
	v_pk_fma_f32 v[112:113], v[20:21], v[180:181], v[112:113] op_sel:[0,1,0]
	v_pk_fma_f32 v[150:151], v[20:21], v[212:213], v[150:151] op_sel:[0,1,0]
	v_pk_fma_f32 v[144:145], v[20:21], v[204:205], v[20:21] op_sel:[0,1,0] neg_lo:[1,0,0] neg_hi:[1,0,0]
	ds_read_b128 v[164:167], v152 offset:30976
	v_pk_fma_f32 v[112:113], v[68:69], v[182:183], v[112:113] op_sel_hi:[1,0,1]
	v_pk_fma_f32 v[150:151], v[68:69], v[214:215], v[150:151] op_sel_hi:[1,0,1]
	v_pk_fma_f32 v[146:147], v[68:69], v[206:207], v[68:69] op_sel_hi:[1,0,1] neg_lo:[1,0,0] neg_hi:[1,0,0]
	ds_read2st64_b64 v[244:247], v153 offset0:62 offset1:65
	v_pk_fma_f32 v[112:113], v[70:71], v[182:183], v[112:113] op_sel:[0,1,0]
	v_pk_fma_f32 v[150:151], v[70:71], v[214:215], v[150:151] op_sel:[0,1,0]
	v_pk_fma_f32 v[148:149], v[70:71], v[206:207], v[70:71] op_sel:[0,1,0] neg_lo:[1,0,0] neg_hi:[1,0,0]
	ds_read_b128 v[168:171], v152 offset:31232
	v_pk_fma_f32 v[142:143], v[240:241], v[208:209], v[142:143] op_sel_hi:[1,0,1]
	v_pk_fma_f32 v[144:145], v[240:241], v[208:209], v[144:145] op_sel:[0,1,0]
	v_add_f32_dpp v150, v150, v150 quad_perm:[1,0,3,2] row_mask:0xf bank_mask:0xf bound_ctrl:1
	v_add_f32_dpp v151, v151, v151 quad_perm:[1,0,3,2] row_mask:0xf bank_mask:0xf bound_ctrl:1
	v_pk_fma_f32 v[146:147], v[240:241], v[210:211], v[146:147] op_sel_hi:[1,0,1]
	v_add_f32_dpp v150, v150, v150 quad_perm:[2,3,0,1] row_mask:0xf bank_mask:0xf bound_ctrl:1
	v_add_f32_dpp v151, v151, v151 quad_perm:[2,3,0,1] row_mask:0xf bank_mask:0xf bound_ctrl:1
	v_pk_fma_f32 v[148:149], v[240:241], v[210:211], v[148:149] op_sel:[0,1,0]
	v_add_f32_dpp v150, v150, v150 row_half_mirror row_mask:0xf bank_mask:0xf bound_ctrl:1
	v_add_f32_dpp v151, v151, v151 row_half_mirror row_mask:0xf bank_mask:0xf bound_ctrl:1
	ds_read_b128 v[192:195], v152 offset:33024
	v_add_f32_dpp v150, v150, v150 row_mirror row_mask:0xf bank_mask:0xf bound_ctrl:1
	v_add_f32_dpp v151, v151, v151 row_mirror row_mask:0xf bank_mask:0xf bound_ctrl:1
	ds_read_b128 v[184:187], v152 offset:32512
	ds_read_b128 v[176:179], v152 offset:31744
	ds_read_b128 v[188:191], v152 offset:32768
	ds_read_b128 v[196:199], v152 offset:33280
	ds_read_b128 v[160:163], v152 offset:30720
	ds_read_b128 v[180:183], v152 offset:32256
	v_pk_fma_f32 v[66:67], v[150:151], v[216:217], v[142:143] op_sel_hi:[1,0,1]
	v_pk_fma_f32 v[20:21], v[150:151], v[216:217], v[144:145] op_sel:[0,1,0]
	v_pk_fma_f32 v[68:69], v[150:151], v[218:219], v[146:147] op_sel_hi:[1,0,1]
	v_pk_fma_f32 v[70:71], v[150:151], v[218:219], v[148:149] op_sel:[0,1,0]
	v_pk_mul_f32 v[114:115], v[66:67], v[200:201] op_sel_hi:[1,0]
	v_pk_mul_f32 v[150:151], v[66:67], v[232:233] op_sel_hi:[1,0]
	v_pk_fma_f32 v[142:143], v[66:67], v[224:225], v[66:67] op_sel_hi:[1,0,1] neg_lo:[1,0,0] neg_hi:[1,0,0]
	v_pk_fma_f32 v[114:115], v[20:21], v[200:201], v[114:115] op_sel:[0,1,0]
	v_pk_fma_f32 v[150:151], v[20:21], v[232:233], v[150:151] op_sel:[0,1,0]
	v_pk_fma_f32 v[144:145], v[20:21], v[224:225], v[20:21] op_sel:[0,1,0] neg_lo:[1,0,0] neg_hi:[1,0,0]
	v_pk_fma_f32 v[114:115], v[68:69], v[202:203], v[114:115] op_sel_hi:[1,0,1]
	v_pk_fma_f32 v[150:151], v[68:69], v[234:235], v[150:151] op_sel_hi:[1,0,1]
	v_pk_fma_f32 v[146:147], v[68:69], v[226:227], v[68:69] op_sel_hi:[1,0,1] neg_lo:[1,0,0] neg_hi:[1,0,0]
	v_pk_fma_f32 v[114:115], v[70:71], v[202:203], v[114:115] op_sel:[0,1,0]
	v_pk_fma_f32 v[150:151], v[70:71], v[234:235], v[150:151] op_sel:[0,1,0]
	v_pk_fma_f32 v[148:149], v[70:71], v[226:227], v[70:71] op_sel:[0,1,0] neg_lo:[1,0,0] neg_hi:[1,0,0]
	v_pk_fma_f32 v[142:143], v[242:243], v[228:229], v[142:143] op_sel_hi:[1,0,1]
	v_pk_fma_f32 v[144:145], v[242:243], v[228:229], v[144:145] op_sel:[0,1,0]
	v_add_f32_dpp v150, v150, v150 quad_perm:[1,0,3,2] row_mask:0xf bank_mask:0xf bound_ctrl:1
	v_add_f32_dpp v151, v151, v151 quad_perm:[1,0,3,2] row_mask:0xf bank_mask:0xf bound_ctrl:1
	v_pk_fma_f32 v[146:147], v[242:243], v[230:231], v[146:147] op_sel_hi:[1,0,1]
	v_add_f32_dpp v150, v150, v150 quad_perm:[2,3,0,1] row_mask:0xf bank_mask:0xf bound_ctrl:1
	v_add_f32_dpp v151, v151, v151 quad_perm:[2,3,0,1] row_mask:0xf bank_mask:0xf bound_ctrl:1
	v_pk_fma_f32 v[148:149], v[242:243], v[230:231], v[148:149] op_sel:[0,1,0]
	v_add_f32_dpp v150, v150, v150 row_half_mirror row_mask:0xf bank_mask:0xf bound_ctrl:1
	v_add_f32_dpp v151, v151, v151 row_half_mirror row_mask:0xf bank_mask:0xf bound_ctrl:1
	s_nop 0
	v_add_f32_dpp v150, v150, v150 row_mirror row_mask:0xf bank_mask:0xf bound_ctrl:1
	v_add_f32_dpp v151, v151, v151 row_mirror row_mask:0xf bank_mask:0xf bound_ctrl:1
	s_waitcnt lgkmcnt(0)
; #define LAS __attribute__((address_space(3)))
; #define ROW16_SUM4(x, y, z, w) do { DPP4(x, y, z, w, "quad_perm:[1,0,3,2]", "s_nop 1"); DPP4(x, y, z, w, "quad_perm:[2,3,0,1]", ""); DPP4(x, y, z, w, "row_half_mirror", ""); DPP4(x, y, z, w, "row_mirror", ""); } while (0)
; template <bool SAMPLE>
; __device__ __forceinline__ void rwkv_unit(PR P, LAS float* lds, const int b, const int h, const int half, const int wv) {
;     ...
;             for (int g = 0; g < TC / GS; ++g) {
;                 float yk0 = 0.f, yk1 = 0.f;
;                 const LAS float* q0 = cur + (g * GS) * 384;
;                 f32x4 r4 = *(const LAS f32x4*)(q0 + j0), o4 = *(const LAS f32x4*)(q0 + 64 + j0), k4 = *(const LAS f32x4*)(q0 + 128 + j0), a4 = *(const LAS f32x4*)(q0 + 192 + j0), b4 = *(const LAS f32x4*)(q0 + 256 + j0);
;                 f32x2 v2 = *(const LAS f32x2*)(q0 + 320 + row0);
;                 float py0 = 0.f, py1 = 0.f;
; #pragma unroll
;                 for (int tt = 0; tt < GS; ++tt) {
;                     const LAS float* qn = q0 + (tt + 1 < GS ? tt + 1 : tt) * 384;
;                     const f32x4 nr4 = *(const LAS f32x4*)(qn + j0), no4 = *(const LAS f32x4*)(qn + 64 + j0), nk4 = *(const LAS f32x4*)(qn + 128 + j0), na4 = *(const LAS f32x4*)(qn + 192 + j0), nb4 = *(const LAS f32x4*)(qn + 256 + j0);
;                     const f32x2 nv2 = *(const LAS f32x2*)(qn + 320 + row0);
;                     f32x2 sa = (S[0] * a4[0] + S[1] * a4[1]) + (S[2] * a4[2] + S[3] * a4[3]);
;                     float sx = sa.x, sy = sa.y; ROW16_SUM4(sx, sy, py0, py1); sa = (f32x2){sx, sy};
;                     if (tt > 0) { yk0 = cgl == tt - 1 ? py0 : yk0; yk1 = cgl == tt - 1 ? py1 : yk1; }
; #pragma unroll
;                     for (int c = 0; c < 4; ++c) { f32x2 t = S[c] - S[c] * o4[c]; t = t + sa * b4[c]; S[c] = t + v2 * k4[c]; }
;                     const f32x2 y = (S[0] * r4[0] + S[1] * r4[1]) + (S[2] * r4[2] + S[3] * r4[3]);
;                     py0 = y.x; py1 = y.y;
;                     r4 = nr4; o4 = no4; k4 = nk4; a4 = na4; b4 = nb4; v2 = nv2;
;                 }
	v_pk_fma_f32 v[66:67], v[150:151], v[236:237], v[142:143] op_sel_hi:[1,0,1]
	v_pk_fma_f32 v[20:21], v[150:151], v[236:237], v[144:145] op_sel:[0,1,0]
	v_pk_fma_f32 v[68:69], v[150:151], v[238:239], v[146:147] op_sel_hi:[1,0,1]
	v_pk_fma_f32 v[70:71], v[150:151], v[238:239], v[148:149] op_sel:[0,1,0]
	v_pk_mul_f32 v[116:117], v[66:67], v[220:221] op_sel_hi:[1,0]
	v_pk_mul_f32 v[150:151], v[66:67], v[172:173] op_sel_hi:[1,0]
	v_pk_fma_f32 v[142:143], v[66:67], v[164:165], v[66:67] op_sel_hi:[1,0,1] neg_lo:[1,0,0] neg_hi:[1,0,0]
	ds_read_b128 v[212:215], v152 offset:34560
	v_pk_fma_f32 v[116:117], v[20:21], v[220:221], v[116:117] op_sel:[0,1,0]
	v_pk_fma_f32 v[150:151], v[20:21], v[172:173], v[150:151] op_sel:[0,1,0]
	v_pk_fma_f32 v[144:145], v[20:21], v[164:165], v[20:21] op_sel:[0,1,0] neg_lo:[1,0,0] neg_hi:[1,0,0]
	ds_read_b128 v[204:207], v152 offset:34048
	v_pk_fma_f32 v[116:117], v[68:69], v[222:223], v[116:117] op_sel_hi:[1,0,1]
	v_pk_fma_f32 v[150:151], v[68:69], v[174:175], v[150:151] op_sel_hi:[1,0,1]
	v_pk_fma_f32 v[146:147], v[68:69], v[166:167], v[68:69] op_sel_hi:[1,0,1] neg_lo:[1,0,0] neg_hi:[1,0,0]
	ds_read2st64_b64 v[248:251], v153 offset0:68 offset1:71
	v_pk_fma_f32 v[116:117], v[70:71], v[222:223], v[116:117] op_sel:[0,1,0]
	v_pk_fma_f32 v[150:151], v[70:71], v[174:175], v[150:151] op_sel:[0,1,0]
	v_pk_fma_f32 v[148:149], v[70:71], v[166:167], v[70:71] op_sel:[0,1,0] neg_lo:[1,0,0] neg_hi:[1,0,0]
	ds_read_b128 v[208:211], v152 offset:34304
	v_pk_fma_f32 v[142:143], v[244:245], v[168:169], v[142:143] op_sel_hi:[1,0,1]
	v_pk_fma_f32 v[144:145], v[244:245], v[168:169], v[144:145] op_sel:[0,1,0]
	v_add_f32_dpp v150, v150, v150 quad_perm:[1,0,3,2] row_mask:0xf bank_mask:0xf bound_ctrl:1
	v_add_f32_dpp v151, v151, v151 quad_perm:[1,0,3,2] row_mask:0xf bank_mask:0xf bound_ctrl:1
	v_pk_fma_f32 v[146:147], v[244:245], v[170:171], v[146:147] op_sel_hi:[1,0,1]
	v_add_f32_dpp v150, v150, v150 quad_perm:[2,3,0,1] row_mask:0xf bank_mask:0xf bound_ctrl:1
	v_add_f32_dpp v151, v151, v151 quad_perm:[2,3,0,1] row_mask:0xf bank_mask:0xf bound_ctrl:1
	v_pk_fma_f32 v[148:149], v[244:245], v[170:171], v[148:149] op_sel:[0,1,0]
	v_add_f32_dpp v150, v150, v150 row_half_mirror row_mask:0xf bank_mask:0xf bound_ctrl:1
	v_add_f32_dpp v151, v151, v151 row_half_mirror row_mask:0xf bank_mask:0xf bound_ctrl:1
	ds_read_b128 v[232:235], v152 offset:36096
	v_add_f32_dpp v150, v150, v150 row_mirror row_mask:0xf bank_mask:0xf bound_ctrl:1
	v_add_f32_dpp v151, v151, v151 row_mirror row_mask:0xf bank_mask:0xf bound_ctrl:1
	ds_read_b128 v[224:227], v152 offset:35584
	ds_read_b128 v[216:219], v152 offset:34816
	ds_read_b128 v[228:231], v152 offset:35840
	ds_read_b128 v[236:239], v152 offset:36352
	ds_read_b128 v[200:203], v152 offset:33792
	ds_read_b128 v[220:223], v152 offset:35328
	v_pk_fma_f32 v[66:67], v[150:151], v[176:177], v[142:143] op_sel_hi:[1,0,1]
	v_pk_fma_f32 v[20:21], v[150:151], v[176:177], v[144:145] op_sel:[0,1,0]
	v_pk_fma_f32 v[68:69], v[150:151], v[178:179], v[146:147] op_sel_hi:[1,0,1]
	v_pk_fma_f32 v[70:71], v[150:151], v[178:179], v[148:149] op_sel:[0,1,0]
	v_pk_mul_f32 v[118:119], v[66:67], v[160:161] op_sel_hi:[1,0]
	v_pk_mul_f32 v[150:151], v[66:67], v[192:193] op_sel_hi:[1,0]
	v_pk_fma_f32 v[142:143], v[66:67], v[184:185], v[66:67] op_sel_hi:[1,0,1] neg_lo:[1,0,0] neg_hi:[1,0,0]
	v_pk_fma_f32 v[118:119], v[20:21], v[160:161], v[118:119] op_sel:[0,1,0]
	v_pk_fma_f32 v[150:151], v[20:21], v[192:193], v[150:151] op_sel:[0,1,0]
	v_pk_fma_f32 v[144:145], v[20:21], v[184:185], v[20:21] op_sel:[0,1,0] neg_lo:[1,0,0] neg_hi:[1,0,0]
	v_pk_fma_f32 v[118:119], v[68:69], v[162:163], v[118:119] op_sel_hi:[1,0,1]
	v_pk_fma_f32 v[150:151], v[68:69], v[194:195], v[150:151] op_sel_hi:[1,0,1]
	v_pk_fma_f32 v[146:147], v[68:69], v[186:187], v[68:69] op_sel_hi:[1,0,1] neg_lo:[1,0,0] neg_hi:[1,0,0]
	v_pk_fma_f32 v[118:119], v[70:71], v[162:163], v[118:119] op_sel:[0,1,0]
	v_pk_fma_f32 v[150:151], v[70:71], v[194:195], v[150:151] op_sel:[0,1,0]
	v_pk_fma_f32 v[148:149], v[70:71], v[186:187], v[70:71] op_sel:[0,1,0] neg_lo:[1,0,0] neg_hi:[1,0,0]
	v_pk_fma_f32 v[142:143], v[246:247], v[188:189], v[142:143] op_sel_hi:[1,0,1]
	v_pk_fma_f32 v[144:145], v[246:247], v[188:189], v[144:145] op_sel:[0,1,0]
	v_add_f32_dpp v150, v150, v150 quad_perm:[1,0,3,2] row_mask:0xf bank_mask:0xf bound_ctrl:1
	v_add_f32_dpp v151, v151, v151 quad_perm:[1,0,3,2] row_mask:0xf bank_mask:0xf bound_ctrl:1
	v_pk_fma_f32 v[146:147], v[246:247], v[190:191], v[146:147] op_sel_hi:[1,0,1]
	v_add_f32_dpp v150, v150, v150 quad_perm:[2,3,0,1] row_mask:0xf bank_mask:0xf bound_ctrl:1
	v_add_f32_dpp v151, v151, v151 quad_perm:[2,3,0,1] row_mask:0xf bank_mask:0xf bound_ctrl:1
	v_pk_fma_f32 v[148:149], v[246:247], v[190:191], v[148:149] op_sel:[0,1,0]
	v_add_f32_dpp v150, v150, v150 row_half_mirror row_mask:0xf bank_mask:0xf bound_ctrl:1
	v_add_f32_dpp v151, v151, v151 row_half_mirror row_mask:0xf bank_mask:0xf bound_ctrl:1
	s_nop 0
	v_add_f32_dpp v150, v150, v150 row_mirror row_mask:0xf bank_mask:0xf bound_ctrl:1
	v_add_f32_dpp v151, v151, v151 row_mirror row_mask:0xf bank_mask:0xf bound_ctrl:1
	s_waitcnt lgkmcnt(0)
; #define LAS __attribute__((address_space(3)))
; #define ROW16_SUM4(x, y, z, w) do { DPP4(x, y, z, w, "quad_perm:[1,0,3,2]", "s_nop 1"); DPP4(x, y, z, w, "quad_perm:[2,3,0,1]", ""); DPP4(x, y, z, w, "row_half_mirror", ""); DPP4(x, y, z, w, "row_mirror", ""); } while (0)
; template <bool SAMPLE>
; __device__ __forceinline__ void rwkv_unit(PR P, LAS float* lds, const int b, const int h, const int half, const int wv) {
;     ...
;             for (int g = 0; g < TC / GS; ++g) {
;                 float yk0 = 0.f, yk1 = 0.f;
;                 const LAS float* q0 = cur + (g * GS) * 384;
;                 f32x4 r4 = *(const LAS f32x4*)(q0 + j0), o4 = *(const LAS f32x4*)(q0 + 64 + j0), k4 = *(const LAS f32x4*)(q0 + 128 + j0), a4 = *(const LAS f32x4*)(q0 + 192 + j0), b4 = *(const LAS f32x4*)(q0 + 256 + j0);
;                 f32x2 v2 = *(const LAS f32x2*)(q0 + 320 + row0);
;                 float py0 = 0.f, py1 = 0.f;
; #pragma unroll
;                 for (int tt = 0; tt < GS; ++tt) {
;                     const LAS float* qn = q0 + (tt + 1 < GS ? tt + 1 : tt) * 384;
;                     const f32x4 nr4 = *(const LAS f32x4*)(qn + j0), no4 = *(const LAS f32x4*)(qn + 64 + j0), nk4 = *(const LAS f32x4*)(qn + 128 + j0), na4 = *(const LAS f32x4*)(qn + 192 + j0), nb4 = *(const LAS f32x4*)(qn + 256 + j0);
;                     const f32x2 nv2 = *(const LAS f32x2*)(qn + 320 + row0);
;                     f32x2 sa = (S[0] * a4[0] + S[1] * a4[1]) + (S[2] * a4[2] + S[3] * a4[3]);
;                     float sx = sa.x, sy = sa.y; ROW16_SUM4(sx, sy, py0, py1); sa = (f32x2){sx, sy};
;                     if (tt > 0) { yk0 = cgl == tt - 1 ? py0 : yk0; yk1 = cgl == tt - 1 ? py1 : yk1; }
; #pragma unroll
;                     for (int c = 0; c < 4; ++c) { f32x2 t = S[c] - S[c] * o4[c]; t = t + sa * b4[c]; S[c] = t + v2 * k4[c]; }
;                     const f32x2 y = (S[0] * r4[0] + S[1] * r4[1]) + (S[2] * r4[2] + S[3] * r4[3]);
;                     py0 = y.x; py1 = y.y;
;                     r4 = nr4; o4 = no4; k4 = nk4; a4 = na4; b4 = nb4; v2 = nv2;
;                 }
	v_pk_fma_f32 v[66:67], v[150:151], v[196:197], v[142:143] op_sel_hi:[1,0,1]
	v_pk_fma_f32 v[20:21], v[150:151], v[196:197], v[144:145] op_sel:[0,1,0]
	v_pk_fma_f32 v[68:69], v[150:151], v[198:199], v[146:147] op_sel_hi:[1,0,1]
	v_pk_fma_f32 v[70:71], v[150:151], v[198:199], v[148:149] op_sel:[0,1,0]
	v_pk_mul_f32 v[120:121], v[66:67], v[180:181] op_sel_hi:[1,0]
	v_pk_mul_f32 v[150:151], v[66:67], v[212:213] op_sel_hi:[1,0]
	v_pk_fma_f32 v[142:143], v[66:67], v[204:205], v[66:67] op_sel_hi:[1,0,1] neg_lo:[1,0,0] neg_hi:[1,0,0]
	ds_read_b128 v[172:175], v152 offset:37632
	v_pk_fma_f32 v[120:121], v[20:21], v[180:181], v[120:121] op_sel:[0,1,0]
	v_pk_fma_f32 v[150:151], v[20:21], v[212:213], v[150:151] op_sel:[0,1,0]
	v_pk_fma_f32 v[144:145], v[20:21], v[204:205], v[20:21] op_sel:[0,1,0] neg_lo:[1,0,0] neg_hi:[1,0,0]
	ds_read_b128 v[164:167], v152 offset:37120
	v_pk_fma_f32 v[120:121], v[68:69], v[182:183], v[120:121] op_sel_hi:[1,0,1]
	v_pk_fma_f32 v[150:151], v[68:69], v[214:215], v[150:151] op_sel_hi:[1,0,1]
	v_pk_fma_f32 v[146:147], v[68:69], v[206:207], v[68:69] op_sel_hi:[1,0,1] neg_lo:[1,0,0] neg_hi:[1,0,0]
	ds_read2st64_b64 v[240:243], v153 offset0:74 offset1:77
	v_pk_fma_f32 v[120:121], v[70:71], v[182:183], v[120:121] op_sel:[0,1,0]
	v_pk_fma_f32 v[150:151], v[70:71], v[214:215], v[150:151] op_sel:[0,1,0]
	v_pk_fma_f32 v[148:149], v[70:71], v[206:207], v[70:71] op_sel:[0,1,0] neg_lo:[1,0,0] neg_hi:[1,0,0]
	ds_read_b128 v[168:171], v152 offset:37376
	v_pk_fma_f32 v[142:143], v[248:249], v[208:209], v[142:143] op_sel_hi:[1,0,1]
	v_pk_fma_f32 v[144:145], v[248:249], v[208:209], v[144:145] op_sel:[0,1,0]
	v_add_f32_dpp v150, v150, v150 quad_perm:[1,0,3,2] row_mask:0xf bank_mask:0xf bound_ctrl:1
	v_add_f32_dpp v151, v151, v151 quad_perm:[1,0,3,2] row_mask:0xf bank_mask:0xf bound_ctrl:1
	v_pk_fma_f32 v[146:147], v[248:249], v[210:211], v[146:147] op_sel_hi:[1,0,1]
	v_add_f32_dpp v150, v150, v150 quad_perm:[2,3,0,1] row_mask:0xf bank_mask:0xf bound_ctrl:1
	v_add_f32_dpp v151, v151, v151 quad_perm:[2,3,0,1] row_mask:0xf bank_mask:0xf bound_ctrl:1
	v_pk_fma_f32 v[148:149], v[248:249], v[210:211], v[148:149] op_sel:[0,1,0]
	v_add_f32_dpp v150, v150, v150 row_half_mirror row_mask:0xf bank_mask:0xf bound_ctrl:1
	v_add_f32_dpp v151, v151, v151 row_half_mirror row_mask:0xf bank_mask:0xf bound_ctrl:1
	ds_read_b128 v[192:195], v152 offset:39168
	v_add_f32_dpp v150, v150, v150 row_mirror row_mask:0xf bank_mask:0xf bound_ctrl:1
	v_add_f32_dpp v151, v151, v151 row_mirror row_mask:0xf bank_mask:0xf bound_ctrl:1
	ds_read_b128 v[184:187], v152 offset:38656
	ds_read_b128 v[176:179], v152 offset:37888
	ds_read_b128 v[188:191], v152 offset:38912
	ds_read_b128 v[196:199], v152 offset:39424
	ds_read_b128 v[160:163], v152 offset:36864
	ds_read_b128 v[180:183], v152 offset:38400
	v_pk_fma_f32 v[66:67], v[150:151], v[216:217], v[142:143] op_sel_hi:[1,0,1]
	v_pk_fma_f32 v[20:21], v[150:151], v[216:217], v[144:145] op_sel:[0,1,0]
	v_pk_fma_f32 v[68:69], v[150:151], v[218:219], v[146:147] op_sel_hi:[1,0,1]
	v_pk_fma_f32 v[70:71], v[150:151], v[218:219], v[148:149] op_sel:[0,1,0]
	v_pk_mul_f32 v[122:123], v[66:67], v[200:201] op_sel_hi:[1,0]
	v_pk_mul_f32 v[150:151], v[66:67], v[232:233] op_sel_hi:[1,0]
	v_pk_fma_f32 v[142:143], v[66:67], v[224:225], v[66:67] op_sel_hi:[1,0,1] neg_lo:[1,0,0] neg_hi:[1,0,0]
	v_pk_fma_f32 v[122:123], v[20:21], v[200:201], v[122:123] op_sel:[0,1,0]
	v_pk_fma_f32 v[150:151], v[20:21], v[232:233], v[150:151] op_sel:[0,1,0]
	v_pk_fma_f32 v[144:145], v[20:21], v[224:225], v[20:21] op_sel:[0,1,0] neg_lo:[1,0,0] neg_hi:[1,0,0]
	v_pk_fma_f32 v[122:123], v[68:69], v[202:203], v[122:123] op_sel_hi:[1,0,1]
	v_pk_fma_f32 v[150:151], v[68:69], v[234:235], v[150:151] op_sel_hi:[1,0,1]
	v_pk_fma_f32 v[146:147], v[68:69], v[226:227], v[68:69] op_sel_hi:[1,0,1] neg_lo:[1,0,0] neg_hi:[1,0,0]
	v_pk_fma_f32 v[122:123], v[70:71], v[202:203], v[122:123] op_sel:[0,1,0]
	v_pk_fma_f32 v[150:151], v[70:71], v[234:235], v[150:151] op_sel:[0,1,0]
	v_pk_fma_f32 v[148:149], v[70:71], v[226:227], v[70:71] op_sel:[0,1,0] neg_lo:[1,0,0] neg_hi:[1,0,0]
	v_pk_fma_f32 v[142:143], v[250:251], v[228:229], v[142:143] op_sel_hi:[1,0,1]
	v_pk_fma_f32 v[144:145], v[250:251], v[228:229], v[144:145] op_sel:[0,1,0]
	v_add_f32_dpp v150, v150, v150 quad_perm:[1,0,3,2] row_mask:0xf bank_mask:0xf bound_ctrl:1
	v_add_f32_dpp v151, v151, v151 quad_perm:[1,0,3,2] row_mask:0xf bank_mask:0xf bound_ctrl:1
	v_pk_fma_f32 v[146:147], v[250:251], v[230:231], v[146:147] op_sel_hi:[1,0,1]
	v_add_f32_dpp v150, v150, v150 quad_perm:[2,3,0,1] row_mask:0xf bank_mask:0xf bound_ctrl:1
	v_add_f32_dpp v151, v151, v151 quad_perm:[2,3,0,1] row_mask:0xf bank_mask:0xf bound_ctrl:1
	v_pk_fma_f32 v[148:149], v[250:251], v[230:231], v[148:149] op_sel:[0,1,0]
	v_add_f32_dpp v150, v150, v150 row_half_mirror row_mask:0xf bank_mask:0xf bound_ctrl:1
	v_add_f32_dpp v151, v151, v151 row_half_mirror row_mask:0xf bank_mask:0xf bound_ctrl:1
	s_nop 0
	v_add_f32_dpp v150, v150, v150 row_mirror row_mask:0xf bank_mask:0xf bound_ctrl:1
	v_add_f32_dpp v151, v151, v151 row_mirror row_mask:0xf bank_mask:0xf bound_ctrl:1
	s_waitcnt lgkmcnt(0)
; #define LAS __attribute__((address_space(3)))
; #define ROW16_SUM4(x, y, z, w) do { DPP4(x, y, z, w, "quad_perm:[1,0,3,2]", "s_nop 1"); DPP4(x, y, z, w, "quad_perm:[2,3,0,1]", ""); DPP4(x, y, z, w, "row_half_mirror", ""); DPP4(x, y, z, w, "row_mirror", ""); } while (0)
; template <bool SAMPLE>
; __device__ __forceinline__ void rwkv_unit(PR P, LAS float* lds, const int b, const int h, const int half, const int wv) {
;     ...
;                 for (int tt = 0; tt < GS; ++tt) {
;                     const LAS float* qn = q0 + (tt + 1 < GS ? tt + 1 : tt) * 384;
;                     const f32x4 nr4 = *(const LAS f32x4*)(qn + j0), no4 = *(const LAS f32x4*)(qn + 64 + j0), nk4 = *(const LAS f32x4*)(qn + 128 + j0), na4 = *(const LAS f32x4*)(qn + 192 + j0), nb4 = *(const LAS f32x4*)(qn + 256 + j0);
;                     const f32x2 nv2 = *(const LAS f32x2*)(qn + 320 + row0);
;                     f32x2 sa = (S[0] * a4[0] + S[1] * a4[1]) + (S[2] * a4[2] + S[3] * a4[3]);
;                     float sx = sa.x, sy = sa.y; ROW16_SUM4(sx, sy, py0, py1); sa = (f32x2){sx, sy};
;                     if (tt > 0) { yk0 = cgl == tt - 1 ? py0 : yk0; yk1 = cgl == tt - 1 ? py1 : yk1; }
; #pragma unroll
;                     for (int c = 0; c < 4; ++c) { f32x2 t = S[c] - S[c] * o4[c]; t = t + sa * b4[c]; S[c] = t + v2 * k4[c]; }
;                     const f32x2 y = (S[0] * r4[0] + S[1] * r4[1]) + (S[2] * r4[2] + S[3] * r4[3]);
;                     py0 = y.x; py1 = y.y;
;                     r4 = nr4; o4 = no4; k4 = nk4; a4 = na4; b4 = nb4; v2 = nv2;
	v_pk_fma_f32 v[66:67], v[150:151], v[236:237], v[142:143] op_sel_hi:[1,0,1]
	v_pk_fma_f32 v[20:21], v[150:151], v[236:237], v[144:145] op_sel:[0,1,0]
	v_pk_fma_f32 v[68:69], v[150:151], v[238:239], v[146:147] op_sel_hi:[1,0,1]
	v_pk_fma_f32 v[70:71], v[150:151], v[238:239], v[148:149] op_sel:[0,1,0]
	v_pk_mul_f32 v[124:125], v[66:67], v[220:221] op_sel_hi:[1,0]
	v_pk_mul_f32 v[150:151], v[66:67], v[172:173] op_sel_hi:[1,0]
	v_pk_fma_f32 v[142:143], v[66:67], v[164:165], v[66:67] op_sel_hi:[1,0,1] neg_lo:[1,0,0] neg_hi:[1,0,0]
	ds_read_b128 v[212:215], v152 offset:40704
	v_pk_fma_f32 v[124:125], v[20:21], v[220:221], v[124:125] op_sel:[0,1,0]
	v_pk_fma_f32 v[150:151], v[20:21], v[172:173], v[150:151] op_sel:[0,1,0]
	v_pk_fma_f32 v[144:145], v[20:21], v[164:165], v[20:21] op_sel:[0,1,0] neg_lo:[1,0,0] neg_hi:[1,0,0]
	ds_read_b128 v[204:207], v152 offset:40192
	v_pk_fma_f32 v[124:125], v[68:69], v[222:223], v[124:125] op_sel_hi:[1,0,1]
	v_pk_fma_f32 v[150:151], v[68:69], v[174:175], v[150:151] op_sel_hi:[1,0,1]
	v_pk_fma_f32 v[146:147], v[68:69], v[166:167], v[68:69] op_sel_hi:[1,0,1] neg_lo:[1,0,0] neg_hi:[1,0,0]
	ds_read2st64_b64 v[244:247], v153 offset0:80 offset1:83
	v_pk_fma_f32 v[124:125], v[70:71], v[222:223], v[124:125] op_sel:[0,1,0]
	v_pk_fma_f32 v[150:151], v[70:71], v[174:175], v[150:151] op_sel:[0,1,0]
	v_pk_fma_f32 v[148:149], v[70:71], v[166:167], v[70:71] op_sel:[0,1,0] neg_lo:[1,0,0] neg_hi:[1,0,0]
	ds_read_b128 v[208:211], v152 offset:40448
	v_pk_fma_f32 v[142:143], v[240:241], v[168:169], v[142:143] op_sel_hi:[1,0,1]
	v_pk_fma_f32 v[144:145], v[240:241], v[168:169], v[144:145] op_sel:[0,1,0]
	v_add_f32_dpp v150, v150, v150 quad_perm:[1,0,3,2] row_mask:0xf bank_mask:0xf bound_ctrl:1
	v_add_f32_dpp v151, v151, v151 quad_perm:[1,0,3,2] row_mask:0xf bank_mask:0xf bound_ctrl:1
	v_pk_fma_f32 v[146:147], v[240:241], v[170:171], v[146:147] op_sel_hi:[1,0,1]
	v_add_f32_dpp v150, v150, v150 quad_perm:[2,3,0,1] row_mask:0xf bank_mask:0xf bound_ctrl:1
	v_add_f32_dpp v151, v151, v151 quad_perm:[2,3,0,1] row_mask:0xf bank_mask:0xf bound_ctrl:1
	v_pk_fma_f32 v[148:149], v[240:241], v[170:171], v[148:149] op_sel:[0,1,0]
	v_add_f32_dpp v150, v150, v150 row_half_mirror row_mask:0xf bank_mask:0xf bound_ctrl:1
	v_add_f32_dpp v151, v151, v151 row_half_mirror row_mask:0xf bank_mask:0xf bound_ctrl:1
	ds_read_b128 v[232:235], v152 offset:42240
	v_add_f32_dpp v150, v150, v150 row_mirror row_mask:0xf bank_mask:0xf bound_ctrl:1
	v_add_f32_dpp v151, v151, v151 row_mirror row_mask:0xf bank_mask:0xf bound_ctrl:1
	ds_read_b128 v[224:227], v152 offset:41728
	ds_read_b128 v[216:219], v152 offset:40960
	ds_read_b128 v[228:231], v152 offset:41984
	ds_read_b128 v[236:239], v152 offset:42496
	ds_read_b128 v[200:203], v152 offset:39936
	ds_read_b128 v[220:223], v152 offset:41472
	v_pk_fma_f32 v[66:67], v[150:151], v[176:177], v[142:143] op_sel_hi:[1,0,1]
	v_pk_fma_f32 v[20:21], v[150:151], v[176:177], v[144:145] op_sel:[0,1,0]
	v_pk_fma_f32 v[68:69], v[150:151], v[178:179], v[146:147] op_sel_hi:[1,0,1]
	v_pk_fma_f32 v[70:71], v[150:151], v[178:179], v[148:149] op_sel:[0,1,0]
	v_pk_mul_f32 v[126:127], v[66:67], v[160:161] op_sel_hi:[1,0]
	v_pk_mul_f32 v[150:151], v[66:67], v[192:193] op_sel_hi:[1,0]
	v_pk_fma_f32 v[142:143], v[66:67], v[184:185], v[66:67] op_sel_hi:[1,0,1] neg_lo:[1,0,0] neg_hi:[1,0,0]
	v_pk_fma_f32 v[126:127], v[20:21], v[160:161], v[126:127] op_sel:[0,1,0]
	v_pk_fma_f32 v[150:151], v[20:21], v[192:193], v[150:151] op_sel:[0,1,0]
	v_pk_fma_f32 v[144:145], v[20:21], v[184:185], v[20:21] op_sel:[0,1,0] neg_lo:[1,0,0] neg_hi:[1,0,0]
	v_pk_fma_f32 v[126:127], v[68:69], v[162:163], v[126:127] op_sel_hi:[1,0,1]
	v_pk_fma_f32 v[150:151], v[68:69], v[194:195], v[150:151] op_sel_hi:[1,0,1]
	v_pk_fma_f32 v[146:147], v[68:69], v[186:187], v[68:69] op_sel_hi:[1,0,1] neg_lo:[1,0,0] neg_hi:[1,0,0]
	v_pk_fma_f32 v[126:127], v[70:71], v[162:163], v[126:127] op_sel:[0,1,0]
	v_pk_fma_f32 v[150:151], v[70:71], v[194:195], v[150:151] op_sel:[0,1,0]
	v_pk_fma_f32 v[148:149], v[70:71], v[186:187], v[70:71] op_sel:[0,1,0] neg_lo:[1,0,0] neg_hi:[1,0,0]
	v_pk_fma_f32 v[142:143], v[242:243], v[188:189], v[142:143] op_sel_hi:[1,0,1]
	v_pk_fma_f32 v[144:145], v[242:243], v[188:189], v[144:145] op_sel:[0,1,0]
	v_add_f32_dpp v150, v150, v150 quad_perm:[1,0,3,2] row_mask:0xf bank_mask:0xf bound_ctrl:1
	v_add_f32_dpp v151, v151, v151 quad_perm:[1,0,3,2] row_mask:0xf bank_mask:0xf bound_ctrl:1
	v_pk_fma_f32 v[146:147], v[242:243], v[190:191], v[146:147] op_sel_hi:[1,0,1]
	v_add_f32_dpp v150, v150, v150 quad_perm:[2,3,0,1] row_mask:0xf bank_mask:0xf bound_ctrl:1
	v_add_f32_dpp v151, v151, v151 quad_perm:[2,3,0,1] row_mask:0xf bank_mask:0xf bound_ctrl:1
	v_pk_fma_f32 v[148:149], v[242:243], v[190:191], v[148:149] op_sel:[0,1,0]
	v_add_f32_dpp v150, v150, v150 row_half_mirror row_mask:0xf bank_mask:0xf bound_ctrl:1
	v_add_f32_dpp v151, v151, v151 row_half_mirror row_mask:0xf bank_mask:0xf bound_ctrl:1
	s_nop 0
	v_add_f32_dpp v150, v150, v150 row_mirror row_mask:0xf bank_mask:0xf bound_ctrl:1
	v_add_f32_dpp v151, v151, v151 row_mirror row_mask:0xf bank_mask:0xf bound_ctrl:1
	s_waitcnt lgkmcnt(0)
; #define LAS __attribute__((address_space(3)))
; #define ROW16_SUM4(x, y, z, w) do { DPP4(x, y, z, w, "quad_perm:[1,0,3,2]", "s_nop 1"); DPP4(x, y, z, w, "quad_perm:[2,3,0,1]", ""); DPP4(x, y, z, w, "row_half_mirror", ""); DPP4(x, y, z, w, "row_mirror", ""); } while (0)
; template <bool SAMPLE>
; __device__ __forceinline__ void rwkv_unit(PR P, LAS float* lds, const int b, const int h, const int half, const int wv) {
;     ...
;                 for (int tt = 0; tt < GS; ++tt) {
;                     const LAS float* qn = q0 + (tt + 1 < GS ? tt + 1 : tt) * 384;
;                     const f32x4 nr4 = *(const LAS f32x4*)(qn + j0), no4 = *(const LAS f32x4*)(qn + 64 + j0), nk4 = *(const LAS f32x4*)(qn + 128 + j0), na4 = *(const LAS f32x4*)(qn + 192 + j0), nb4 = *(const LAS f32x4*)(qn + 256 + j0);
;                     const f32x2 nv2 = *(const LAS f32x2*)(qn + 320 + row0);
;                     f32x2 sa = (S[0] * a4[0] + S[1] * a4[1]) + (S[2] * a4[2] + S[3] * a4[3]);
;                     float sx = sa.x, sy = sa.y; ROW16_SUM4(sx, sy, py0, py1); sa = (f32x2){sx, sy};
;                     if (tt > 0) { yk0 = cgl == tt - 1 ? py0 : yk0; yk1 = cgl == tt - 1 ? py1 : yk1; }
; #pragma unroll
;                     for (int c = 0; c < 4; ++c) { f32x2 t = S[c] - S[c] * o4[c]; t = t + sa * b4[c]; S[c] = t + v2 * k4[c]; }
;                     const f32x2 y = (S[0] * r4[0] + S[1] * r4[1]) + (S[2] * r4[2] + S[3] * r4[3]);
;                     py0 = y.x; py1 = y.y;
;                     r4 = nr4; o4 = no4; k4 = nk4; a4 = na4; b4 = nb4; v2 = nv2;
	v_pk_fma_f32 v[66:67], v[150:151], v[196:197], v[142:143] op_sel_hi:[1,0,1]
	v_pk_fma_f32 v[20:21], v[150:151], v[196:197], v[144:145] op_sel:[0,1,0]
	v_pk_fma_f32 v[68:69], v[150:151], v[198:199], v[146:147] op_sel_hi:[1,0,1]
	v_pk_fma_f32 v[70:71], v[150:151], v[198:199], v[148:149] op_sel:[0,1,0]
	v_pk_mul_f32 v[128:129], v[66:67], v[180:181] op_sel_hi:[1,0]
	v_pk_mul_f32 v[150:151], v[66:67], v[212:213] op_sel_hi:[1,0]
	v_pk_fma_f32 v[142:143], v[66:67], v[204:205], v[66:67] op_sel_hi:[1,0,1] neg_lo:[1,0,0] neg_hi:[1,0,0]
	ds_read_b128 v[172:175], v152 offset:43776
	v_pk_fma_f32 v[128:129], v[20:21], v[180:181], v[128:129] op_sel:[0,1,0]
	v_pk_fma_f32 v[150:151], v[20:21], v[212:213], v[150:151] op_sel:[0,1,0]
	v_pk_fma_f32 v[144:145], v[20:21], v[204:205], v[20:21] op_sel:[0,1,0] neg_lo:[1,0,0] neg_hi:[1,0,0]
	ds_read_b128 v[164:167], v152 offset:43264
	v_pk_fma_f32 v[128:129], v[68:69], v[182:183], v[128:129] op_sel_hi:[1,0,1]
	v_pk_fma_f32 v[150:151], v[68:69], v[214:215], v[150:151] op_sel_hi:[1,0,1]
	v_pk_fma_f32 v[146:147], v[68:69], v[206:207], v[68:69] op_sel_hi:[1,0,1] neg_lo:[1,0,0] neg_hi:[1,0,0]
	ds_read2st64_b64 v[248:251], v153 offset0:86 offset1:89
	v_pk_fma_f32 v[128:129], v[70:71], v[182:183], v[128:129] op_sel:[0,1,0]
	v_pk_fma_f32 v[150:151], v[70:71], v[214:215], v[150:151] op_sel:[0,1,0]
	v_pk_fma_f32 v[148:149], v[70:71], v[206:207], v[70:71] op_sel:[0,1,0] neg_lo:[1,0,0] neg_hi:[1,0,0]
	ds_read_b128 v[168:171], v152 offset:43520
	v_pk_fma_f32 v[142:143], v[244:245], v[208:209], v[142:143] op_sel_hi:[1,0,1]
	v_pk_fma_f32 v[144:145], v[244:245], v[208:209], v[144:145] op_sel:[0,1,0]
	v_add_f32_dpp v150, v150, v150 quad_perm:[1,0,3,2] row_mask:0xf bank_mask:0xf bound_ctrl:1
	v_add_f32_dpp v151, v151, v151 quad_perm:[1,0,3,2] row_mask:0xf bank_mask:0xf bound_ctrl:1
	v_pk_fma_f32 v[146:147], v[244:245], v[210:211], v[146:147] op_sel_hi:[1,0,1]
	v_add_f32_dpp v150, v150, v150 quad_perm:[2,3,0,1] row_mask:0xf bank_mask:0xf bound_ctrl:1
	v_add_f32_dpp v151, v151, v151 quad_perm:[2,3,0,1] row_mask:0xf bank_mask:0xf bound_ctrl:1
	v_pk_fma_f32 v[148:149], v[244:245], v[210:211], v[148:149] op_sel:[0,1,0]
	v_add_f32_dpp v150, v150, v150 row_half_mirror row_mask:0xf bank_mask:0xf bound_ctrl:1
	v_add_f32_dpp v151, v151, v151 row_half_mirror row_mask:0xf bank_mask:0xf bound_ctrl:1
	ds_read_b128 v[192:195], v152 offset:45312
	v_add_f32_dpp v150, v150, v150 row_mirror row_mask:0xf bank_mask:0xf bound_ctrl:1
	v_add_f32_dpp v151, v151, v151 row_mirror row_mask:0xf bank_mask:0xf bound_ctrl:1
	ds_read_b128 v[184:187], v152 offset:44800
	ds_read_b128 v[176:179], v152 offset:44032
	ds_read_b128 v[188:191], v152 offset:45056
	ds_read_b128 v[196:199], v152 offset:45568
	ds_read_b128 v[160:163], v152 offset:43008
	ds_read_b128 v[180:183], v152 offset:44544
	v_pk_fma_f32 v[66:67], v[150:151], v[216:217], v[142:143] op_sel_hi:[1,0,1]
	v_pk_fma_f32 v[20:21], v[150:151], v[216:217], v[144:145] op_sel:[0,1,0]
	v_pk_fma_f32 v[68:69], v[150:151], v[218:219], v[146:147] op_sel_hi:[1,0,1]
	v_pk_fma_f32 v[70:71], v[150:151], v[218:219], v[148:149] op_sel:[0,1,0]
	v_pk_mul_f32 v[130:131], v[66:67], v[200:201] op_sel_hi:[1,0]
	v_pk_mul_f32 v[150:151], v[66:67], v[232:233] op_sel_hi:[1,0]
	v_pk_fma_f32 v[142:143], v[66:67], v[224:225], v[66:67] op_sel_hi:[1,0,1] neg_lo:[1,0,0] neg_hi:[1,0,0]
	v_pk_fma_f32 v[130:131], v[20:21], v[200:201], v[130:131] op_sel:[0,1,0]
	v_pk_fma_f32 v[150:151], v[20:21], v[232:233], v[150:151] op_sel:[0,1,0]
	v_pk_fma_f32 v[144:145], v[20:21], v[224:225], v[20:21] op_sel:[0,1,0] neg_lo:[1,0,0] neg_hi:[1,0,0]
	v_pk_fma_f32 v[130:131], v[68:69], v[202:203], v[130:131] op_sel_hi:[1,0,1]
	v_pk_fma_f32 v[150:151], v[68:69], v[234:235], v[150:151] op_sel_hi:[1,0,1]
	v_pk_fma_f32 v[146:147], v[68:69], v[226:227], v[68:69] op_sel_hi:[1,0,1] neg_lo:[1,0,0] neg_hi:[1,0,0]
	v_pk_fma_f32 v[130:131], v[70:71], v[202:203], v[130:131] op_sel:[0,1,0]
	v_pk_fma_f32 v[150:151], v[70:71], v[234:235], v[150:151] op_sel:[0,1,0]
	v_pk_fma_f32 v[148:149], v[70:71], v[226:227], v[70:71] op_sel:[0,1,0] neg_lo:[1,0,0] neg_hi:[1,0,0]
	v_pk_fma_f32 v[142:143], v[246:247], v[228:229], v[142:143] op_sel_hi:[1,0,1]
	v_pk_fma_f32 v[144:145], v[246:247], v[228:229], v[144:145] op_sel:[0,1,0]
	v_add_f32_dpp v150, v150, v150 quad_perm:[1,0,3,2] row_mask:0xf bank_mask:0xf bound_ctrl:1
	v_add_f32_dpp v151, v151, v151 quad_perm:[1,0,3,2] row_mask:0xf bank_mask:0xf bound_ctrl:1
	v_pk_fma_f32 v[146:147], v[246:247], v[230:231], v[146:147] op_sel_hi:[1,0,1]
	v_add_f32_dpp v150, v150, v150 quad_perm:[2,3,0,1] row_mask:0xf bank_mask:0xf bound_ctrl:1
	v_add_f32_dpp v151, v151, v151 quad_perm:[2,3,0,1] row_mask:0xf bank_mask:0xf bound_ctrl:1
	v_pk_fma_f32 v[148:149], v[246:247], v[230:231], v[148:149] op_sel:[0,1,0]
	v_add_f32_dpp v150, v150, v150 row_half_mirror row_mask:0xf bank_mask:0xf bound_ctrl:1
	v_add_f32_dpp v151, v151, v151 row_half_mirror row_mask:0xf bank_mask:0xf bound_ctrl:1
	s_nop 0
	v_add_f32_dpp v150, v150, v150 row_mirror row_mask:0xf bank_mask:0xf bound_ctrl:1
	v_add_f32_dpp v151, v151, v151 row_mirror row_mask:0xf bank_mask:0xf bound_ctrl:1
	s_waitcnt lgkmcnt(0)
; #define LAS __attribute__((address_space(3)))
; #define ROW16_SUM4(x, y, z, w) do { DPP4(x, y, z, w, "quad_perm:[1,0,3,2]", "s_nop 1"); DPP4(x, y, z, w, "quad_perm:[2,3,0,1]", ""); DPP4(x, y, z, w, "row_half_mirror", ""); DPP4(x, y, z, w, "row_mirror", ""); } while (0)
; template <bool SAMPLE>
; __device__ __forceinline__ void rwkv_unit(PR P, LAS float* lds, const int b, const int h, const int half, const int wv) {
;     ...
;                 for (int tt = 0; tt < GS; ++tt) {
;                     const LAS float* qn = q0 + (tt + 1 < GS ? tt + 1 : tt) * 384;
;                     const f32x4 nr4 = *(const LAS f32x4*)(qn + j0), no4 = *(const LAS f32x4*)(qn + 64 + j0), nk4 = *(const LAS f32x4*)(qn + 128 + j0), na4 = *(const LAS f32x4*)(qn + 192 + j0), nb4 = *(const LAS f32x4*)(qn + 256 + j0);
;                     const f32x2 nv2 = *(const LAS f32x2*)(qn + 320 + row0);
;                     f32x2 sa = (S[0] * a4[0] + S[1] * a4[1]) + (S[2] * a4[2] + S[3] * a4[3]);
;                     float sx = sa.x, sy = sa.y; ROW16_SUM4(sx, sy, py0, py1); sa = (f32x2){sx, sy};
;                     if (tt > 0) { yk0 = cgl == tt - 1 ? py0 : yk0; yk1 = cgl == tt - 1 ? py1 : yk1; }
; #pragma unroll
;                     for (int c = 0; c < 4; ++c) { f32x2 t = S[c] - S[c] * o4[c]; t = t + sa * b4[c]; S[c] = t + v2 * k4[c]; }
;                     const f32x2 y = (S[0] * r4[0] + S[1] * r4[1]) + (S[2] * r4[2] + S[3] * r4[3]);
;                     py0 = y.x; py1 = y.y;
;                     r4 = nr4; o4 = no4; k4 = nk4; a4 = na4; b4 = nb4; v2 = nv2;
	v_pk_fma_f32 v[66:67], v[150:151], v[236:237], v[142:143] op_sel_hi:[1,0,1]
	v_pk_fma_f32 v[20:21], v[150:151], v[236:237], v[144:145] op_sel:[0,1,0]
	v_pk_fma_f32 v[68:69], v[150:151], v[238:239], v[146:147] op_sel_hi:[1,0,1]
	v_pk_fma_f32 v[70:71], v[150:151], v[238:239], v[148:149] op_sel:[0,1,0]
	v_pk_mul_f32 v[132:133], v[66:67], v[220:221] op_sel_hi:[1,0]
	v_pk_mul_f32 v[150:151], v[66:67], v[172:173] op_sel_hi:[1,0]
	v_pk_fma_f32 v[142:143], v[66:67], v[164:165], v[66:67] op_sel_hi:[1,0,1] neg_lo:[1,0,0] neg_hi:[1,0,0]
	ds_read_b128 v[212:215], v152 offset:46848
	v_pk_fma_f32 v[132:133], v[20:21], v[220:221], v[132:133] op_sel:[0,1,0]
	v_pk_fma_f32 v[150:151], v[20:21], v[172:173], v[150:151] op_sel:[0,1,0]
	v_pk_fma_f32 v[144:145], v[20:21], v[164:165], v[20:21] op_sel:[0,1,0] neg_lo:[1,0,0] neg_hi:[1,0,0]
	ds_read_b128 v[204:207], v152 offset:46336
	v_pk_fma_f32 v[132:133], v[68:69], v[222:223], v[132:133] op_sel_hi:[1,0,1]
	v_pk_fma_f32 v[150:151], v[68:69], v[174:175], v[150:151] op_sel_hi:[1,0,1]
	v_pk_fma_f32 v[146:147], v[68:69], v[166:167], v[68:69] op_sel_hi:[1,0,1] neg_lo:[1,0,0] neg_hi:[1,0,0]
	ds_read2st64_b64 v[240:243], v153 offset0:92 offset1:95
	v_pk_fma_f32 v[132:133], v[70:71], v[222:223], v[132:133] op_sel:[0,1,0]
	v_pk_fma_f32 v[150:151], v[70:71], v[174:175], v[150:151] op_sel:[0,1,0]
	v_pk_fma_f32 v[148:149], v[70:71], v[166:167], v[70:71] op_sel:[0,1,0] neg_lo:[1,0,0] neg_hi:[1,0,0]
	ds_read_b128 v[208:211], v152 offset:46592
	v_pk_fma_f32 v[142:143], v[248:249], v[168:169], v[142:143] op_sel_hi:[1,0,1]
	v_pk_fma_f32 v[144:145], v[248:249], v[168:169], v[144:145] op_sel:[0,1,0]
	v_add_f32_dpp v150, v150, v150 quad_perm:[1,0,3,2] row_mask:0xf bank_mask:0xf bound_ctrl:1
	v_add_f32_dpp v151, v151, v151 quad_perm:[1,0,3,2] row_mask:0xf bank_mask:0xf bound_ctrl:1
	v_pk_fma_f32 v[146:147], v[248:249], v[170:171], v[146:147] op_sel_hi:[1,0,1]
	v_add_f32_dpp v150, v150, v150 quad_perm:[2,3,0,1] row_mask:0xf bank_mask:0xf bound_ctrl:1
	v_add_f32_dpp v151, v151, v151 quad_perm:[2,3,0,1] row_mask:0xf bank_mask:0xf bound_ctrl:1
	v_pk_fma_f32 v[148:149], v[248:249], v[170:171], v[148:149] op_sel:[0,1,0]
	v_add_f32_dpp v150, v150, v150 row_half_mirror row_mask:0xf bank_mask:0xf bound_ctrl:1
	v_add_f32_dpp v151, v151, v151 row_half_mirror row_mask:0xf bank_mask:0xf bound_ctrl:1
	ds_read_b128 v[232:235], v152 offset:48384
	v_add_f32_dpp v150, v150, v150 row_mirror row_mask:0xf bank_mask:0xf bound_ctrl:1
	v_add_f32_dpp v151, v151, v151 row_mirror row_mask:0xf bank_mask:0xf bound_ctrl:1
	ds_read_b128 v[224:227], v152 offset:47872
	ds_read_b128 v[216:219], v152 offset:47104
	ds_read_b128 v[228:231], v152 offset:48128
	ds_read_b128 v[236:239], v152 offset:48640
	ds_read_b128 v[200:203], v152 offset:46080
	ds_read_b128 v[220:223], v152 offset:47616
	v_pk_fma_f32 v[66:67], v[150:151], v[176:177], v[142:143] op_sel_hi:[1,0,1]
	v_pk_fma_f32 v[20:21], v[150:151], v[176:177], v[144:145] op_sel:[0,1,0]
	v_pk_fma_f32 v[68:69], v[150:151], v[178:179], v[146:147] op_sel_hi:[1,0,1]
	v_pk_fma_f32 v[70:71], v[150:151], v[178:179], v[148:149] op_sel:[0,1,0]
	v_pk_mul_f32 v[134:135], v[66:67], v[160:161] op_sel_hi:[1,0]
	v_pk_mul_f32 v[150:151], v[66:67], v[192:193] op_sel_hi:[1,0]
	v_pk_fma_f32 v[142:143], v[66:67], v[184:185], v[66:67] op_sel_hi:[1,0,1] neg_lo:[1,0,0] neg_hi:[1,0,0]
	v_pk_fma_f32 v[134:135], v[20:21], v[160:161], v[134:135] op_sel:[0,1,0]
	v_pk_fma_f32 v[150:151], v[20:21], v[192:193], v[150:151] op_sel:[0,1,0]
	v_pk_fma_f32 v[144:145], v[20:21], v[184:185], v[20:21] op_sel:[0,1,0] neg_lo:[1,0,0] neg_hi:[1,0,0]
	v_pk_fma_f32 v[134:135], v[68:69], v[162:163], v[134:135] op_sel_hi:[1,0,1]
	v_pk_fma_f32 v[150:151], v[68:69], v[194:195], v[150:151] op_sel_hi:[1,0,1]
	v_pk_fma_f32 v[146:147], v[68:69], v[186:187], v[68:69] op_sel_hi:[1,0,1] neg_lo:[1,0,0] neg_hi:[1,0,0]
	v_pk_fma_f32 v[134:135], v[70:71], v[162:163], v[134:135] op_sel:[0,1,0]
	v_pk_fma_f32 v[150:151], v[70:71], v[194:195], v[150:151] op_sel:[0,1,0]
	v_pk_fma_f32 v[148:149], v[70:71], v[186:187], v[70:71] op_sel:[0,1,0] neg_lo:[1,0,0] neg_hi:[1,0,0]
	v_pk_fma_f32 v[142:143], v[250:251], v[188:189], v[142:143] op_sel_hi:[1,0,1]
	v_pk_fma_f32 v[144:145], v[250:251], v[188:189], v[144:145] op_sel:[0,1,0]
	v_add_f32_dpp v150, v150, v150 quad_perm:[1,0,3,2] row_mask:0xf bank_mask:0xf bound_ctrl:1
	v_add_f32_dpp v151, v151, v151 quad_perm:[1,0,3,2] row_mask:0xf bank_mask:0xf bound_ctrl:1
	v_pk_fma_f32 v[146:147], v[250:251], v[190:191], v[146:147] op_sel_hi:[1,0,1]
	v_add_f32_dpp v150, v150, v150 quad_perm:[2,3,0,1] row_mask:0xf bank_mask:0xf bound_ctrl:1
	v_add_f32_dpp v151, v151, v151 quad_perm:[2,3,0,1] row_mask:0xf bank_mask:0xf bound_ctrl:1
	v_pk_fma_f32 v[148:149], v[250:251], v[190:191], v[148:149] op_sel:[0,1,0]
	v_add_f32_dpp v150, v150, v150 row_half_mirror row_mask:0xf bank_mask:0xf bound_ctrl:1
	v_add_f32_dpp v151, v151, v151 row_half_mirror row_mask:0xf bank_mask:0xf bound_ctrl:1
	s_nop 0
	v_add_f32_dpp v150, v150, v150 row_mirror row_mask:0xf bank_mask:0xf bound_ctrl:1
	v_add_f32_dpp v151, v151, v151 row_mirror row_mask:0xf bank_mask:0xf bound_ctrl:1
	s_waitcnt lgkmcnt(0)
; #define LAS __attribute__((address_space(3)))
; #define ROW16_SUM4(x, y, z, w) do { DPP4(x, y, z, w, "quad_perm:[1,0,3,2]", "s_nop 1"); DPP4(x, y, z, w, "quad_perm:[2,3,0,1]", ""); DPP4(x, y, z, w, "row_half_mirror", ""); DPP4(x, y, z, w, "row_mirror", ""); } while (0)
; template <bool SAMPLE>
; __device__ __forceinline__ void rwkv_unit(PR P, LAS float* lds, const int b, const int h, const int half, const int wv) {
;     ...
;                 for (int tt = 0; tt < GS; ++tt) {
;                     const LAS float* qn = q0 + (tt + 1 < GS ? tt + 1 : tt) * 384;
;                     const f32x4 nr4 = *(const LAS f32x4*)(qn + j0), no4 = *(const LAS f32x4*)(qn + 64 + j0), nk4 = *(const LAS f32x4*)(qn + 128 + j0), na4 = *(const LAS f32x4*)(qn + 192 + j0), nb4 = *(const LAS f32x4*)(qn + 256 + j0);
;                     const f32x2 nv2 = *(const LAS f32x2*)(qn + 320 + row0);
;                     f32x2 sa = (S[0] * a4[0] + S[1] * a4[1]) + (S[2] * a4[2] + S[3] * a4[3]);
;                     float sx = sa.x, sy = sa.y; ROW16_SUM4(sx, sy, py0, py1); sa = (f32x2){sx, sy};
;                     if (tt > 0) { yk0 = cgl == tt - 1 ? py0 : yk0; yk1 = cgl == tt - 1 ? py1 : yk1; }
; #pragma unroll
;                     for (int c = 0; c < 4; ++c) { f32x2 t = S[c] - S[c] * o4[c]; t = t + sa * b4[c]; S[c] = t + v2 * k4[c]; }
;                     const f32x2 y = (S[0] * r4[0] + S[1] * r4[1]) + (S[2] * r4[2] + S[3] * r4[3]);
;                     py0 = y.x; py1 = y.y;
;                     r4 = nr4; o4 = no4; k4 = nk4; a4 = na4; b4 = nb4; v2 = nv2;
	v_pk_fma_f32 v[66:67], v[150:151], v[196:197], v[142:143] op_sel_hi:[1,0,1]
	v_pk_fma_f32 v[20:21], v[150:151], v[196:197], v[144:145] op_sel:[0,1,0]
	v_pk_fma_f32 v[68:69], v[150:151], v[198:199], v[146:147] op_sel_hi:[1,0,1]
	v_pk_fma_f32 v[70:71], v[150:151], v[198:199], v[148:149] op_sel:[0,1,0]
	v_pk_mul_f32 v[136:137], v[66:67], v[180:181] op_sel_hi:[1,0]
	v_pk_mul_f32 v[150:151], v[66:67], v[212:213] op_sel_hi:[1,0]
	v_pk_fma_f32 v[142:143], v[66:67], v[204:205], v[66:67] op_sel_hi:[1,0,1] neg_lo:[1,0,0] neg_hi:[1,0,0]
	v_pk_fma_f32 v[136:137], v[20:21], v[180:181], v[136:137] op_sel:[0,1,0]
	v_pk_fma_f32 v[150:151], v[20:21], v[212:213], v[150:151] op_sel:[0,1,0]
	v_pk_fma_f32 v[144:145], v[20:21], v[204:205], v[20:21] op_sel:[0,1,0] neg_lo:[1,0,0] neg_hi:[1,0,0]
	v_pk_fma_f32 v[136:137], v[68:69], v[182:183], v[136:137] op_sel_hi:[1,0,1]
	v_pk_fma_f32 v[150:151], v[68:69], v[214:215], v[150:151] op_sel_hi:[1,0,1]
	v_pk_fma_f32 v[146:147], v[68:69], v[206:207], v[68:69] op_sel_hi:[1,0,1] neg_lo:[1,0,0] neg_hi:[1,0,0]
	v_pk_fma_f32 v[136:137], v[70:71], v[182:183], v[136:137] op_sel:[0,1,0]
	v_pk_fma_f32 v[150:151], v[70:71], v[214:215], v[150:151] op_sel:[0,1,0]
	v_pk_fma_f32 v[148:149], v[70:71], v[206:207], v[70:71] op_sel:[0,1,0] neg_lo:[1,0,0] neg_hi:[1,0,0]
	v_pk_fma_f32 v[142:143], v[240:241], v[208:209], v[142:143] op_sel_hi:[1,0,1]
	v_pk_fma_f32 v[144:145], v[240:241], v[208:209], v[144:145] op_sel:[0,1,0]
	v_add_f32_dpp v150, v150, v150 quad_perm:[1,0,3,2] row_mask:0xf bank_mask:0xf bound_ctrl:1
	v_add_f32_dpp v151, v151, v151 quad_perm:[1,0,3,2] row_mask:0xf bank_mask:0xf bound_ctrl:1
	v_pk_fma_f32 v[146:147], v[240:241], v[210:211], v[146:147] op_sel_hi:[1,0,1]
	v_add_f32_dpp v150, v150, v150 quad_perm:[2,3,0,1] row_mask:0xf bank_mask:0xf bound_ctrl:1
	v_add_f32_dpp v151, v151, v151 quad_perm:[2,3,0,1] row_mask:0xf bank_mask:0xf bound_ctrl:1
	v_pk_fma_f32 v[148:149], v[240:241], v[210:211], v[148:149] op_sel:[0,1,0]
	v_add_f32_dpp v150, v150, v150 row_half_mirror row_mask:0xf bank_mask:0xf bound_ctrl:1
	v_add_f32_dpp v151, v151, v151 row_half_mirror row_mask:0xf bank_mask:0xf bound_ctrl:1
	s_nop 0
	v_add_f32_dpp v150, v150, v150 row_mirror row_mask:0xf bank_mask:0xf bound_ctrl:1
	v_add_f32_dpp v151, v151, v151 row_mirror row_mask:0xf bank_mask:0xf bound_ctrl:1
	v_pk_fma_f32 v[66:67], v[150:151], v[216:217], v[142:143] op_sel_hi:[1,0,1]
	v_pk_fma_f32 v[20:21], v[150:151], v[216:217], v[144:145] op_sel:[0,1,0]
	v_pk_fma_f32 v[68:69], v[150:151], v[218:219], v[146:147] op_sel_hi:[1,0,1]
	v_pk_fma_f32 v[70:71], v[150:151], v[218:219], v[148:149] op_sel:[0,1,0]
	v_pk_mul_f32 v[138:139], v[66:67], v[200:201] op_sel_hi:[1,0]
	v_pk_mul_f32 v[150:151], v[66:67], v[232:233] op_sel_hi:[1,0]
	v_pk_fma_f32 v[142:143], v[66:67], v[224:225], v[66:67] op_sel_hi:[1,0,1] neg_lo:[1,0,0] neg_hi:[1,0,0]
	v_pk_fma_f32 v[138:139], v[20:21], v[200:201], v[138:139] op_sel:[0,1,0]
	v_pk_fma_f32 v[150:151], v[20:21], v[232:233], v[150:151] op_sel:[0,1,0]
	v_pk_fma_f32 v[144:145], v[20:21], v[224:225], v[20:21] op_sel:[0,1,0] neg_lo:[1,0,0] neg_hi:[1,0,0]
	v_pk_fma_f32 v[138:139], v[68:69], v[202:203], v[138:139] op_sel_hi:[1,0,1]
	v_pk_fma_f32 v[150:151], v[68:69], v[234:235], v[150:151] op_sel_hi:[1,0,1]
	v_pk_fma_f32 v[146:147], v[68:69], v[226:227], v[68:69] op_sel_hi:[1,0,1] neg_lo:[1,0,0] neg_hi:[1,0,0]
	v_pk_fma_f32 v[138:139], v[70:71], v[202:203], v[138:139] op_sel:[0,1,0]
	v_pk_fma_f32 v[150:151], v[70:71], v[234:235], v[150:151] op_sel:[0,1,0]
	v_pk_fma_f32 v[148:149], v[70:71], v[226:227], v[70:71] op_sel:[0,1,0] neg_lo:[1,0,0] neg_hi:[1,0,0]
	v_pk_fma_f32 v[142:143], v[242:243], v[228:229], v[142:143] op_sel_hi:[1,0,1]
	v_pk_fma_f32 v[144:145], v[242:243], v[228:229], v[144:145] op_sel:[0,1,0]
	v_add_f32_dpp v150, v150, v150 quad_perm:[1,0,3,2] row_mask:0xf bank_mask:0xf bound_ctrl:1
	v_add_f32_dpp v151, v151, v151 quad_perm:[1,0,3,2] row_mask:0xf bank_mask:0xf bound_ctrl:1
	v_pk_fma_f32 v[146:147], v[242:243], v[230:231], v[146:147] op_sel_hi:[1,0,1]
	v_add_f32_dpp v150, v150, v150 quad_perm:[2,3,0,1] row_mask:0xf bank_mask:0xf bound_ctrl:1
	v_add_f32_dpp v151, v151, v151 quad_perm:[2,3,0,1] row_mask:0xf bank_mask:0xf bound_ctrl:1
	v_pk_fma_f32 v[148:149], v[242:243], v[230:231], v[148:149] op_sel:[0,1,0]
	v_add_f32_dpp v150, v150, v150 row_half_mirror row_mask:0xf bank_mask:0xf bound_ctrl:1
	v_add_f32_dpp v151, v151, v151 row_half_mirror row_mask:0xf bank_mask:0xf bound_ctrl:1
	s_nop 0
	v_add_f32_dpp v150, v150, v150 row_mirror row_mask:0xf bank_mask:0xf bound_ctrl:1
	v_add_f32_dpp v151, v151, v151 row_mirror row_mask:0xf bank_mask:0xf bound_ctrl:1
	v_pk_fma_f32 v[66:67], v[150:151], v[236:237], v[142:143] op_sel_hi:[1,0,1]
	v_pk_fma_f32 v[20:21], v[150:151], v[236:237], v[144:145] op_sel:[0,1,0]
	v_pk_fma_f32 v[68:69], v[150:151], v[238:239], v[146:147] op_sel_hi:[1,0,1]
	v_pk_fma_f32 v[70:71], v[150:151], v[238:239], v[148:149] op_sel:[0,1,0]
	v_pk_mul_f32 v[140:141], v[66:67], v[220:221] op_sel_hi:[1,0]
	v_pk_fma_f32 v[140:141], v[20:21], v[220:221], v[140:141] op_sel:[0,1,0]
	v_pk_fma_f32 v[140:141], v[68:69], v[222:223], v[140:141] op_sel_hi:[1,0,1]
	v_pk_fma_f32 v[140:141], v[70:71], v[222:223], v[140:141] op_sel:[0,1,0]
	s_branch .LBB0_704
; __device__ __forceinline__ unsigned cvt_pk_bf16(float lo, float hi) { const f32x2_t v = {lo, hi}; const bf16x2_t b = __builtin_convertvector(v, bf16x2_t); return __builtin_bit_cast(unsigned, b); }
; #define ROW16_SUM2(x, y) do { DPP2(x, y, "quad_perm:[1,0,3,2]", "s_nop 1"); DPP2(x, y, "quad_perm:[2,3,0,1]", "s_nop 0"); DPP2(x, y, "row_half_mirror", "s_nop 0"); DPP2(x, y, "row_mirror", "s_nop 0"); } while (0)
; template <bool SAMPLE>
; __device__ __forceinline__ void rwkv_unit(PR P, LAS float* lds, const int b, const int h, const int half, const int wv) {
;     ...
;                 ROW16_SUM2(py0, py1); yk0 = cgl == GS - 1 ? py0 : yk0; yk1 = cgl == GS - 1 ? py1 : yk1;
;                 if (cgl < GS) *(unsigned*)(YS + (size_t)(row_base + c * TC + g * GS + cgl) * 512 + h * 64 + row0) = pg8::cvt_pk_bf16(yk0, yk1);
;     ...
;     if (wid < 4) { *(float4*)sout = make_float4(S[0].x, S[1].x, S[2].x, S[3].x); *(float4*)(sout + 64) = make_float4(S[0].y, S[1].y, S[2].y, S[3].y); }
.LBB0_723:
	s_and_saveexec_b64 s[10:11], s[8:9]
	s_cbranch_execz .LBB0_725
	v_add_f32_dpp v110, v110, v110 row_ror:8 row_mask:0xf bank_mask:0x3 bound_ctrl:1
	v_add_f32_dpp v110, v126, v126 row_ror:8 row_mask:0xf bank_mask:0xc bound_ctrl:1
	v_add_f32_dpp v112, v112, v112 row_ror:8 row_mask:0xf bank_mask:0x3 bound_ctrl:1
	v_add_f32_dpp v112, v128, v128 row_ror:8 row_mask:0xf bank_mask:0xc bound_ctrl:1
	v_add_f32_dpp v114, v114, v114 row_ror:8 row_mask:0xf bank_mask:0x3 bound_ctrl:1
	v_add_f32_dpp v114, v130, v130 row_ror:8 row_mask:0xf bank_mask:0xc bound_ctrl:1
	v_add_f32_dpp v116, v116, v116 row_ror:8 row_mask:0xf bank_mask:0x3 bound_ctrl:1
	v_add_f32_dpp v116, v132, v132 row_ror:8 row_mask:0xf bank_mask:0xc bound_ctrl:1
	v_add_f32_dpp v118, v118, v118 row_ror:8 row_mask:0xf bank_mask:0x3 bound_ctrl:1
	v_add_f32_dpp v118, v134, v134 row_ror:8 row_mask:0xf bank_mask:0xc bound_ctrl:1
	v_add_f32_dpp v120, v120, v120 row_ror:8 row_mask:0xf bank_mask:0x3 bound_ctrl:1
	v_add_f32_dpp v120, v136, v136 row_ror:8 row_mask:0xf bank_mask:0xc bound_ctrl:1
	v_add_f32_dpp v122, v122, v122 row_ror:8 row_mask:0xf bank_mask:0x3 bound_ctrl:1
	v_add_f32_dpp v122, v138, v138 row_ror:8 row_mask:0xf bank_mask:0xc bound_ctrl:1
	v_add_f32_dpp v124, v124, v124 row_ror:8 row_mask:0xf bank_mask:0x3 bound_ctrl:1
	v_add_f32_dpp v124, v140, v140 row_ror:8 row_mask:0xf bank_mask:0xc bound_ctrl:1
	v_add_f32_dpp v111, v111, v111 row_ror:8 row_mask:0xf bank_mask:0x3 bound_ctrl:1
	v_add_f32_dpp v111, v127, v127 row_ror:8 row_mask:0xf bank_mask:0xc bound_ctrl:1
	v_add_f32_dpp v113, v113, v113 row_ror:8 row_mask:0xf bank_mask:0x3 bound_ctrl:1
	v_add_f32_dpp v113, v129, v129 row_ror:8 row_mask:0xf bank_mask:0xc bound_ctrl:1
	v_add_f32_dpp v115, v115, v115 row_ror:8 row_mask:0xf bank_mask:0x3 bound_ctrl:1
	v_add_f32_dpp v115, v131, v131 row_ror:8 row_mask:0xf bank_mask:0xc bound_ctrl:1
	v_add_f32_dpp v117, v117, v117 row_ror:8 row_mask:0xf bank_mask:0x3 bound_ctrl:1
	v_add_f32_dpp v117, v133, v133 row_ror:8 row_mask:0xf bank_mask:0xc bound_ctrl:1
	v_add_f32_dpp v119, v119, v119 row_ror:8 row_mask:0xf bank_mask:0x3 bound_ctrl:1
	v_add_f32_dpp v119, v135, v135 row_ror:8 row_mask:0xf bank_mask:0xc bound_ctrl:1
	v_add_f32_dpp v121, v121, v121 row_ror:8 row_mask:0xf bank_mask:0x3 bound_ctrl:1
	v_add_f32_dpp v121, v137, v137 row_ror:8 row_mask:0xf bank_mask:0xc bound_ctrl:1
	v_add_f32_dpp v123, v123, v123 row_ror:8 row_mask:0xf bank_mask:0x3 bound_ctrl:1
	v_add_f32_dpp v123, v139, v139 row_ror:8 row_mask:0xf bank_mask:0xc bound_ctrl:1
	v_add_f32_dpp v125, v125, v125 row_ror:8 row_mask:0xf bank_mask:0x3 bound_ctrl:1
	v_add_f32_dpp v125, v141, v141 row_ror:8 row_mask:0xf bank_mask:0xc bound_ctrl:1
	v_add_f32_dpp v110, v110, v110 row_shl:4 row_mask:0xf bank_mask:0x5 bound_ctrl:1
	v_add_f32_dpp v110, v118, v118 row_shr:4 row_mask:0xf bank_mask:0xa bound_ctrl:1
	v_add_f32_dpp v112, v112, v112 row_shl:4 row_mask:0xf bank_mask:0x5 bound_ctrl:1
	v_add_f32_dpp v112, v120, v120 row_shr:4 row_mask:0xf bank_mask:0xa bound_ctrl:1
	v_add_f32_dpp v114, v114, v114 row_shl:4 row_mask:0xf bank_mask:0x5 bound_ctrl:1
	v_add_f32_dpp v114, v122, v122 row_shr:4 row_mask:0xf bank_mask:0xa bound_ctrl:1
	v_add_f32_dpp v116, v116, v116 row_shl:4 row_mask:0xf bank_mask:0x5 bound_ctrl:1
	v_add_f32_dpp v116, v124, v124 row_shr:4 row_mask:0xf bank_mask:0xa bound_ctrl:1
	v_add_f32_dpp v111, v111, v111 row_shl:4 row_mask:0xf bank_mask:0x5 bound_ctrl:1
	v_add_f32_dpp v111, v119, v119 row_shr:4 row_mask:0xf bank_mask:0xa bound_ctrl:1
	v_add_f32_dpp v113, v113, v113 row_shl:4 row_mask:0xf bank_mask:0x5 bound_ctrl:1
	v_add_f32_dpp v113, v121, v121 row_shr:4 row_mask:0xf bank_mask:0xa bound_ctrl:1
	v_add_f32_dpp v115, v115, v115 row_shl:4 row_mask:0xf bank_mask:0x5 bound_ctrl:1
	v_add_f32_dpp v115, v123, v123 row_shr:4 row_mask:0xf bank_mask:0xa bound_ctrl:1
	v_add_f32_dpp v117, v117, v117 row_shl:4 row_mask:0xf bank_mask:0x5 bound_ctrl:1
	v_add_f32_dpp v117, v125, v125 row_shr:4 row_mask:0xf bank_mask:0xa bound_ctrl:1
	v_add_f32_dpp v110, v110, v110 quad_perm:[1,0,3,2] row_mask:0xf bank_mask:0xf bound_ctrl:1
	v_add_f32_dpp v112, v112, v112 quad_perm:[1,0,3,2] row_mask:0xf bank_mask:0xf bound_ctrl:1
	v_add_f32_dpp v114, v114, v114 quad_perm:[1,0,3,2] row_mask:0xf bank_mask:0xf bound_ctrl:1
	v_add_f32_dpp v116, v116, v116 quad_perm:[1,0,3,2] row_mask:0xf bank_mask:0xf bound_ctrl:1
	v_add_f32_dpp v111, v111, v111 quad_perm:[1,0,3,2] row_mask:0xf bank_mask:0xf bound_ctrl:1
	v_add_f32_dpp v113, v113, v113 quad_perm:[1,0,3,2] row_mask:0xf bank_mask:0xf bound_ctrl:1
	v_add_f32_dpp v115, v115, v115 quad_perm:[1,0,3,2] row_mask:0xf bank_mask:0xf bound_ctrl:1
	v_add_f32_dpp v117, v117, v117 quad_perm:[1,0,3,2] row_mask:0xf bank_mask:0xf bound_ctrl:1
	v_add_f32_dpp v110, v110, v110 quad_perm:[2,3,0,1] row_mask:0xf bank_mask:0xf bound_ctrl:1
	v_add_f32_dpp v112, v112, v112 quad_perm:[2,3,0,1] row_mask:0xf bank_mask:0xf bound_ctrl:1
	v_add_f32_dpp v114, v114, v114 quad_perm:[2,3,0,1] row_mask:0xf bank_mask:0xf bound_ctrl:1
	v_add_f32_dpp v116, v116, v116 quad_perm:[2,3,0,1] row_mask:0xf bank_mask:0xf bound_ctrl:1
	v_add_f32_dpp v111, v111, v111 quad_perm:[2,3,0,1] row_mask:0xf bank_mask:0xf bound_ctrl:1
	v_add_f32_dpp v113, v113, v113 quad_perm:[2,3,0,1] row_mask:0xf bank_mask:0xf bound_ctrl:1
	v_add_f32_dpp v115, v115, v115 quad_perm:[2,3,0,1] row_mask:0xf bank_mask:0xf bound_ctrl:1
	v_add_f32_dpp v117, v117, v117 quad_perm:[2,3,0,1] row_mask:0xf bank_mask:0xf bound_ctrl:1
	v_add_u32_e32 v72, 16, v57
	v_ashrrev_i32_e32 v73, 31, v72
	v_lshlrev_b64 v[72:73], 10, v[72:73]
	v_lshl_add_u64 v[72:73], v[64:65], 0, v[72:73]
	v_cndmask_b32_e64 v154, v116, v114, s[16:17]
	v_cndmask_b32_e64 v155, v117, v115, s[16:17]
	v_cndmask_b32_e64 v154, v154, v112, s[14:15]
	v_cndmask_b32_e64 v155, v155, v113, s[14:15]
	v_cndmask_b32_e64 v154, v154, v110, s[12:13]
	v_cndmask_b32_e64 v155, v155, v111, s[12:13]
	v_cvt_pk_bf16_f32 v154, v154, v155
	global_store_dword v[72:73], v154, off
	s_lshl_b32 s5, s5, 3
	s_or_b32 s4, s5, s4
	s_ashr_i32 s5, s4, 31
	s_lshl_b64 s[4:5], s[4:5], 14
	s_add_u32 s4, s44, s4
	s_addc_u32 s5, s45, s5
	s_waitcnt vmcnt(4)
	v_lshlrev_b32_e32 v0, 8, v54
	v_mov_b32_e32 v1, 0
	v_lshl_add_u64 v[2:3], s[4:5], 0, v[0:1]
	v_lshlrev_b32_e32 v0, 2, v76
	s_waitcnt vmcnt(3)
	v_lshl_add_u64 v[4:5], v[2:3], 0, v[0:1]
	s_mov_b64 s[4:5], 0x4208000
	v_lshl_add_u64 v[6:7], v[4:5], 0, s[4:5]
	v_add_co_u32_e32 v4, vcc, 0x4208000, v4
	v_mov_b32_e32 v0, v66
	v_mov_b32_e32 v1, v20
	v_mov_b32_e32 v2, v68
	v_mov_b32_e32 v3, v70
	v_addc_co_u32_e32 v5, vcc, 0, v5, vcc
	v_mov_b32_e32 v20, v67
	v_mov_b32_e32 v22, v69
	v_mov_b32_e32 v23, v71
	global_store_dwordx4 v[4:5], v[0:3], off
	global_store_dwordx4 v[6:7], v[20:23], off offset:256

; __device__ __forceinline__ int fresh_tid(int wv) { int l; asm volatile("v_mbcnt_lo_u32_b32 %0, -1, 0\n\tv_mbcnt_hi_u32_b32 %0, -1, %0" : "=v"(l)); return wv * 64 + l; }
; #define LAS __attribute__((address_space(3)))
; __device__ __forceinline__ TDesc tconv_desc(const float* wg, const float* wu, const float* wd, const float* win, const float* wout, unsigned char* ws, int i) {
;     TDesc d; int mode = 0, tile = i;
;     if (i < 704) { d.W = wg; d.Bt = (bf16_t*)(ws + WS_WGU); d.K = 1024; d.N = DFF; mode = 1; }
;     else if (i < 1408) { d.W = wu; d.Bt = (bf16_t*)(ws + WS_WGU); d.K = 1024; d.N = DFF; mode = 2; tile = i - 704; }
;     else if (i < 2112) { d.W = wd; d.Bt = (bf16_t*)(ws + WS_WD); d.K = DFF; d.N = 1024; tile = i - 1408; }
;     else if (i < 3072) { d.W = win; d.Bt = (bf16_t*)(ws + WS_WIN); d.K = 1024; d.N = NCOLS; tile = i - 2112; }
;     else { d.W = wout; d.Bt = (bf16_t*)(ws + WS_WOUT); d.K = 1024; d.N = 1024; tile = i - 3072; }
;     const int nkt = d.K / 64; const int kt = tile % nkt, nt = tile / nkt; d.k0 = kt * 64; d.n0 = nt * 64;
;     d.brow0 = mode == 0 ? d.n0 : ((d.n0 >> 7) * 256 + (d.n0 & 127) + (mode == 2 ? 128 : 0));
;     return d;
; }
; __device__ __forceinline__ void tconv_list(const float* wg, const float* wu, const float* wd, const float* win, const float* wout, unsigned char* ws, const int ntiles, LAS float* t, const int wv) {
;     const int tid = fresh_tid(wv); const int G = gridDim.x;
;     float cur[8], nxt[8];
;     int i = blockIdx.x;
;     if (i < ntiles) { const TDesc d = tconv_desc(wg, wu, wd, win, wout, ws, i);
; #pragma unroll
;         for (int e = 0; e < 8; ++e) { const int idx = e * 512 + tid, r = idx >> 6, c = idx & 63; cur[e] = __builtin_nontemporal_load(d.W + (size_t)(d.k0 + r) * d.N + d.n0 + c); } }
;     for (; i < ntiles; i += G) {
;         const TDesc d = tconv_desc(wg, wu, wd, win, wout, ws, i);
;         { const TDesc dn = tconv_desc(wg, wu, wd, win, wout, ws, i + G < ntiles ? i + G : i);
; #pragma unroll
;             for (int e = 0; e < 8; ++e) { const int idx = e * 512 + tid, r = idx >> 6, c = idx & 63; nxt[e] = __builtin_nontemporal_load(dn.W + (size_t)(dn.k0 + r) * dn.N + dn.n0 + c); } }
.LBB0_847:
	s_cmp_lt_u32 s2, 32
	s_cbranch_scc1 .Ltc4_skip
	v_writelane_b32 v40, s4, 4
	v_writelane_b32 v40, s5, 5
	v_writelane_b32 v40, s6, 6
	v_writelane_b32 v40, s7, 7
	v_writelane_b32 v40, s8, 8
	v_writelane_b32 v40, s9, 9
	v_writelane_b32 v40, s10, 10
	v_writelane_b32 v40, s11, 11
	v_writelane_b32 v40, s12, 12
	v_writelane_b32 v40, s13, 13
	v_writelane_b32 v40, s14, 14
	v_writelane_b32 v40, s15, 15
	v_writelane_b32 v40, s16, 16
	v_writelane_b32 v40, s17, 17
	v_writelane_b32 v40, s18, 18
	v_writelane_b32 v40, s19, 19
	v_writelane_b32 v40, s20, 20
	v_writelane_b32 v40, s21, 21
	v_writelane_b32 v40, s22, 22
	v_writelane_b32 v40, s23, 23
	v_writelane_b32 v40, s24, 24
	v_writelane_b32 v40, s25, 25
	v_writelane_b32 v40, s26, 26
	v_writelane_b32 v40, s27, 27
	v_writelane_b32 v40, s28, 28
	v_writelane_b32 v40, s29, 29
	v_writelane_b32 v40, s30, 30
	v_writelane_b32 v40, s31, 31
	s_load_dwordx2 s[24:25], s[38:39], 0xd8
	s_load_dwordx2 s[26:27], s[38:39], 0xd0
	s_load_dwordx2 s[18:19], s[38:39], 0xb8
	s_load_dwordx2 s[20:21], s[38:39], 0xc0
	s_load_dwordx2 s[22:23], s[38:39], 0xc8
	v_mbcnt_lo_u32_b32 v0, -1, 0
	v_mbcnt_hi_u32_b32 v0, -1, v0
	s_lshr_b32 s28, s33, 6
	v_lshlrev_b32_e32 v1, 2, v0
	v_lshrrev_b32_e32 v2, 5, v0
	v_and_b32_e32 v3, 31, v0
	s_mul_i32 s7, s28, 260
	v_add_u32_e32 v5, s7, v1
	v_mul_u32_u24_e32 v6, 0x208, v3
	s_lshl_b32 s7, s28, 3
	v_lshl_add_u32 v6, v2, 2, v6
	v_add_u32_e32 v6, s7, v6
	v_lshlrev_b32_e32 v3, 2, v3
	s_sub_u32 s4, s2, 32
	s_waitcnt lgkmcnt(0)
	s_cmp_lt_u32 s4, 704
	s_cbranch_scc0 .Ltc4_seg1_0
	s_mov_b32 s7, s4
	s_and_b32 s8, s7, 15
	s_lshr_b32 s9, s7, 4
	s_mul_i32 s7, s8, 720896
	s_lshl_b32 s29, s9, 8
	s_add_u32 s7, s7, s29
	s_mul_i32 s29, s28, 11264
	s_add_u32 s7, s7, s29
	s_add_u32 s10, s18, s7
	s_addc_u32 s11, s19, 0
	s_lshr_b32 s7, s9, 1
	s_lshl_b32 s7, s7, 8
	s_and_b32 s29, s9, 1
	s_lshl_b32 s29, s29, 6
	s_add_u32 s7, s7, s29
	s_mul_i32 s7, s7, 2048
	s_lshl_b32 s29, s8, 7
	s_add_u32 s7, s7, s29
	s_mul_i32 s29, s28, 4096
	s_add_u32 s7, s7, s29
	s_add_u32 s12, s26, 0x2100000
	s_addc_u32 s13, s27, 0
	s_add_u32 s12, s12, s7
	s_addc_u32 s13, s13, 0
	s_mov_b32 s14, 90112
	s_mov_b32 s15, 32768
	s_movk_i32 s16, 2048
	s_branch .Ltc4_segend_0

; __device__ __forceinline__ TDesc tconv_desc(const float* wg, const float* wu, const float* wd, const float* win, const float* wout, unsigned char* ws, int i) {
;     TDesc d; int mode = 0, tile = i;
;     if (i < 704) { d.W = wg; d.Bt = (bf16_t*)(ws + WS_WGU); d.K = 1024; d.N = DFF; mode = 1; }
;     else if (i < 1408) { d.W = wu; d.Bt = (bf16_t*)(ws + WS_WGU); d.K = 1024; d.N = DFF; mode = 2; tile = i - 704; }
;     else if (i < 2112) { d.W = wd; d.Bt = (bf16_t*)(ws + WS_WD); d.K = DFF; d.N = 1024; tile = i - 1408; }
;     else if (i < 3072) { d.W = win; d.Bt = (bf16_t*)(ws + WS_WIN); d.K = 1024; d.N = NCOLS; tile = i - 2112; }
;     else { d.W = wout; d.Bt = (bf16_t*)(ws + WS_WOUT); d.K = 1024; d.N = 1024; tile = i - 3072; }
;     const int nkt = d.K / 64; const int kt = tile % nkt, nt = tile / nkt; d.k0 = kt * 64; d.n0 = nt * 64;
;     d.brow0 = mode == 0 ? d.n0 : ((d.n0 >> 7) * 256 + (d.n0 & 127) + (mode == 2 ? 128 : 0));
; __device__ __forceinline__ void tconv_list(const float* wg, const float* wu, const float* wd, const float* win, const float* wout, unsigned char* ws, const int ntiles, LAS float* t, const int wv) {
;     ...
;     for (; i < ntiles; i += G) {
;         const TDesc d = tconv_desc(wg, wu, wd, win, wout, ws, i);
;         { const TDesc dn = tconv_desc(wg, wu, wd, win, wout, ws, i + G < ntiles ? i + G : i);
; #pragma unroll
;             for (int e = 0; e < 8; ++e) { const int idx = e * 512 + tid, r = idx >> 6, c = idx & 63; nxt[e] = __builtin_nontemporal_load(dn.W + (size_t)(dn.k0 + r) * dn.N + dn.n0 + c); } }
.Ltc4_loop:
	s_add_u32 s4, s4, 224
	s_cmp_lt_u32 s4, 808
	s_cselect_b32 s31, 1, 0
	s_cbranch_scc0 .Ltc4_nonexta
	v_writelane_b32 v40, s8, 32
	v_writelane_b32 v40, s9, 33
	s_cmp_lt_u32 s4, 704
	s_cbranch_scc0 .Ltc4_seg1_1
	s_mov_b32 s7, s4
	s_and_b32 s8, s7, 15
	s_lshr_b32 s9, s7, 4
	s_mul_i32 s7, s8, 720896
	s_lshl_b32 s29, s9, 8
	s_add_u32 s7, s7, s29
	s_mul_i32 s29, s28, 11264
	s_add_u32 s7, s7, s29
	s_add_u32 s10, s18, s7
	s_addc_u32 s11, s19, 0
	s_lshr_b32 s7, s9, 1
	s_lshl_b32 s7, s7, 8
	s_and_b32 s29, s9, 1
	s_lshl_b32 s29, s29, 6
	s_add_u32 s7, s7, s29
	s_mul_i32 s7, s7, 2048
	s_lshl_b32 s29, s8, 7
	s_add_u32 s7, s7, s29
	s_mul_i32 s29, s28, 4096
	s_add_u32 s7, s7, s29
	s_add_u32 s12, s26, 0x2100000
	s_addc_u32 s13, s27, 0
	s_add_u32 s12, s12, s7
	s_addc_u32 s13, s13, 0
	s_mov_b32 s14, 90112
	s_mov_b32 s15, 32768
	s_movk_i32 s16, 2048
	s_branch .Ltc4_segend_1

; __device__ __forceinline__ unsigned cvt_pk_bf16(float lo, float hi) { const f32x2_t v = {lo, hi}; const bf16x2_t b = __builtin_convertvector(v, bf16x2_t); return __builtin_bit_cast(unsigned, b); }
; __device__ __forceinline__ void tconv_list(const float* wg, const float* wu, const float* wd, const float* win, const float* wout, unsigned char* ws, const int ntiles, LAS float* t, const int wv) {
;     ...
; #pragma unroll
;         for (int e = 0; e < 8; ++e) { const int idx = e * 512 + tid, r = idx >> 6, c = idx & 63; t[r * 65 + c] = cur[e]; }
;         __syncthreads();
; #pragma unroll
;         for (int e = 0; e < 4; ++e) { const int idx = e * 512 + tid, n = idx >> 5, kp = idx & 31;
;             const unsigned w = pg8::cvt_pk_bf16(t[(2 * kp) * 65 + n], t[(2 * kp + 1) * 65 + n]);
;             *(unsigned*)(d.Bt + (size_t)(d.brow0 + n) * d.K + d.k0 + 2 * kp) = w; }
;         __syncthreads();
; #pragma unroll
;         for (int e = 0; e < 8; ++e) cur[e] = nxt[e];
.Ltc4_havea:
	ds_write_b32 v5, v8 offset:0
	ds_write_b32 v5, v9 offset:2080
	ds_write_b32 v5, v10 offset:4160
	ds_write_b32 v5, v11 offset:6240
	ds_write_b32 v5, v12 offset:8320
	ds_write_b32 v5, v13 offset:10400
	ds_write_b32 v5, v14 offset:12480
	ds_write_b32 v5, v15 offset:14560
	v_mad_u32_u24 v4, v2, s30, v3
	s_waitcnt lgkmcnt(0)
	s_barrier
	ds_read2_b32 v[24:25], v6 offset0:0 offset1:65
	ds_read2_b32 v[26:27], v6 offset0:16 offset1:81
	ds_read2_b32 v[28:29], v6 offset0:32 offset1:97
	ds_read2_b32 v[30:31], v6 offset0:48 offset1:113
	s_waitcnt lgkmcnt(3)
	v_cvt_pk_bf16_f32 v32, v24, v25
	s_waitcnt lgkmcnt(2)
	v_cvt_pk_bf16_f32 v33, v26, v27
	s_waitcnt lgkmcnt(1)
	v_cvt_pk_bf16_f32 v34, v28, v29
	s_waitcnt lgkmcnt(0)
	v_cvt_pk_bf16_f32 v35, v30, v31
	global_store_dword v4, v32, s[8:9]
	s_add_u32 s8, s8, s17
	s_addc_u32 s9, s9, 0
	global_store_dword v4, v33, s[8:9]
	s_add_u32 s8, s8, s17
	s_addc_u32 s9, s9, 0
	global_store_dword v4, v34, s[8:9]
	s_add_u32 s8, s8, s17
	s_addc_u32 s9, s9, 0
	global_store_dword v4, v35, s[8:9]
	s_barrier
	s_cmp_eq_u32 s31, 0
	s_cbranch_scc1 .Ltc4_done
	s_mov_b32 s17, s15
	s_mov_b32 s30, s16
	s_mov_b64 s[8:9], s[12:13]
	s_add_u32 s4, s4, 224
	s_cmp_lt_u32 s4, 808
	s_cselect_b32 s31, 1, 0
	s_cbranch_scc0 .Ltc4_nonextb
	v_writelane_b32 v40, s8, 32
	v_writelane_b32 v40, s9, 33
	s_cmp_lt_u32 s4, 704
	s_cbranch_scc0 .Ltc4_seg1_2
	s_mov_b32 s7, s4
	s_and_b32 s8, s7, 15
	s_lshr_b32 s9, s7, 4
	s_mul_i32 s7, s8, 720896
	s_lshl_b32 s29, s9, 8
	s_add_u32 s7, s7, s29
	s_mul_i32 s29, s28, 11264
	s_add_u32 s7, s7, s29
	s_add_u32 s10, s18, s7
	s_addc_u32 s11, s19, 0
	s_lshr_b32 s7, s9, 1
	s_lshl_b32 s7, s7, 8
	s_and_b32 s29, s9, 1
	s_lshl_b32 s29, s29, 6
	s_add_u32 s7, s7, s29
	s_mul_i32 s7, s7, 2048
	s_lshl_b32 s29, s8, 7
	s_add_u32 s7, s7, s29
	s_mul_i32 s29, s28, 4096
	s_add_u32 s7, s7, s29
	s_add_u32 s12, s26, 0x2100000
	s_addc_u32 s13, s27, 0
	s_add_u32 s12, s12, s7
	s_addc_u32 s13, s13, 0
	s_mov_b32 s14, 90112
	s_mov_b32 s15, 32768
	s_movk_i32 s16, 2048
	s_branch .Ltc4_segend_2

; __device__ __forceinline__ int fresh_tid(int wv) { int l; asm volatile("v_mbcnt_lo_u32_b32 %0, -1, 0\n\tv_mbcnt_hi_u32_b32 %0, -1, %0" : "=v"(l)); return wv * 64 + l; }
; #define LAS __attribute__((address_space(3)))
; __device__ __forceinline__ unsigned xb_xcc_id() { return (unsigned)__builtin_amdgcn_s_getreg((3 << 11) | 20) & 0xFu; }
; __device__ __forceinline__ void xcd_barrier(unsigned* barw, volatile LAS unsigned* stw, const int wv) {
;     XcdBarrier b; b.bar = barw; b.x = xb_xcc_id(); b.st = stw;
;     asm volatile("s_waitcnt vmcnt(0)" ::: "memory");
;     __syncthreads();
;     if (fresh_tid(wv) == 0) {
;         unsigned* bar = b.bar;
;         __builtin_amdgcn_s_waitcnt(0);
;         unsigned nloc = b.st[0], nx = b.st[1];
;         if (nloc == 0u) { xcd_barrier_complete(bar, b.x, nloc, nx); b.st[0] = nloc; b.st[1] = nx; }
.Ltc4_done:
	v_readlane_b32 s4, v40, 4
	v_readlane_b32 s5, v40, 5
	v_readlane_b32 s6, v40, 6
	v_readlane_b32 s7, v40, 7
	v_readlane_b32 s8, v40, 8
	v_readlane_b32 s9, v40, 9
	v_readlane_b32 s10, v40, 10
	v_readlane_b32 s11, v40, 11
	v_readlane_b32 s12, v40, 12
	v_readlane_b32 s13, v40, 13
	v_readlane_b32 s14, v40, 14
	v_readlane_b32 s15, v40, 15
	v_readlane_b32 s16, v40, 16
	v_readlane_b32 s17, v40, 17
	v_readlane_b32 s18, v40, 18
	v_readlane_b32 s19, v40, 19
	v_readlane_b32 s20, v40, 20
	v_readlane_b32 s21, v40, 21
	v_readlane_b32 s22, v40, 22
	v_readlane_b32 s23, v40, 23
	v_readlane_b32 s24, v40, 24
	v_readlane_b32 s25, v40, 25
	v_readlane_b32 s26, v40, 26
	v_readlane_b32 s27, v40, 27
	v_readlane_b32 s28, v40, 28
	v_readlane_b32 s29, v40, 29
	v_readlane_b32 s30, v40, 30
	v_readlane_b32 s31, v40, 31
	s_nop 4
.Ltc4_skip:
	s_getreg_b32 s4, hwreg(HW_REG_XCC_ID, 0, 4)
	s_waitcnt vmcnt(0)
	s_waitcnt vmcnt(0) lgkmcnt(0)
	s_barrier
	v_mbcnt_lo_u32_b32 v0, -1, 0
	v_mbcnt_hi_u32_b32 v0, -1, v0
	s_nop 0
	v_cmp_eq_u32_e32 vcc, s74, v0
	s_and_saveexec_b64 s[0:1], vcc
	s_cbranch_execz .LBB0_899
	s_add_u32 s8, s12, 0x200
	s_addc_u32 s9, s13, 0
	s_add_i32 s5, 0, 0x23ff0
	v_mov_b32_e32 v0, s5
	s_waitcnt vmcnt(0) expcnt(0) lgkmcnt(0)
	ds_read_b32 v2, v0
	s_add_i32 s5, 0, 0x23ff4
	v_mov_b32_e32 v0, s5
	ds_read_b32 v0, v0
	s_and_b32 s4, s4, 15
	s_waitcnt lgkmcnt(1)
	v_cmp_ne_u32_e32 vcc, 0, v2
	s_cbranch_vccnz .LBB0_863
	s_add_u32 s10, s12, 0x1000
	s_addc_u32 s11, s13, 0
	s_add_u32 s14, s12, 0x1100
	s_addc_u32 s15, s13, 0
	s_add_u32 s16, s12, 0x1200
	s_addc_u32 s17, s13, 0
	s_add_u32 s18, s12, 0x1300
	s_addc_u32 s19, s13, 0
	s_mov_b32 s5, 1
	v_mov_b32_e32 v16, 0
	s_branch .LBB0_851
